# residual-epilogue cross-row reductions via v_permlane16/32_swap instead of ds_bpermute round trips (P7 epilogue 31 -> 24 us by probe); on top of pipelined diff QK, static priority raise, conv+gelu epi
# speedup vs baseline: 1.0116x; 1.0023x over previous
;     __device__ __forceinline__ void operator()(const f32x4 (&acc)[2][2][4][2], const Unit& u, int wr, int wc, int fr, int fq) const {
;     ...
;         const int row0 = u.pm * BM + wr * 64 + fr, col0 = u.pn * BM + wc * 32 + 8 * fq; const bool odd = (fr & 1) != 0;
; #pragma unroll
;         for (int ai = 0; ai < 2; ++ai)
; #pragma unroll
;             for (int m = 0; m < 4; ++m) {
;                 const int row = row0 + ai * HALF + m * 16; float s = 0.f;
;                 const size_t off = (size_t)row * DM + col0;
;                 const size_t offp = (size_t)(row - (odd ? 1 : 0)) * DM + col0 + (odd ? 4 : 0);
; #pragma unroll
;                 for (int bj = 0; bj < 2; ++bj) {
;                     f32x4 b0, b1;
;                     if constexpr (BASE_F32) { const f32x4 la = *(const GAS f32x4*)(basef + offp + bj * HALF), lb = *(const GAS f32x4*)(basef + offp + DM + bj * HALF);
;                         const f32x4 snd = odd ? la : lb; f32x4 rcv; rcv[0] = dpp_xor1(snd[0]); rcv[1] = dpp_xor1(snd[1]); rcv[2] = dpp_xor1(snd[2]); rcv[3] = dpp_xor1(snd[3]);
;                         b0 = odd ? rcv : la; b1 = odd ? lb : rcv; }
;                     else { const u32x4 bw = *(const u32x4*)(baseb + off + bj * HALF);
;                         b0 = (f32x4){bf_lo(bw.x), bf_hi(bw.x), bf_lo(bw.y), bf_hi(bw.y)}; b1 = (f32x4){bf_lo(bw.z), bf_hi(bw.z), bf_lo(bw.w), bf_hi(bw.w)}; }
;                     const f32x4 v0 = acc[ai][bj][m][0] + b0, v1 = acc[ai][bj][m][1] + b1;
;                     if constexpr (OUT_F32) { const f32x4 snd = odd ? v0 : v1; f32x4 rcv; rcv[0] = dpp_xor1(snd[0]); rcv[1] = dpp_xor1(snd[1]); rcv[2] = dpp_xor1(snd[2]); rcv[3] = dpp_xor1(snd[3]);
;                         *(f32x4*)(H + offp + bj * HALF) = odd ? rcv : v0; *(f32x4*)(H + offp + DM + bj * HALF) = odd ? v1 : rcv; }
;                     else { u32x4 w; w.x = cvt_pk_bf16(v0[0], v0[1]); w.y = cvt_pk_bf16(v0[2], v0[3]); w.z = cvt_pk_bf16(v1[0], v1[1]); w.w = cvt_pk_bf16(v1[2], v1[3]);
;                         *(u32x4*)(HB + off + bj * HALF) = w; }
;                     s += (v0[0] * v0[0] + v0[1] * v0[1]) + (v0[2] * v0[2] + v0[3] * v0[3]) + (v1[0] * v1[0] + v1[1] * v1[1]) + (v1[2] * v1[2] + v1[3] * v1[3]);
;                 }
;                 s += __shfl_xor(s, 16); s += __shfl_xor(s, 32);
;                 if (fq == 0) unsafeAtomicAdd(ssn + row, s);
;             }
.LBB0_1005:
	v_lshl_add_u32 v148, s30, 8, v150
	v_sub_u32_e32 v158, v148, v152
	v_ashrrev_i32_e32 v159, 31, v158
	v_lshl_or_b32 v146, s34, 8, v153
	v_lshlrev_b64 v[158:159], 13, v[158:159]
	v_ashrrev_i32_e32 v147, 31, v146
	v_lshl_add_u64 v[158:159], s[8:9], 0, v[158:159]
	v_lshl_add_u64 v[158:159], v[146:147], 2, v[158:159]
	v_lshl_add_u64 v[166:167], v[158:159], 0, v[136:137]
	v_add_co_u32_e32 v168, vcc, s45, v166
	v_ashrrev_i32_e32 v149, 31, v148
	s_nop 0
	v_addc_co_u32_e32 v169, vcc, 0, v167, vcc
	global_load_dwordx4 v[158:161], v[166:167], off
	global_load_dwordx4 v[162:165], v[168:169], off
	v_readlane_b32 s24, v254, 25
	v_mov_b32_e32 v172, v137
	v_mov_b32_e32 v173, v137
	v_mov_b32_e32 v174, v137
	v_mov_b32_e32 v175, v137
	v_lshlrev_b64 v[170:171], 12, v[148:149]
	v_readlane_b32 s25, v254, 26
	s_waitcnt vmcnt(0)
	v_cndmask_b32_e64 v176, v161, v165, s[0:1]
	v_cndmask_b32_e64 v177, v160, v164, s[0:1]
	v_cndmask_b32_e64 v178, v159, v163, s[0:1]
	v_cndmask_b32_e64 v179, v158, v162, s[0:1]
	v_lshl_add_u64 v[170:171], s[24:25], 0, v[170:171]
	v_mov_b32_dpp v173, v178 quad_perm:[1,0,3,2] row_mask:0xf bank_mask:0xf
	v_mov_b32_dpp v172, v179 quad_perm:[1,0,3,2] row_mask:0xf bank_mask:0xf
	v_mov_b32_dpp v174, v177 quad_perm:[1,0,3,2] row_mask:0xf bank_mask:0xf
	v_mov_b32_dpp v175, v176 quad_perm:[1,0,3,2] row_mask:0xf bank_mask:0xf
	v_lshl_add_u64 v[170:171], v[146:147], 1, v[170:171]
	v_cndmask_b32_e64 v159, v173, v159, s[0:1]
	v_cndmask_b32_e64 v158, v172, v158, s[0:1]
	v_cndmask_b32_e64 v161, v175, v161, s[0:1]
	v_cndmask_b32_e64 v160, v174, v160, s[0:1]
	v_cndmask_b32_e64 v163, v163, v173, s[0:1]
	v_cndmask_b32_e64 v162, v162, v172, s[0:1]
	v_cndmask_b32_e64 v165, v165, v175, s[0:1]
	v_cndmask_b32_e64 v164, v164, v174, s[0:1]
	v_pk_add_f32 v[126:127], v[126:127], v[160:161]
	v_pk_add_f32 v[172:173], v[124:125], v[158:159]
	v_pk_add_f32 v[164:165], v[122:123], v[164:165]
	v_pk_add_f32 v[162:163], v[120:121], v[162:163]
	v_cvt_pk_bf16_f32 v120, v172, v173
	v_cvt_pk_bf16_f32 v121, v126, v127
	v_mul_f32_e32 v173, v173, v173
	v_cvt_pk_bf16_f32 v122, v162, v163
	v_cvt_pk_bf16_f32 v123, v164, v165
	global_store_dwordx4 v[170:171], v[120:123], off
	global_load_dwordx4 v[122:125], v[166:167], off offset:512
	s_nop 0
	global_load_dwordx4 v[158:161], v[168:169], off offset:512
	v_mul_f32_e32 v127, v127, v127
	v_mul_f32_e32 v163, v163, v163
	v_fmac_f32_e32 v173, v172, v172
	v_fmac_f32_e32 v127, v126, v126
	v_mul_f32_e32 v165, v165, v165
	v_fmac_f32_e32 v163, v162, v162
	v_add_f32_e32 v126, v173, v127
	v_fmac_f32_e32 v165, v164, v164
	v_add_f32_e32 v126, v163, v126
	v_mov_b32_e32 v121, v137
	v_mov_b32_e32 v166, v137
	v_mov_b32_e32 v167, v137
	v_mov_b32_e32 v168, v137
	v_add_f32_e32 v162, v165, v126
	v_and_b32_e32 v169, 64, v157
	v_xor_b32_e32 v120, 16, v157
	v_add_u32_e32 v169, 64, v169
	v_cmp_lt_i32_e32 vcc, v120, v169
	s_waitcnt vmcnt(0)
	v_cndmask_b32_e64 v126, v125, v161, s[0:1]
	v_cndmask_b32_e64 v127, v124, v160, s[0:1]
	v_cndmask_b32_e64 v163, v123, v159, s[0:1]
	v_cndmask_b32_e64 v164, v122, v158, s[0:1]
	v_mov_b32_dpp v167, v127 quad_perm:[1,0,3,2] row_mask:0xf bank_mask:0xf
	v_mov_b32_dpp v166, v163 quad_perm:[1,0,3,2] row_mask:0xf bank_mask:0xf
	v_mov_b32_dpp v121, v164 quad_perm:[1,0,3,2] row_mask:0xf bank_mask:0xf
	v_mov_b32_dpp v168, v126 quad_perm:[1,0,3,2] row_mask:0xf bank_mask:0xf
	v_cndmask_b32_e64 v123, v166, v123, s[0:1]
	v_cndmask_b32_e64 v122, v121, v122, s[0:1]
	v_cndmask_b32_e64 v125, v168, v125, s[0:1]
	v_cndmask_b32_e64 v124, v167, v124, s[0:1]
	v_cndmask_b32_e64 v127, v159, v166, s[0:1]
	v_cndmask_b32_e64 v126, v158, v121, s[0:1]
	v_pk_add_f32 v[118:119], v[118:119], v[124:125]
	v_pk_add_f32 v[116:117], v[116:117], v[122:123]
	v_cndmask_b32_e64 v159, v161, v168, s[0:1]
	v_cndmask_b32_e64 v158, v160, v167, s[0:1]
	v_pk_add_f32 v[124:125], v[112:113], v[126:127]
	v_mul_f32_e32 v112, v117, v117
	v_mul_f32_e32 v113, v119, v119
	v_pk_add_f32 v[122:123], v[114:115], v[158:159]
	v_mul_f32_e32 v114, v125, v125
	v_fmac_f32_e32 v112, v116, v116
	v_fmac_f32_e32 v113, v118, v118
	v_mul_f32_e32 v115, v123, v123
	v_fmac_f32_e32 v114, v124, v124
	v_add_f32_e32 v112, v112, v113
	v_fmac_f32_e32 v115, v122, v122
	v_add_f32_e32 v112, v114, v112
	v_cndmask_b32_e32 v120, v157, v120, vcc
	v_add_f32_e32 v112, v115, v112
	v_lshlrev_b32_e32 v120, 2, v120
	v_add_f32_e32 v112, v162, v112
	v_mov_b32_e32 v113, v112
	s_nop 1
	v_permlane16_swap_b32_e32 v113, v112
	v_xor_b32_e32 v114, 32, v157
	v_cmp_lt_i32_e32 vcc, v114, v169
	v_cvt_pk_bf16_f32 v116, v116, v117
	v_cvt_pk_bf16_f32 v117, v118, v119
	s_waitcnt lgkmcnt(0)
	v_add_f32_e32 v112, v112, v113
	v_cvt_pk_bf16_f32 v118, v124, v125
	v_cvt_pk_bf16_f32 v119, v122, v123
	v_cndmask_b32_e32 v114, v157, v114, vcc
	v_lshlrev_b32_e32 v114, 2, v114
	v_mov_b32_e32 v113, v112
	s_nop 1
	v_permlane32_swap_b32_e32 v113, v112
	global_store_dwordx4 v[170:171], v[116:119], off offset:256
	s_and_saveexec_b64 s[30:31], s[2:3]
	s_cbranch_execz .LBB0_1007
	v_lshl_add_u64 v[116:117], v[148:149], 2, s[12:13]
	s_waitcnt lgkmcnt(0)
	v_add_f32_e32 v112, v112, v113
	global_atomic_add_f32 v[116:117], v112, off
;     __device__ __forceinline__ void operator()(const f32x4 (&acc)[2][2][4][2], const Unit& u, int wr, int wc, int fr, int fq) const {
;     ...
;         const int row0 = u.pm * BM + wr * 64 + fr, col0 = u.pn * BM + wc * 32 + 8 * fq; const bool odd = (fr & 1) != 0;
; #pragma unroll
;         for (int ai = 0; ai < 2; ++ai)
; #pragma unroll
;             for (int m = 0; m < 4; ++m) {
;                 const int row = row0 + ai * HALF + m * 16; float s = 0.f;
;                 const size_t off = (size_t)row * DM + col0;
;                 const size_t offp = (size_t)(row - (odd ? 1 : 0)) * DM + col0 + (odd ? 4 : 0);
; #pragma unroll
;                 for (int bj = 0; bj < 2; ++bj) {
;                     f32x4 b0, b1;
;                     if constexpr (BASE_F32) { const f32x4 la = *(const GAS f32x4*)(basef + offp + bj * HALF), lb = *(const GAS f32x4*)(basef + offp + DM + bj * HALF);
;                         const f32x4 snd = odd ? la : lb; f32x4 rcv; rcv[0] = dpp_xor1(snd[0]); rcv[1] = dpp_xor1(snd[1]); rcv[2] = dpp_xor1(snd[2]); rcv[3] = dpp_xor1(snd[3]);
;                         b0 = odd ? rcv : la; b1 = odd ? lb : rcv; }
;                     else { const u32x4 bw = *(const u32x4*)(baseb + off + bj * HALF);
;                         b0 = (f32x4){bf_lo(bw.x), bf_hi(bw.x), bf_lo(bw.y), bf_hi(bw.y)}; b1 = (f32x4){bf_lo(bw.z), bf_hi(bw.z), bf_lo(bw.w), bf_hi(bw.w)}; }
;                     const f32x4 v0 = acc[ai][bj][m][0] + b0, v1 = acc[ai][bj][m][1] + b1;
;                     if constexpr (OUT_F32) { const f32x4 snd = odd ? v0 : v1; f32x4 rcv; rcv[0] = dpp_xor1(snd[0]); rcv[1] = dpp_xor1(snd[1]); rcv[2] = dpp_xor1(snd[2]); rcv[3] = dpp_xor1(snd[3]);
;                         *(f32x4*)(H + offp + bj * HALF) = odd ? rcv : v0; *(f32x4*)(H + offp + DM + bj * HALF) = odd ? v1 : rcv; }
;                     else { u32x4 w; w.x = cvt_pk_bf16(v0[0], v0[1]); w.y = cvt_pk_bf16(v0[2], v0[3]); w.z = cvt_pk_bf16(v1[0], v1[1]); w.w = cvt_pk_bf16(v1[2], v1[3]);
;                         *(u32x4*)(HB + off + bj * HALF) = w; }
;                     s += (v0[0] * v0[0] + v0[1] * v0[1]) + (v0[2] * v0[2] + v0[3] * v0[3]) + (v1[0] * v1[0] + v1[1] * v1[1]) + (v1[2] * v1[2] + v1[3] * v1[3]);
;                 }
;                 s += __shfl_xor(s, 16); s += __shfl_xor(s, 32);
;                 if (fq == 0) unsafeAtomicAdd(ssn + row, s);
;             }
.LBB0_1007:
	s_or_b64 exec, exec, s[30:31]
	v_or_b32_e32 v112, 16, v148
	v_sub_u32_e32 v116, v112, v152
	v_ashrrev_i32_e32 v117, 31, v116
	v_lshlrev_b64 v[116:117], 13, v[116:117]
	v_lshl_add_u64 v[116:117], s[8:9], 0, v[116:117]
	v_lshl_add_u64 v[116:117], v[146:147], 2, v[116:117]
	v_lshl_add_u64 v[126:127], v[116:117], 0, v[136:137]
	v_add_co_u32_e32 v158, vcc, 0x2000, v126
	s_waitcnt lgkmcnt(0)
	v_ashrrev_i32_e32 v113, 31, v112
	v_addc_co_u32_e32 v159, vcc, 0, v127, vcc
	global_load_dwordx4 v[116:119], v[126:127], off
	global_load_dwordx4 v[122:125], v[158:159], off
	v_readlane_b32 s24, v254, 25
	v_mov_b32_e32 v115, v137
	v_mov_b32_e32 v121, v137
	v_mov_b32_e32 v149, v137
	v_mov_b32_e32 v162, v137
	v_lshlrev_b64 v[160:161], 12, v[112:113]
	v_readlane_b32 s25, v254, 26
	s_waitcnt vmcnt(0)
	v_cndmask_b32_e64 v163, v119, v125, s[0:1]
	v_cndmask_b32_e64 v164, v118, v124, s[0:1]
	v_cndmask_b32_e64 v165, v117, v123, s[0:1]
	v_cndmask_b32_e64 v166, v116, v122, s[0:1]
	v_lshl_add_u64 v[160:161], s[24:25], 0, v[160:161]
	v_mov_b32_dpp v121, v165 quad_perm:[1,0,3,2] row_mask:0xf bank_mask:0xf
	v_mov_b32_dpp v115, v166 quad_perm:[1,0,3,2] row_mask:0xf bank_mask:0xf
	v_mov_b32_dpp v149, v164 quad_perm:[1,0,3,2] row_mask:0xf bank_mask:0xf
	v_mov_b32_dpp v162, v163 quad_perm:[1,0,3,2] row_mask:0xf bank_mask:0xf
	v_lshl_add_u64 v[160:161], v[146:147], 1, v[160:161]
	v_cndmask_b32_e64 v117, v121, v117, s[0:1]
	v_cndmask_b32_e64 v116, v115, v116, s[0:1]
	v_cndmask_b32_e64 v119, v162, v119, s[0:1]
	v_cndmask_b32_e64 v118, v149, v118, s[0:1]
	v_cndmask_b32_e64 v123, v123, v121, s[0:1]
	v_cndmask_b32_e64 v122, v122, v115, s[0:1]
	v_cndmask_b32_e64 v125, v125, v162, s[0:1]
	v_cndmask_b32_e64 v124, v124, v149, s[0:1]
	v_pk_add_f32 v[118:119], v[110:111], v[118:119]
	v_pk_add_f32 v[116:117], v[108:109], v[116:117]
	v_pk_add_f32 v[124:125], v[106:107], v[124:125]
	v_pk_add_f32 v[122:123], v[104:105], v[122:123]
	v_cvt_pk_bf16_f32 v104, v116, v117
	v_cvt_pk_bf16_f32 v105, v118, v119
	v_mul_f32_e32 v117, v117, v117
	v_cvt_pk_bf16_f32 v106, v122, v123
	v_cvt_pk_bf16_f32 v107, v124, v125
	global_store_dwordx4 v[160:161], v[104:107], off
	global_load_dwordx4 v[104:107], v[126:127], off offset:512
	s_nop 0
	global_load_dwordx4 v[108:111], v[158:159], off offset:512
	v_mul_f32_e32 v119, v119, v119
	v_mul_f32_e32 v123, v123, v123
	v_fmac_f32_e32 v117, v116, v116
	v_fmac_f32_e32 v119, v118, v118
	v_mov_b32_e32 v115, v137
	v_mov_b32_e32 v121, v137
	v_mov_b32_e32 v126, v137
	v_mov_b32_e32 v127, v137
	v_fmac_f32_e32 v123, v122, v122
	v_add_f32_e32 v116, v117, v119
	v_mul_f32_e32 v125, v125, v125
	v_fmac_f32_e32 v125, v124, v124
	v_add_f32_e32 v116, v123, v116
	v_add_f32_e32 v116, v125, v116
	s_waitcnt vmcnt(0)
	v_cndmask_b32_e64 v117, v107, v111, s[0:1]
	v_cndmask_b32_e64 v118, v106, v110, s[0:1]
	v_cndmask_b32_e64 v119, v105, v109, s[0:1]
	v_cndmask_b32_e64 v122, v104, v108, s[0:1]
	v_mov_b32_dpp v126, v118 quad_perm:[1,0,3,2] row_mask:0xf bank_mask:0xf
	v_mov_b32_dpp v121, v119 quad_perm:[1,0,3,2] row_mask:0xf bank_mask:0xf
	v_mov_b32_dpp v115, v122 quad_perm:[1,0,3,2] row_mask:0xf bank_mask:0xf
	v_mov_b32_dpp v127, v117 quad_perm:[1,0,3,2] row_mask:0xf bank_mask:0xf
	v_cndmask_b32_e64 v105, v121, v105, s[0:1]
	v_cndmask_b32_e64 v104, v115, v104, s[0:1]
	v_cndmask_b32_e64 v107, v127, v107, s[0:1]
	v_cndmask_b32_e64 v106, v126, v106, s[0:1]
	v_cndmask_b32_e64 v109, v109, v121, s[0:1]
	v_cndmask_b32_e64 v108, v108, v115, s[0:1]
	v_pk_add_f32 v[102:103], v[102:103], v[106:107]
	v_pk_add_f32 v[100:101], v[100:101], v[104:105]
	v_cndmask_b32_e64 v111, v111, v127, s[0:1]
	v_cndmask_b32_e64 v110, v110, v126, s[0:1]
	v_pk_add_f32 v[106:107], v[96:97], v[108:109]
	v_mul_f32_e32 v96, v101, v101
	v_mul_f32_e32 v97, v103, v103
	v_pk_add_f32 v[104:105], v[98:99], v[110:111]
	v_mul_f32_e32 v98, v107, v107
	v_fmac_f32_e32 v96, v100, v100
	v_fmac_f32_e32 v97, v102, v102
	v_mul_f32_e32 v99, v105, v105
	v_fmac_f32_e32 v98, v106, v106
	v_add_f32_e32 v96, v96, v97
	v_add_f32_e32 v96, v98, v96
	v_fmac_f32_e32 v99, v104, v104
	v_add_f32_e32 v96, v99, v96
	v_add_f32_e32 v96, v116, v96
	v_mov_b32_e32 v97, v96
	s_nop 1
	v_permlane16_swap_b32_e32 v97, v96
	v_cvt_pk_bf16_f32 v98, v100, v101
	v_cvt_pk_bf16_f32 v99, v102, v103
	v_cvt_pk_bf16_f32 v100, v106, v107
	v_cvt_pk_bf16_f32 v101, v104, v105
	s_waitcnt lgkmcnt(0)
	v_add_f32_e32 v96, v96, v97
	v_mov_b32_e32 v97, v96
	s_nop 1
	v_permlane32_swap_b32_e32 v97, v96
	global_store_dwordx4 v[160:161], v[98:101], off offset:256
	s_and_saveexec_b64 s[30:31], s[2:3]
	s_cbranch_execz .LBB0_1009
	v_lshl_add_u64 v[98:99], v[112:113], 2, s[12:13]
	s_waitcnt lgkmcnt(0)
	v_add_f32_e32 v96, v96, v97
	global_atomic_add_f32 v[98:99], v96, off
;     __device__ __forceinline__ void operator()(const f32x4 (&acc)[2][2][4][2], const Unit& u, int wr, int wc, int fr, int fq) const {
;     ...
;         const int row0 = u.pm * BM + wr * 64 + fr, col0 = u.pn * BM + wc * 32 + 8 * fq; const bool odd = (fr & 1) != 0;
; #pragma unroll
;         for (int ai = 0; ai < 2; ++ai)
; #pragma unroll
;             for (int m = 0; m < 4; ++m) {
;                 const int row = row0 + ai * HALF + m * 16; float s = 0.f;
;                 const size_t off = (size_t)row * DM + col0;
;                 const size_t offp = (size_t)(row - (odd ? 1 : 0)) * DM + col0 + (odd ? 4 : 0);
; #pragma unroll
;                 for (int bj = 0; bj < 2; ++bj) {
;                     f32x4 b0, b1;
;                     if constexpr (BASE_F32) { const f32x4 la = *(const GAS f32x4*)(basef + offp + bj * HALF), lb = *(const GAS f32x4*)(basef + offp + DM + bj * HALF);
;                         const f32x4 snd = odd ? la : lb; f32x4 rcv; rcv[0] = dpp_xor1(snd[0]); rcv[1] = dpp_xor1(snd[1]); rcv[2] = dpp_xor1(snd[2]); rcv[3] = dpp_xor1(snd[3]);
;                         b0 = odd ? rcv : la; b1 = odd ? lb : rcv; }
;                     else { const u32x4 bw = *(const u32x4*)(baseb + off + bj * HALF);
;                         b0 = (f32x4){bf_lo(bw.x), bf_hi(bw.x), bf_lo(bw.y), bf_hi(bw.y)}; b1 = (f32x4){bf_lo(bw.z), bf_hi(bw.z), bf_lo(bw.w), bf_hi(bw.w)}; }
;                     const f32x4 v0 = acc[ai][bj][m][0] + b0, v1 = acc[ai][bj][m][1] + b1;
;                     if constexpr (OUT_F32) { const f32x4 snd = odd ? v0 : v1; f32x4 rcv; rcv[0] = dpp_xor1(snd[0]); rcv[1] = dpp_xor1(snd[1]); rcv[2] = dpp_xor1(snd[2]); rcv[3] = dpp_xor1(snd[3]);
;                         *(f32x4*)(H + offp + bj * HALF) = odd ? rcv : v0; *(f32x4*)(H + offp + DM + bj * HALF) = odd ? v1 : rcv; }
;                     else { u32x4 w; w.x = cvt_pk_bf16(v0[0], v0[1]); w.y = cvt_pk_bf16(v0[2], v0[3]); w.z = cvt_pk_bf16(v1[0], v1[1]); w.w = cvt_pk_bf16(v1[2], v1[3]);
;                         *(u32x4*)(HB + off + bj * HALF) = w; }
;                     s += (v0[0] * v0[0] + v0[1] * v0[1]) + (v0[2] * v0[2] + v0[3] * v0[3]) + (v1[0] * v1[0] + v1[1] * v1[1]) + (v1[2] * v1[2] + v1[3] * v1[3]);
;                 }
;                 s += __shfl_xor(s, 16); s += __shfl_xor(s, 32);
;                 if (fq == 0) unsafeAtomicAdd(ssn + row, s);
;             }
.LBB0_1009:
	s_or_b64 exec, exec, s[30:31]
	v_or_b32_e32 v96, 32, v148
	v_sub_u32_e32 v98, v96, v152
	v_ashrrev_i32_e32 v99, 31, v98
	v_lshlrev_b64 v[98:99], 13, v[98:99]
	v_lshl_add_u64 v[98:99], s[8:9], 0, v[98:99]
	v_lshl_add_u64 v[98:99], v[146:147], 2, v[98:99]
	v_lshl_add_u64 v[106:107], v[98:99], 0, v[136:137]
	v_add_co_u32_e32 v108, vcc, 0x2000, v106
	s_waitcnt lgkmcnt(0)
	v_ashrrev_i32_e32 v97, 31, v96
	v_addc_co_u32_e32 v109, vcc, 0, v107, vcc
	global_load_dwordx4 v[98:101], v[106:107], off
	global_load_dwordx4 v[102:105], v[108:109], off
	v_readlane_b32 s24, v254, 25
	v_mov_b32_e32 v112, v137
	v_mov_b32_e32 v113, v137
	v_mov_b32_e32 v115, v137
	v_mov_b32_e32 v116, v137
	v_lshlrev_b64 v[110:111], 12, v[96:97]
	v_readlane_b32 s25, v254, 26
	s_waitcnt vmcnt(0)
	v_cndmask_b32_e64 v117, v101, v105, s[0:1]
	v_cndmask_b32_e64 v118, v100, v104, s[0:1]
	v_cndmask_b32_e64 v119, v99, v103, s[0:1]
	v_cndmask_b32_e64 v121, v98, v102, s[0:1]
	v_lshl_add_u64 v[110:111], s[24:25], 0, v[110:111]
	v_mov_b32_dpp v113, v119 quad_perm:[1,0,3,2] row_mask:0xf bank_mask:0xf
	v_mov_b32_dpp v112, v121 quad_perm:[1,0,3,2] row_mask:0xf bank_mask:0xf
	v_mov_b32_dpp v115, v118 quad_perm:[1,0,3,2] row_mask:0xf bank_mask:0xf
	v_mov_b32_dpp v116, v117 quad_perm:[1,0,3,2] row_mask:0xf bank_mask:0xf
	v_lshl_add_u64 v[110:111], v[146:147], 1, v[110:111]
	v_cndmask_b32_e64 v99, v113, v99, s[0:1]
	v_cndmask_b32_e64 v98, v112, v98, s[0:1]
	v_cndmask_b32_e64 v101, v116, v101, s[0:1]
	v_cndmask_b32_e64 v100, v115, v100, s[0:1]
	v_cndmask_b32_e64 v103, v103, v113, s[0:1]
	v_cndmask_b32_e64 v102, v102, v112, s[0:1]
	v_cndmask_b32_e64 v105, v105, v116, s[0:1]
	v_cndmask_b32_e64 v104, v104, v115, s[0:1]
	v_pk_add_f32 v[100:101], v[94:95], v[100:101]
	v_pk_add_f32 v[98:99], v[92:93], v[98:99]
	v_pk_add_f32 v[104:105], v[90:91], v[104:105]
	v_pk_add_f32 v[102:103], v[88:89], v[102:103]
	v_cvt_pk_bf16_f32 v88, v98, v99
	v_cvt_pk_bf16_f32 v89, v100, v101
	v_mul_f32_e32 v99, v99, v99
	v_cvt_pk_bf16_f32 v90, v102, v103
	v_cvt_pk_bf16_f32 v91, v104, v105
	global_store_dwordx4 v[110:111], v[88:91], off
	global_load_dwordx4 v[88:91], v[106:107], off offset:512
	s_nop 0
	global_load_dwordx4 v[92:95], v[108:109], off offset:512
	v_mul_f32_e32 v101, v101, v101
	v_mul_f32_e32 v103, v103, v103
	v_fmac_f32_e32 v99, v98, v98
	v_fmac_f32_e32 v101, v100, v100
	v_mov_b32_e32 v106, v137
	v_mov_b32_e32 v107, v137
	v_mov_b32_e32 v108, v137
	v_mov_b32_e32 v109, v137
	v_fmac_f32_e32 v103, v102, v102
	v_add_f32_e32 v98, v99, v101
	v_mul_f32_e32 v105, v105, v105
	v_fmac_f32_e32 v105, v104, v104
	v_add_f32_e32 v98, v103, v98
	v_add_f32_e32 v98, v105, v98
	s_waitcnt vmcnt(0)
	v_cndmask_b32_e64 v99, v91, v95, s[0:1]
	v_cndmask_b32_e64 v100, v90, v94, s[0:1]
	v_cndmask_b32_e64 v101, v89, v93, s[0:1]
	v_cndmask_b32_e64 v102, v88, v92, s[0:1]
	v_mov_b32_dpp v108, v100 quad_perm:[1,0,3,2] row_mask:0xf bank_mask:0xf
	v_mov_b32_dpp v107, v101 quad_perm:[1,0,3,2] row_mask:0xf bank_mask:0xf
	v_mov_b32_dpp v106, v102 quad_perm:[1,0,3,2] row_mask:0xf bank_mask:0xf
	v_mov_b32_dpp v109, v99 quad_perm:[1,0,3,2] row_mask:0xf bank_mask:0xf
	v_cndmask_b32_e64 v89, v107, v89, s[0:1]
	v_cndmask_b32_e64 v88, v106, v88, s[0:1]
	v_cndmask_b32_e64 v91, v109, v91, s[0:1]
	v_cndmask_b32_e64 v90, v108, v90, s[0:1]
	v_cndmask_b32_e64 v93, v93, v107, s[0:1]
	v_cndmask_b32_e64 v92, v92, v106, s[0:1]
	v_pk_add_f32 v[86:87], v[86:87], v[90:91]
	v_pk_add_f32 v[84:85], v[84:85], v[88:89]
	v_cndmask_b32_e64 v95, v95, v109, s[0:1]
	v_cndmask_b32_e64 v94, v94, v108, s[0:1]
	v_pk_add_f32 v[90:91], v[80:81], v[92:93]
	v_mul_f32_e32 v80, v85, v85
	v_mul_f32_e32 v81, v87, v87
	v_pk_add_f32 v[88:89], v[82:83], v[94:95]
	v_mul_f32_e32 v82, v91, v91
	v_fmac_f32_e32 v80, v84, v84
	v_fmac_f32_e32 v81, v86, v86
	v_mul_f32_e32 v83, v89, v89
	v_fmac_f32_e32 v82, v90, v90
	v_add_f32_e32 v80, v80, v81
	v_add_f32_e32 v80, v82, v80
	v_fmac_f32_e32 v83, v88, v88
	v_add_f32_e32 v80, v83, v80
	v_add_f32_e32 v80, v98, v80
	v_mov_b32_e32 v81, v80
	s_nop 1
	v_permlane16_swap_b32_e32 v81, v80
	v_cvt_pk_bf16_f32 v82, v84, v85
	v_cvt_pk_bf16_f32 v83, v86, v87
	v_cvt_pk_bf16_f32 v84, v90, v91
	v_cvt_pk_bf16_f32 v85, v88, v89
	s_waitcnt lgkmcnt(0)
	v_add_f32_e32 v80, v80, v81
	v_mov_b32_e32 v81, v80
	s_nop 1
	v_permlane32_swap_b32_e32 v81, v80
	global_store_dwordx4 v[110:111], v[82:85], off offset:256
	s_and_saveexec_b64 s[30:31], s[2:3]
	s_cbranch_execz .LBB0_1011
	v_lshl_add_u64 v[82:83], v[96:97], 2, s[12:13]
	s_waitcnt lgkmcnt(0)
	v_add_f32_e32 v80, v80, v81
	global_atomic_add_f32 v[82:83], v80, off
;     __device__ __forceinline__ void operator()(const f32x4 (&acc)[2][2][4][2], const Unit& u, int wr, int wc, int fr, int fq) const {
;     ...
;         const int row0 = u.pm * BM + wr * 64 + fr, col0 = u.pn * BM + wc * 32 + 8 * fq; const bool odd = (fr & 1) != 0;
; #pragma unroll
;         for (int ai = 0; ai < 2; ++ai)
; #pragma unroll
;             for (int m = 0; m < 4; ++m) {
;                 const int row = row0 + ai * HALF + m * 16; float s = 0.f;
;                 const size_t off = (size_t)row * DM + col0;
;                 const size_t offp = (size_t)(row - (odd ? 1 : 0)) * DM + col0 + (odd ? 4 : 0);
; #pragma unroll
;                 for (int bj = 0; bj < 2; ++bj) {
;                     f32x4 b0, b1;
;                     if constexpr (BASE_F32) { const f32x4 la = *(const GAS f32x4*)(basef + offp + bj * HALF), lb = *(const GAS f32x4*)(basef + offp + DM + bj * HALF);
;                         const f32x4 snd = odd ? la : lb; f32x4 rcv; rcv[0] = dpp_xor1(snd[0]); rcv[1] = dpp_xor1(snd[1]); rcv[2] = dpp_xor1(snd[2]); rcv[3] = dpp_xor1(snd[3]);
;                         b0 = odd ? rcv : la; b1 = odd ? lb : rcv; }
;                     else { const u32x4 bw = *(const u32x4*)(baseb + off + bj * HALF);
;                         b0 = (f32x4){bf_lo(bw.x), bf_hi(bw.x), bf_lo(bw.y), bf_hi(bw.y)}; b1 = (f32x4){bf_lo(bw.z), bf_hi(bw.z), bf_lo(bw.w), bf_hi(bw.w)}; }
;                     const f32x4 v0 = acc[ai][bj][m][0] + b0, v1 = acc[ai][bj][m][1] + b1;
;                     if constexpr (OUT_F32) { const f32x4 snd = odd ? v0 : v1; f32x4 rcv; rcv[0] = dpp_xor1(snd[0]); rcv[1] = dpp_xor1(snd[1]); rcv[2] = dpp_xor1(snd[2]); rcv[3] = dpp_xor1(snd[3]);
;                         *(f32x4*)(H + offp + bj * HALF) = odd ? rcv : v0; *(f32x4*)(H + offp + DM + bj * HALF) = odd ? v1 : rcv; }
;                     else { u32x4 w; w.x = cvt_pk_bf16(v0[0], v0[1]); w.y = cvt_pk_bf16(v0[2], v0[3]); w.z = cvt_pk_bf16(v1[0], v1[1]); w.w = cvt_pk_bf16(v1[2], v1[3]);
;                         *(u32x4*)(HB + off + bj * HALF) = w; }
;                     s += (v0[0] * v0[0] + v0[1] * v0[1]) + (v0[2] * v0[2] + v0[3] * v0[3]) + (v1[0] * v1[0] + v1[1] * v1[1]) + (v1[2] * v1[2] + v1[3] * v1[3]);
;                 }
;                 s += __shfl_xor(s, 16); s += __shfl_xor(s, 32);
;                 if (fq == 0) unsafeAtomicAdd(ssn + row, s);
;             }
.LBB0_1011:
	s_or_b64 exec, exec, s[30:31]
	v_or_b32_e32 v80, 48, v148
	v_sub_u32_e32 v82, v80, v152
	v_ashrrev_i32_e32 v83, 31, v82
	v_lshlrev_b64 v[82:83], 13, v[82:83]
	v_lshl_add_u64 v[82:83], s[8:9], 0, v[82:83]
	v_lshl_add_u64 v[82:83], v[146:147], 2, v[82:83]
	v_lshl_add_u64 v[90:91], v[82:83], 0, v[136:137]
	v_add_co_u32_e32 v92, vcc, 0x2000, v90
	s_waitcnt lgkmcnt(0)
	v_ashrrev_i32_e32 v81, 31, v80
	v_addc_co_u32_e32 v93, vcc, 0, v91, vcc
	global_load_dwordx4 v[82:85], v[90:91], off
	global_load_dwordx4 v[86:89], v[92:93], off
	v_readlane_b32 s24, v254, 25
	v_mov_b32_e32 v96, v137
	v_mov_b32_e32 v97, v137
	v_mov_b32_e32 v98, v137
	v_mov_b32_e32 v99, v137
	v_lshlrev_b64 v[94:95], 12, v[80:81]
	v_readlane_b32 s25, v254, 26
	s_waitcnt vmcnt(0)
	v_cndmask_b32_e64 v100, v85, v89, s[0:1]
	v_cndmask_b32_e64 v101, v84, v88, s[0:1]
	v_cndmask_b32_e64 v102, v83, v87, s[0:1]
	v_cndmask_b32_e64 v103, v82, v86, s[0:1]
	v_lshl_add_u64 v[94:95], s[24:25], 0, v[94:95]
	v_mov_b32_dpp v97, v102 quad_perm:[1,0,3,2] row_mask:0xf bank_mask:0xf
	v_mov_b32_dpp v96, v103 quad_perm:[1,0,3,2] row_mask:0xf bank_mask:0xf
	v_mov_b32_dpp v98, v101 quad_perm:[1,0,3,2] row_mask:0xf bank_mask:0xf
	v_mov_b32_dpp v99, v100 quad_perm:[1,0,3,2] row_mask:0xf bank_mask:0xf
	v_lshl_add_u64 v[94:95], v[146:147], 1, v[94:95]
	v_cndmask_b32_e64 v83, v97, v83, s[0:1]
	v_cndmask_b32_e64 v82, v96, v82, s[0:1]
	v_cndmask_b32_e64 v85, v99, v85, s[0:1]
	v_cndmask_b32_e64 v84, v98, v84, s[0:1]
	v_cndmask_b32_e64 v87, v87, v97, s[0:1]
	v_cndmask_b32_e64 v86, v86, v96, s[0:1]
	v_cndmask_b32_e64 v89, v89, v99, s[0:1]
	v_cndmask_b32_e64 v88, v88, v98, s[0:1]
	v_pk_add_f32 v[84:85], v[78:79], v[84:85]
	v_pk_add_f32 v[82:83], v[76:77], v[82:83]
	v_pk_add_f32 v[88:89], v[74:75], v[88:89]
	v_pk_add_f32 v[86:87], v[72:73], v[86:87]
	v_cvt_pk_bf16_f32 v72, v82, v83
	v_cvt_pk_bf16_f32 v73, v84, v85
	v_mul_f32_e32 v83, v83, v83
	v_cvt_pk_bf16_f32 v74, v86, v87
	v_cvt_pk_bf16_f32 v75, v88, v89
	global_store_dwordx4 v[94:95], v[72:75], off
	global_load_dwordx4 v[72:75], v[90:91], off offset:512
	s_nop 0
	global_load_dwordx4 v[76:79], v[92:93], off offset:512
	v_mul_f32_e32 v85, v85, v85
	v_mul_f32_e32 v87, v87, v87
	v_fmac_f32_e32 v83, v82, v82
	v_fmac_f32_e32 v85, v84, v84
	v_mov_b32_e32 v90, v137
	v_mov_b32_e32 v91, v137
	v_mov_b32_e32 v92, v137
	v_mov_b32_e32 v93, v137
	v_fmac_f32_e32 v87, v86, v86
	v_add_f32_e32 v82, v83, v85
	v_mul_f32_e32 v89, v89, v89
	v_fmac_f32_e32 v89, v88, v88
	v_add_f32_e32 v82, v87, v82
	v_add_f32_e32 v82, v89, v82
	s_waitcnt vmcnt(0)
	v_cndmask_b32_e64 v83, v75, v79, s[0:1]
	v_cndmask_b32_e64 v84, v74, v78, s[0:1]
	v_cndmask_b32_e64 v85, v73, v77, s[0:1]
	v_cndmask_b32_e64 v86, v72, v76, s[0:1]
	v_mov_b32_dpp v92, v84 quad_perm:[1,0,3,2] row_mask:0xf bank_mask:0xf
	v_mov_b32_dpp v91, v85 quad_perm:[1,0,3,2] row_mask:0xf bank_mask:0xf
	v_mov_b32_dpp v90, v86 quad_perm:[1,0,3,2] row_mask:0xf bank_mask:0xf
	v_mov_b32_dpp v93, v83 quad_perm:[1,0,3,2] row_mask:0xf bank_mask:0xf
	v_cndmask_b32_e64 v73, v91, v73, s[0:1]
	v_cndmask_b32_e64 v72, v90, v72, s[0:1]
	v_cndmask_b32_e64 v75, v93, v75, s[0:1]
	v_cndmask_b32_e64 v74, v92, v74, s[0:1]
	v_cndmask_b32_e64 v77, v77, v91, s[0:1]
	v_cndmask_b32_e64 v76, v76, v90, s[0:1]
	v_pk_add_f32 v[70:71], v[70:71], v[74:75]
	v_pk_add_f32 v[68:69], v[68:69], v[72:73]
	v_cndmask_b32_e64 v79, v79, v93, s[0:1]
	v_cndmask_b32_e64 v78, v78, v92, s[0:1]
	v_pk_add_f32 v[74:75], v[64:65], v[76:77]
	v_mul_f32_e32 v64, v69, v69
	v_mul_f32_e32 v65, v71, v71
	v_pk_add_f32 v[72:73], v[66:67], v[78:79]
	v_mul_f32_e32 v66, v75, v75
	v_fmac_f32_e32 v64, v68, v68
	v_fmac_f32_e32 v65, v70, v70
	v_mul_f32_e32 v67, v73, v73
	v_fmac_f32_e32 v66, v74, v74
	v_add_f32_e32 v64, v64, v65
	v_add_f32_e32 v64, v66, v64
	v_fmac_f32_e32 v67, v72, v72
	v_add_f32_e32 v64, v67, v64
	v_add_f32_e32 v64, v82, v64
	v_mov_b32_e32 v65, v64
	s_nop 1
	v_permlane16_swap_b32_e32 v65, v64
	v_cvt_pk_bf16_f32 v66, v68, v69
	v_cvt_pk_bf16_f32 v67, v70, v71
	v_cvt_pk_bf16_f32 v68, v74, v75
	v_cvt_pk_bf16_f32 v69, v72, v73
	s_waitcnt lgkmcnt(0)
	v_add_f32_e32 v64, v64, v65
	v_mov_b32_e32 v65, v64
	s_nop 1
	v_permlane32_swap_b32_e32 v65, v64
	global_store_dwordx4 v[94:95], v[66:69], off offset:256
	s_and_saveexec_b64 s[30:31], s[2:3]
	s_cbranch_execz .LBB0_1013
	v_lshl_add_u64 v[66:67], v[80:81], 2, s[12:13]
	s_waitcnt lgkmcnt(0)
	v_add_f32_e32 v64, v64, v65
	global_atomic_add_f32 v[66:67], v64, off
;     __device__ __forceinline__ void operator()(const f32x4 (&acc)[2][2][4][2], const Unit& u, int wr, int wc, int fr, int fq) const {
;     ...
;         const int row0 = u.pm * BM + wr * 64 + fr, col0 = u.pn * BM + wc * 32 + 8 * fq; const bool odd = (fr & 1) != 0;
; #pragma unroll
;         for (int ai = 0; ai < 2; ++ai)
; #pragma unroll
;             for (int m = 0; m < 4; ++m) {
;                 const int row = row0 + ai * HALF + m * 16; float s = 0.f;
;                 const size_t off = (size_t)row * DM + col0;
;                 const size_t offp = (size_t)(row - (odd ? 1 : 0)) * DM + col0 + (odd ? 4 : 0);
; #pragma unroll
;                 for (int bj = 0; bj < 2; ++bj) {
;                     f32x4 b0, b1;
;                     if constexpr (BASE_F32) { const f32x4 la = *(const GAS f32x4*)(basef + offp + bj * HALF), lb = *(const GAS f32x4*)(basef + offp + DM + bj * HALF);
;                         const f32x4 snd = odd ? la : lb; f32x4 rcv; rcv[0] = dpp_xor1(snd[0]); rcv[1] = dpp_xor1(snd[1]); rcv[2] = dpp_xor1(snd[2]); rcv[3] = dpp_xor1(snd[3]);
;                         b0 = odd ? rcv : la; b1 = odd ? lb : rcv; }
;                     else { const u32x4 bw = *(const u32x4*)(baseb + off + bj * HALF);
;                         b0 = (f32x4){bf_lo(bw.x), bf_hi(bw.x), bf_lo(bw.y), bf_hi(bw.y)}; b1 = (f32x4){bf_lo(bw.z), bf_hi(bw.z), bf_lo(bw.w), bf_hi(bw.w)}; }
;                     const f32x4 v0 = acc[ai][bj][m][0] + b0, v1 = acc[ai][bj][m][1] + b1;
;                     if constexpr (OUT_F32) { const f32x4 snd = odd ? v0 : v1; f32x4 rcv; rcv[0] = dpp_xor1(snd[0]); rcv[1] = dpp_xor1(snd[1]); rcv[2] = dpp_xor1(snd[2]); rcv[3] = dpp_xor1(snd[3]);
;                         *(f32x4*)(H + offp + bj * HALF) = odd ? rcv : v0; *(f32x4*)(H + offp + DM + bj * HALF) = odd ? v1 : rcv; }
;                     else { u32x4 w; w.x = cvt_pk_bf16(v0[0], v0[1]); w.y = cvt_pk_bf16(v0[2], v0[3]); w.z = cvt_pk_bf16(v1[0], v1[1]); w.w = cvt_pk_bf16(v1[2], v1[3]);
;                         *(u32x4*)(HB + off + bj * HALF) = w; }
;                     s += (v0[0] * v0[0] + v0[1] * v0[1]) + (v0[2] * v0[2] + v0[3] * v0[3]) + (v1[0] * v1[0] + v1[1] * v1[1]) + (v1[2] * v1[2] + v1[3] * v1[3]);
;                 }
;                 s += __shfl_xor(s, 16); s += __shfl_xor(s, 32);
;                 if (fq == 0) unsafeAtomicAdd(ssn + row, s);
;             }
.LBB0_1013:
	s_or_b64 exec, exec, s[30:31]
	v_add_u32_e32 v64, 0x80, v148
	v_sub_u32_e32 v66, v64, v152
	v_ashrrev_i32_e32 v67, 31, v66
	v_lshlrev_b64 v[66:67], 13, v[66:67]
	v_lshl_add_u64 v[66:67], s[8:9], 0, v[66:67]
	v_lshl_add_u64 v[66:67], v[146:147], 2, v[66:67]
	v_lshl_add_u64 v[74:75], v[66:67], 0, v[136:137]
	v_add_co_u32_e32 v76, vcc, 0x2000, v74
	s_waitcnt lgkmcnt(0)
	v_ashrrev_i32_e32 v65, 31, v64
	v_addc_co_u32_e32 v77, vcc, 0, v75, vcc
	global_load_dwordx4 v[66:69], v[74:75], off
	global_load_dwordx4 v[70:73], v[76:77], off
	v_readlane_b32 s24, v254, 25
	v_mov_b32_e32 v80, v137
	v_mov_b32_e32 v81, v137
	v_mov_b32_e32 v82, v137
	v_mov_b32_e32 v83, v137
	v_lshlrev_b64 v[78:79], 12, v[64:65]
	v_readlane_b32 s25, v254, 26
	s_waitcnt vmcnt(0)
	v_cndmask_b32_e64 v84, v69, v73, s[0:1]
	v_cndmask_b32_e64 v85, v68, v72, s[0:1]
	v_cndmask_b32_e64 v86, v67, v71, s[0:1]
	v_cndmask_b32_e64 v87, v66, v70, s[0:1]
	v_lshl_add_u64 v[78:79], s[24:25], 0, v[78:79]
	v_mov_b32_dpp v81, v86 quad_perm:[1,0,3,2] row_mask:0xf bank_mask:0xf
	v_mov_b32_dpp v80, v87 quad_perm:[1,0,3,2] row_mask:0xf bank_mask:0xf
	v_mov_b32_dpp v82, v85 quad_perm:[1,0,3,2] row_mask:0xf bank_mask:0xf
	v_mov_b32_dpp v83, v84 quad_perm:[1,0,3,2] row_mask:0xf bank_mask:0xf
	v_lshl_add_u64 v[78:79], v[146:147], 1, v[78:79]
	v_cndmask_b32_e64 v67, v81, v67, s[0:1]
	v_cndmask_b32_e64 v66, v80, v66, s[0:1]
	v_cndmask_b32_e64 v69, v83, v69, s[0:1]
	v_cndmask_b32_e64 v68, v82, v68, s[0:1]
	v_cndmask_b32_e64 v71, v71, v81, s[0:1]
	v_cndmask_b32_e64 v70, v70, v80, s[0:1]
	v_cndmask_b32_e64 v73, v73, v83, s[0:1]
	v_cndmask_b32_e64 v72, v72, v82, s[0:1]
	v_pk_add_f32 v[68:69], v[62:63], v[68:69]
	v_pk_add_f32 v[66:67], v[60:61], v[66:67]
	v_pk_add_f32 v[72:73], v[58:59], v[72:73]
	v_pk_add_f32 v[70:71], v[56:57], v[70:71]
	v_cvt_pk_bf16_f32 v56, v66, v67
	v_cvt_pk_bf16_f32 v57, v68, v69
	v_mul_f32_e32 v67, v67, v67
	v_cvt_pk_bf16_f32 v58, v70, v71
	v_cvt_pk_bf16_f32 v59, v72, v73
	global_store_dwordx4 v[78:79], v[56:59], off
	global_load_dwordx4 v[56:59], v[74:75], off offset:512
	s_nop 0
	global_load_dwordx4 v[60:63], v[76:77], off offset:512
	v_mul_f32_e32 v69, v69, v69
	v_mul_f32_e32 v71, v71, v71
	v_fmac_f32_e32 v67, v66, v66
	v_fmac_f32_e32 v69, v68, v68
	v_mov_b32_e32 v74, v137
	v_mov_b32_e32 v75, v137
	v_mov_b32_e32 v76, v137
	v_mov_b32_e32 v77, v137
	v_fmac_f32_e32 v71, v70, v70
	v_add_f32_e32 v66, v67, v69
	v_mul_f32_e32 v73, v73, v73
	v_fmac_f32_e32 v73, v72, v72
	v_add_f32_e32 v66, v71, v66
	v_add_f32_e32 v66, v73, v66
	s_waitcnt vmcnt(0)
	v_cndmask_b32_e64 v67, v59, v63, s[0:1]
	v_cndmask_b32_e64 v68, v58, v62, s[0:1]
	v_cndmask_b32_e64 v69, v57, v61, s[0:1]
	v_cndmask_b32_e64 v70, v56, v60, s[0:1]
	v_mov_b32_dpp v76, v68 quad_perm:[1,0,3,2] row_mask:0xf bank_mask:0xf
	v_mov_b32_dpp v75, v69 quad_perm:[1,0,3,2] row_mask:0xf bank_mask:0xf
	v_mov_b32_dpp v74, v70 quad_perm:[1,0,3,2] row_mask:0xf bank_mask:0xf
	v_mov_b32_dpp v77, v67 quad_perm:[1,0,3,2] row_mask:0xf bank_mask:0xf
	v_cndmask_b32_e64 v57, v75, v57, s[0:1]
	v_cndmask_b32_e64 v56, v74, v56, s[0:1]
	v_cndmask_b32_e64 v59, v77, v59, s[0:1]
	v_cndmask_b32_e64 v58, v76, v58, s[0:1]
	v_cndmask_b32_e64 v61, v61, v75, s[0:1]
	v_cndmask_b32_e64 v60, v60, v74, s[0:1]
	v_pk_add_f32 v[54:55], v[54:55], v[58:59]
	v_pk_add_f32 v[52:53], v[52:53], v[56:57]
	v_cndmask_b32_e64 v63, v63, v77, s[0:1]
	v_cndmask_b32_e64 v62, v62, v76, s[0:1]
	v_pk_add_f32 v[58:59], v[48:49], v[60:61]
	v_mul_f32_e32 v48, v53, v53
	v_mul_f32_e32 v49, v55, v55
	v_pk_add_f32 v[56:57], v[50:51], v[62:63]
	v_mul_f32_e32 v50, v59, v59
	v_fmac_f32_e32 v48, v52, v52
	v_fmac_f32_e32 v49, v54, v54
	v_mul_f32_e32 v51, v57, v57
	v_fmac_f32_e32 v50, v58, v58
	v_add_f32_e32 v48, v48, v49
	v_add_f32_e32 v48, v50, v48
	v_fmac_f32_e32 v51, v56, v56
	v_add_f32_e32 v48, v51, v48
	v_add_f32_e32 v48, v66, v48
	v_mov_b32_e32 v49, v48
	s_nop 1
	v_permlane16_swap_b32_e32 v49, v48
	v_cvt_pk_bf16_f32 v50, v52, v53
	v_cvt_pk_bf16_f32 v51, v54, v55
	v_cvt_pk_bf16_f32 v52, v58, v59
	v_cvt_pk_bf16_f32 v53, v56, v57
	s_waitcnt lgkmcnt(0)
	v_add_f32_e32 v48, v48, v49
	v_mov_b32_e32 v49, v48
	s_nop 1
	v_permlane32_swap_b32_e32 v49, v48
	global_store_dwordx4 v[78:79], v[50:53], off offset:256
	s_and_saveexec_b64 s[30:31], s[2:3]
	s_cbranch_execz .LBB0_1015
	v_lshl_add_u64 v[50:51], v[64:65], 2, s[12:13]
	s_waitcnt lgkmcnt(0)
	v_add_f32_e32 v48, v48, v49
	global_atomic_add_f32 v[50:51], v48, off
;     __device__ __forceinline__ void operator()(const f32x4 (&acc)[2][2][4][2], const Unit& u, int wr, int wc, int fr, int fq) const {
;     ...
;         const int row0 = u.pm * BM + wr * 64 + fr, col0 = u.pn * BM + wc * 32 + 8 * fq; const bool odd = (fr & 1) != 0;
; #pragma unroll
;         for (int ai = 0; ai < 2; ++ai)
; #pragma unroll
;             for (int m = 0; m < 4; ++m) {
;                 const int row = row0 + ai * HALF + m * 16; float s = 0.f;
;                 const size_t off = (size_t)row * DM + col0;
;                 const size_t offp = (size_t)(row - (odd ? 1 : 0)) * DM + col0 + (odd ? 4 : 0);
; #pragma unroll
;                 for (int bj = 0; bj < 2; ++bj) {
;                     f32x4 b0, b1;
;                     if constexpr (BASE_F32) { const f32x4 la = *(const GAS f32x4*)(basef + offp + bj * HALF), lb = *(const GAS f32x4*)(basef + offp + DM + bj * HALF);
;                         const f32x4 snd = odd ? la : lb; f32x4 rcv; rcv[0] = dpp_xor1(snd[0]); rcv[1] = dpp_xor1(snd[1]); rcv[2] = dpp_xor1(snd[2]); rcv[3] = dpp_xor1(snd[3]);
;                         b0 = odd ? rcv : la; b1 = odd ? lb : rcv; }
;                     else { const u32x4 bw = *(const u32x4*)(baseb + off + bj * HALF);
;                         b0 = (f32x4){bf_lo(bw.x), bf_hi(bw.x), bf_lo(bw.y), bf_hi(bw.y)}; b1 = (f32x4){bf_lo(bw.z), bf_hi(bw.z), bf_lo(bw.w), bf_hi(bw.w)}; }
;                     const f32x4 v0 = acc[ai][bj][m][0] + b0, v1 = acc[ai][bj][m][1] + b1;
;                     if constexpr (OUT_F32) { const f32x4 snd = odd ? v0 : v1; f32x4 rcv; rcv[0] = dpp_xor1(snd[0]); rcv[1] = dpp_xor1(snd[1]); rcv[2] = dpp_xor1(snd[2]); rcv[3] = dpp_xor1(snd[3]);
;                         *(f32x4*)(H + offp + bj * HALF) = odd ? rcv : v0; *(f32x4*)(H + offp + DM + bj * HALF) = odd ? v1 : rcv; }
;                     else { u32x4 w; w.x = cvt_pk_bf16(v0[0], v0[1]); w.y = cvt_pk_bf16(v0[2], v0[3]); w.z = cvt_pk_bf16(v1[0], v1[1]); w.w = cvt_pk_bf16(v1[2], v1[3]);
;                         *(u32x4*)(HB + off + bj * HALF) = w; }
;                     s += (v0[0] * v0[0] + v0[1] * v0[1]) + (v0[2] * v0[2] + v0[3] * v0[3]) + (v1[0] * v1[0] + v1[1] * v1[1]) + (v1[2] * v1[2] + v1[3] * v1[3]);
;                 }
;                 s += __shfl_xor(s, 16); s += __shfl_xor(s, 32);
;                 if (fq == 0) unsafeAtomicAdd(ssn + row, s);
;             }
.LBB0_1015:
	s_or_b64 exec, exec, s[30:31]
	v_add_u32_e32 v48, 0x90, v148
	v_sub_u32_e32 v50, v48, v152
	v_ashrrev_i32_e32 v51, 31, v50
	v_lshlrev_b64 v[50:51], 13, v[50:51]
	v_lshl_add_u64 v[50:51], s[8:9], 0, v[50:51]
	v_lshl_add_u64 v[50:51], v[146:147], 2, v[50:51]
	v_lshl_add_u64 v[58:59], v[50:51], 0, v[136:137]
	v_add_co_u32_e32 v60, vcc, 0x2000, v58
	s_waitcnt lgkmcnt(0)
	v_ashrrev_i32_e32 v49, 31, v48
	v_addc_co_u32_e32 v61, vcc, 0, v59, vcc
	global_load_dwordx4 v[50:53], v[58:59], off
	global_load_dwordx4 v[54:57], v[60:61], off
	v_readlane_b32 s24, v254, 25
	v_mov_b32_e32 v64, v137
	v_mov_b32_e32 v65, v137
	v_mov_b32_e32 v66, v137
	v_mov_b32_e32 v67, v137
	v_lshlrev_b64 v[62:63], 12, v[48:49]
	v_readlane_b32 s25, v254, 26
	s_waitcnt vmcnt(0)
	v_cndmask_b32_e64 v68, v53, v57, s[0:1]
	v_cndmask_b32_e64 v69, v52, v56, s[0:1]
	v_cndmask_b32_e64 v70, v51, v55, s[0:1]
	v_cndmask_b32_e64 v71, v50, v54, s[0:1]
	v_lshl_add_u64 v[62:63], s[24:25], 0, v[62:63]
	v_mov_b32_dpp v65, v70 quad_perm:[1,0,3,2] row_mask:0xf bank_mask:0xf
	v_mov_b32_dpp v64, v71 quad_perm:[1,0,3,2] row_mask:0xf bank_mask:0xf
	v_mov_b32_dpp v66, v69 quad_perm:[1,0,3,2] row_mask:0xf bank_mask:0xf
	v_mov_b32_dpp v67, v68 quad_perm:[1,0,3,2] row_mask:0xf bank_mask:0xf
	v_lshl_add_u64 v[62:63], v[146:147], 1, v[62:63]
	v_cndmask_b32_e64 v51, v65, v51, s[0:1]
	v_cndmask_b32_e64 v50, v64, v50, s[0:1]
	v_cndmask_b32_e64 v53, v67, v53, s[0:1]
	v_cndmask_b32_e64 v52, v66, v52, s[0:1]
	v_cndmask_b32_e64 v55, v55, v65, s[0:1]
	v_cndmask_b32_e64 v54, v54, v64, s[0:1]
	v_cndmask_b32_e64 v57, v57, v67, s[0:1]
	v_cndmask_b32_e64 v56, v56, v66, s[0:1]
	v_pk_add_f32 v[52:53], v[46:47], v[52:53]
	v_pk_add_f32 v[50:51], v[44:45], v[50:51]
	v_pk_add_f32 v[56:57], v[42:43], v[56:57]
	v_pk_add_f32 v[54:55], v[40:41], v[54:55]
	v_cvt_pk_bf16_f32 v40, v50, v51
	v_cvt_pk_bf16_f32 v41, v52, v53
	v_mul_f32_e32 v51, v51, v51
	v_cvt_pk_bf16_f32 v42, v54, v55
	v_cvt_pk_bf16_f32 v43, v56, v57
	global_store_dwordx4 v[62:63], v[40:43], off
	global_load_dwordx4 v[40:43], v[58:59], off offset:512
	s_nop 0
	global_load_dwordx4 v[44:47], v[60:61], off offset:512
	v_mul_f32_e32 v53, v53, v53
	v_mul_f32_e32 v55, v55, v55
	v_fmac_f32_e32 v51, v50, v50
	v_fmac_f32_e32 v53, v52, v52
	v_mov_b32_e32 v58, v137
	v_mov_b32_e32 v59, v137
	v_mov_b32_e32 v60, v137
	v_mov_b32_e32 v61, v137
	v_fmac_f32_e32 v55, v54, v54
	v_add_f32_e32 v50, v51, v53
	v_mul_f32_e32 v57, v57, v57
	v_fmac_f32_e32 v57, v56, v56
	v_add_f32_e32 v50, v55, v50
	v_add_f32_e32 v50, v57, v50
	s_waitcnt vmcnt(0)
	v_cndmask_b32_e64 v51, v43, v47, s[0:1]
	v_cndmask_b32_e64 v52, v42, v46, s[0:1]
	v_cndmask_b32_e64 v53, v41, v45, s[0:1]
	v_cndmask_b32_e64 v54, v40, v44, s[0:1]
	v_mov_b32_dpp v60, v52 quad_perm:[1,0,3,2] row_mask:0xf bank_mask:0xf
	v_mov_b32_dpp v59, v53 quad_perm:[1,0,3,2] row_mask:0xf bank_mask:0xf
	v_mov_b32_dpp v58, v54 quad_perm:[1,0,3,2] row_mask:0xf bank_mask:0xf
	v_mov_b32_dpp v61, v51 quad_perm:[1,0,3,2] row_mask:0xf bank_mask:0xf
	v_cndmask_b32_e64 v41, v59, v41, s[0:1]
	v_cndmask_b32_e64 v40, v58, v40, s[0:1]
	v_cndmask_b32_e64 v43, v61, v43, s[0:1]
	v_cndmask_b32_e64 v42, v60, v42, s[0:1]
	v_cndmask_b32_e64 v45, v45, v59, s[0:1]
	v_cndmask_b32_e64 v44, v44, v58, s[0:1]
	v_pk_add_f32 v[38:39], v[38:39], v[42:43]
	v_pk_add_f32 v[36:37], v[36:37], v[40:41]
	v_cndmask_b32_e64 v47, v47, v61, s[0:1]
	v_cndmask_b32_e64 v46, v46, v60, s[0:1]
	v_pk_add_f32 v[42:43], v[32:33], v[44:45]
	v_mul_f32_e32 v32, v37, v37
	v_mul_f32_e32 v33, v39, v39
	v_pk_add_f32 v[40:41], v[34:35], v[46:47]
	v_mul_f32_e32 v34, v43, v43
	v_fmac_f32_e32 v32, v36, v36
	v_fmac_f32_e32 v33, v38, v38
	v_mul_f32_e32 v35, v41, v41
	v_fmac_f32_e32 v34, v42, v42
	v_add_f32_e32 v32, v32, v33
	v_add_f32_e32 v32, v34, v32
	v_fmac_f32_e32 v35, v40, v40
	v_add_f32_e32 v32, v35, v32
	v_add_f32_e32 v32, v50, v32
	v_mov_b32_e32 v33, v32
	s_nop 1
	v_permlane16_swap_b32_e32 v33, v32
	v_cvt_pk_bf16_f32 v34, v36, v37
	v_cvt_pk_bf16_f32 v35, v38, v39
	v_cvt_pk_bf16_f32 v36, v42, v43
	v_cvt_pk_bf16_f32 v37, v40, v41
	s_waitcnt lgkmcnt(0)
	v_add_f32_e32 v32, v32, v33
	v_mov_b32_e32 v33, v32
	s_nop 1
	v_permlane32_swap_b32_e32 v33, v32
	global_store_dwordx4 v[62:63], v[34:37], off offset:256
	s_and_saveexec_b64 s[30:31], s[2:3]
	s_cbranch_execz .LBB0_1017
	v_lshl_add_u64 v[34:35], v[48:49], 2, s[12:13]
	s_waitcnt lgkmcnt(0)
	v_add_f32_e32 v32, v32, v33
	global_atomic_add_f32 v[34:35], v32, off
;     __device__ __forceinline__ void operator()(const f32x4 (&acc)[2][2][4][2], const Unit& u, int wr, int wc, int fr, int fq) const {
;     ...
;         const int row0 = u.pm * BM + wr * 64 + fr, col0 = u.pn * BM + wc * 32 + 8 * fq; const bool odd = (fr & 1) != 0;
; #pragma unroll
;         for (int ai = 0; ai < 2; ++ai)
; #pragma unroll
;             for (int m = 0; m < 4; ++m) {
;                 const int row = row0 + ai * HALF + m * 16; float s = 0.f;
;                 const size_t off = (size_t)row * DM + col0;
;                 const size_t offp = (size_t)(row - (odd ? 1 : 0)) * DM + col0 + (odd ? 4 : 0);
; #pragma unroll
;                 for (int bj = 0; bj < 2; ++bj) {
;                     f32x4 b0, b1;
;                     if constexpr (BASE_F32) { const f32x4 la = *(const GAS f32x4*)(basef + offp + bj * HALF), lb = *(const GAS f32x4*)(basef + offp + DM + bj * HALF);
;                         const f32x4 snd = odd ? la : lb; f32x4 rcv; rcv[0] = dpp_xor1(snd[0]); rcv[1] = dpp_xor1(snd[1]); rcv[2] = dpp_xor1(snd[2]); rcv[3] = dpp_xor1(snd[3]);
;                         b0 = odd ? rcv : la; b1 = odd ? lb : rcv; }
;                     else { const u32x4 bw = *(const u32x4*)(baseb + off + bj * HALF);
;                         b0 = (f32x4){bf_lo(bw.x), bf_hi(bw.x), bf_lo(bw.y), bf_hi(bw.y)}; b1 = (f32x4){bf_lo(bw.z), bf_hi(bw.z), bf_lo(bw.w), bf_hi(bw.w)}; }
;                     const f32x4 v0 = acc[ai][bj][m][0] + b0, v1 = acc[ai][bj][m][1] + b1;
;                     if constexpr (OUT_F32) { const f32x4 snd = odd ? v0 : v1; f32x4 rcv; rcv[0] = dpp_xor1(snd[0]); rcv[1] = dpp_xor1(snd[1]); rcv[2] = dpp_xor1(snd[2]); rcv[3] = dpp_xor1(snd[3]);
;                         *(f32x4*)(H + offp + bj * HALF) = odd ? rcv : v0; *(f32x4*)(H + offp + DM + bj * HALF) = odd ? v1 : rcv; }
;                     else { u32x4 w; w.x = cvt_pk_bf16(v0[0], v0[1]); w.y = cvt_pk_bf16(v0[2], v0[3]); w.z = cvt_pk_bf16(v1[0], v1[1]); w.w = cvt_pk_bf16(v1[2], v1[3]);
;                         *(u32x4*)(HB + off + bj * HALF) = w; }
;                     s += (v0[0] * v0[0] + v0[1] * v0[1]) + (v0[2] * v0[2] + v0[3] * v0[3]) + (v1[0] * v1[0] + v1[1] * v1[1]) + (v1[2] * v1[2] + v1[3] * v1[3]);
;                 }
;                 s += __shfl_xor(s, 16); s += __shfl_xor(s, 32);
;                 if (fq == 0) unsafeAtomicAdd(ssn + row, s);
;             }
.LBB0_1017:
	s_or_b64 exec, exec, s[30:31]
	v_add_u32_e32 v32, 0xa0, v148
	v_sub_u32_e32 v34, v32, v152
	v_ashrrev_i32_e32 v35, 31, v34
	v_lshlrev_b64 v[34:35], 13, v[34:35]
	v_lshl_add_u64 v[34:35], s[8:9], 0, v[34:35]
	v_lshl_add_u64 v[34:35], v[146:147], 2, v[34:35]
	v_lshl_add_u64 v[42:43], v[34:35], 0, v[136:137]
	v_add_co_u32_e32 v44, vcc, 0x2000, v42
	s_waitcnt lgkmcnt(0)
	v_ashrrev_i32_e32 v33, 31, v32
	v_addc_co_u32_e32 v45, vcc, 0, v43, vcc
	global_load_dwordx4 v[34:37], v[42:43], off
	global_load_dwordx4 v[38:41], v[44:45], off
	v_readlane_b32 s24, v254, 25
	v_mov_b32_e32 v48, v137
	v_mov_b32_e32 v49, v137
	v_mov_b32_e32 v50, v137
	v_mov_b32_e32 v51, v137
	v_lshlrev_b64 v[46:47], 12, v[32:33]
	v_readlane_b32 s25, v254, 26
	s_waitcnt vmcnt(0)
	v_cndmask_b32_e64 v52, v37, v41, s[0:1]
	v_cndmask_b32_e64 v53, v36, v40, s[0:1]
	v_cndmask_b32_e64 v54, v35, v39, s[0:1]
	v_cndmask_b32_e64 v55, v34, v38, s[0:1]
	v_lshl_add_u64 v[46:47], s[24:25], 0, v[46:47]
	v_mov_b32_dpp v49, v54 quad_perm:[1,0,3,2] row_mask:0xf bank_mask:0xf
	v_mov_b32_dpp v48, v55 quad_perm:[1,0,3,2] row_mask:0xf bank_mask:0xf
	v_mov_b32_dpp v50, v53 quad_perm:[1,0,3,2] row_mask:0xf bank_mask:0xf
	v_mov_b32_dpp v51, v52 quad_perm:[1,0,3,2] row_mask:0xf bank_mask:0xf
	v_lshl_add_u64 v[46:47], v[146:147], 1, v[46:47]
	v_cndmask_b32_e64 v35, v49, v35, s[0:1]
	v_cndmask_b32_e64 v34, v48, v34, s[0:1]
	v_cndmask_b32_e64 v37, v51, v37, s[0:1]
	v_cndmask_b32_e64 v36, v50, v36, s[0:1]
	v_cndmask_b32_e64 v39, v39, v49, s[0:1]
	v_cndmask_b32_e64 v38, v38, v48, s[0:1]
	v_cndmask_b32_e64 v41, v41, v51, s[0:1]
	v_cndmask_b32_e64 v40, v40, v50, s[0:1]
	v_pk_add_f32 v[36:37], v[30:31], v[36:37]
	v_pk_add_f32 v[34:35], v[28:29], v[34:35]
	v_pk_add_f32 v[40:41], v[26:27], v[40:41]
	v_pk_add_f32 v[38:39], v[24:25], v[38:39]
	v_cvt_pk_bf16_f32 v24, v34, v35
	v_cvt_pk_bf16_f32 v25, v36, v37
	v_mul_f32_e32 v35, v35, v35
	v_cvt_pk_bf16_f32 v26, v38, v39
	v_cvt_pk_bf16_f32 v27, v40, v41
	global_store_dwordx4 v[46:47], v[24:27], off
	global_load_dwordx4 v[24:27], v[42:43], off offset:512
	s_nop 0
	global_load_dwordx4 v[28:31], v[44:45], off offset:512
	v_mul_f32_e32 v37, v37, v37
	v_mul_f32_e32 v39, v39, v39
	v_fmac_f32_e32 v35, v34, v34
	v_fmac_f32_e32 v37, v36, v36
	v_mov_b32_e32 v42, v137
	v_mov_b32_e32 v43, v137
	v_mov_b32_e32 v44, v137
	v_mov_b32_e32 v45, v137
	v_fmac_f32_e32 v39, v38, v38
	v_add_f32_e32 v34, v35, v37
	v_mul_f32_e32 v41, v41, v41
	v_fmac_f32_e32 v41, v40, v40
	v_add_f32_e32 v34, v39, v34
	v_add_f32_e32 v34, v41, v34
	s_waitcnt vmcnt(0)
	v_cndmask_b32_e64 v35, v27, v31, s[0:1]
	v_cndmask_b32_e64 v36, v26, v30, s[0:1]
	v_cndmask_b32_e64 v37, v25, v29, s[0:1]
	v_cndmask_b32_e64 v38, v24, v28, s[0:1]
	v_mov_b32_dpp v44, v36 quad_perm:[1,0,3,2] row_mask:0xf bank_mask:0xf
	v_mov_b32_dpp v43, v37 quad_perm:[1,0,3,2] row_mask:0xf bank_mask:0xf
	v_mov_b32_dpp v42, v38 quad_perm:[1,0,3,2] row_mask:0xf bank_mask:0xf
	v_mov_b32_dpp v45, v35 quad_perm:[1,0,3,2] row_mask:0xf bank_mask:0xf
	v_cndmask_b32_e64 v25, v43, v25, s[0:1]
	v_cndmask_b32_e64 v24, v42, v24, s[0:1]
	v_cndmask_b32_e64 v27, v45, v27, s[0:1]
	v_cndmask_b32_e64 v26, v44, v26, s[0:1]
	v_cndmask_b32_e64 v29, v29, v43, s[0:1]
	v_cndmask_b32_e64 v28, v28, v42, s[0:1]
	v_pk_add_f32 v[22:23], v[22:23], v[26:27]
	v_pk_add_f32 v[20:21], v[20:21], v[24:25]
	v_cndmask_b32_e64 v31, v31, v45, s[0:1]
	v_cndmask_b32_e64 v30, v30, v44, s[0:1]
	v_pk_add_f32 v[26:27], v[16:17], v[28:29]
	v_mul_f32_e32 v16, v21, v21
	v_mul_f32_e32 v17, v23, v23
	v_pk_add_f32 v[24:25], v[18:19], v[30:31]
	v_mul_f32_e32 v18, v27, v27
	v_fmac_f32_e32 v16, v20, v20
	v_fmac_f32_e32 v17, v22, v22
	v_mul_f32_e32 v19, v25, v25
	v_fmac_f32_e32 v18, v26, v26
	v_add_f32_e32 v16, v16, v17
	v_add_f32_e32 v16, v18, v16
	v_fmac_f32_e32 v19, v24, v24
	v_add_f32_e32 v16, v19, v16
	v_add_f32_e32 v16, v34, v16
	v_mov_b32_e32 v17, v16
	s_nop 1
	v_permlane16_swap_b32_e32 v17, v16
	v_cvt_pk_bf16_f32 v18, v20, v21
	v_cvt_pk_bf16_f32 v19, v22, v23
	v_cvt_pk_bf16_f32 v20, v26, v27
	v_cvt_pk_bf16_f32 v21, v24, v25
	s_waitcnt lgkmcnt(0)
	v_add_f32_e32 v16, v16, v17
	v_mov_b32_e32 v17, v16
	s_nop 1
	v_permlane32_swap_b32_e32 v17, v16
	global_store_dwordx4 v[46:47], v[18:21], off offset:256
	s_and_saveexec_b64 s[30:31], s[2:3]
	s_cbranch_execz .LBB0_1019
	v_lshl_add_u64 v[18:19], v[32:33], 2, s[12:13]
	s_waitcnt lgkmcnt(0)
	v_add_f32_e32 v16, v16, v17
	global_atomic_add_f32 v[18:19], v16, off
;     __device__ __forceinline__ void operator()(const f32x4 (&acc)[2][2][4][2], const Unit& u, int wr, int wc, int fr, int fq) const {
;     ...
;         const int row0 = u.pm * BM + wr * 64 + fr, col0 = u.pn * BM + wc * 32 + 8 * fq; const bool odd = (fr & 1) != 0;
; #pragma unroll
;         for (int ai = 0; ai < 2; ++ai)
; #pragma unroll
;             for (int m = 0; m < 4; ++m) {
;                 const int row = row0 + ai * HALF + m * 16; float s = 0.f;
;                 const size_t off = (size_t)row * DM + col0;
;                 const size_t offp = (size_t)(row - (odd ? 1 : 0)) * DM + col0 + (odd ? 4 : 0);
; #pragma unroll
;                 for (int bj = 0; bj < 2; ++bj) {
;                     f32x4 b0, b1;
;                     if constexpr (BASE_F32) { const f32x4 la = *(const GAS f32x4*)(basef + offp + bj * HALF), lb = *(const GAS f32x4*)(basef + offp + DM + bj * HALF);
;                         const f32x4 snd = odd ? la : lb; f32x4 rcv; rcv[0] = dpp_xor1(snd[0]); rcv[1] = dpp_xor1(snd[1]); rcv[2] = dpp_xor1(snd[2]); rcv[3] = dpp_xor1(snd[3]);
;                         b0 = odd ? rcv : la; b1 = odd ? lb : rcv; }
;                     else { const u32x4 bw = *(const u32x4*)(baseb + off + bj * HALF);
;                         b0 = (f32x4){bf_lo(bw.x), bf_hi(bw.x), bf_lo(bw.y), bf_hi(bw.y)}; b1 = (f32x4){bf_lo(bw.z), bf_hi(bw.z), bf_lo(bw.w), bf_hi(bw.w)}; }
;                     const f32x4 v0 = acc[ai][bj][m][0] + b0, v1 = acc[ai][bj][m][1] + b1;
;                     if constexpr (OUT_F32) { const f32x4 snd = odd ? v0 : v1; f32x4 rcv; rcv[0] = dpp_xor1(snd[0]); rcv[1] = dpp_xor1(snd[1]); rcv[2] = dpp_xor1(snd[2]); rcv[3] = dpp_xor1(snd[3]);
;                         *(f32x4*)(H + offp + bj * HALF) = odd ? rcv : v0; *(f32x4*)(H + offp + DM + bj * HALF) = odd ? v1 : rcv; }
;                     else { u32x4 w; w.x = cvt_pk_bf16(v0[0], v0[1]); w.y = cvt_pk_bf16(v0[2], v0[3]); w.z = cvt_pk_bf16(v1[0], v1[1]); w.w = cvt_pk_bf16(v1[2], v1[3]);
;                         *(u32x4*)(HB + off + bj * HALF) = w; }
;                     s += (v0[0] * v0[0] + v0[1] * v0[1]) + (v0[2] * v0[2] + v0[3] * v0[3]) + (v1[0] * v1[0] + v1[1] * v1[1]) + (v1[2] * v1[2] + v1[3] * v1[3]);
;                 }
;                 s += __shfl_xor(s, 16); s += __shfl_xor(s, 32);
;                 if (fq == 0) unsafeAtomicAdd(ssn + row, s);
;             }
.LBB0_1019:
	s_or_b64 exec, exec, s[30:31]
	v_add_u32_e32 v16, 0xb0, v148
	v_sub_u32_e32 v18, v16, v152
	v_ashrrev_i32_e32 v19, 31, v18
	v_lshlrev_b64 v[18:19], 13, v[18:19]
	v_lshl_add_u64 v[18:19], s[8:9], 0, v[18:19]
	v_lshl_add_u64 v[18:19], v[146:147], 2, v[18:19]
	v_lshl_add_u64 v[26:27], v[18:19], 0, v[136:137]
	v_add_co_u32_e32 v28, vcc, 0x2000, v26
	s_waitcnt lgkmcnt(0)
	v_ashrrev_i32_e32 v17, 31, v16
	v_addc_co_u32_e32 v29, vcc, 0, v27, vcc
	global_load_dwordx4 v[18:21], v[26:27], off
	global_load_dwordx4 v[22:25], v[28:29], off
	v_readlane_b32 s24, v254, 25
	v_mov_b32_e32 v32, v137
	v_mov_b32_e32 v33, v137
	v_mov_b32_e32 v34, v137
	v_mov_b32_e32 v35, v137
	v_lshlrev_b64 v[30:31], 12, v[16:17]
	v_readlane_b32 s25, v254, 26
	s_waitcnt vmcnt(0)
	v_cndmask_b32_e64 v36, v21, v25, s[0:1]
	v_cndmask_b32_e64 v37, v20, v24, s[0:1]
	v_cndmask_b32_e64 v38, v19, v23, s[0:1]
	v_cndmask_b32_e64 v39, v18, v22, s[0:1]
	v_lshl_add_u64 v[30:31], s[24:25], 0, v[30:31]
	v_mov_b32_dpp v33, v38 quad_perm:[1,0,3,2] row_mask:0xf bank_mask:0xf
	v_mov_b32_dpp v32, v39 quad_perm:[1,0,3,2] row_mask:0xf bank_mask:0xf
	v_mov_b32_dpp v34, v37 quad_perm:[1,0,3,2] row_mask:0xf bank_mask:0xf
	v_mov_b32_dpp v35, v36 quad_perm:[1,0,3,2] row_mask:0xf bank_mask:0xf
	v_lshl_add_u64 v[30:31], v[146:147], 1, v[30:31]
	v_cndmask_b32_e64 v19, v33, v19, s[0:1]
	v_cndmask_b32_e64 v18, v32, v18, s[0:1]
	v_cndmask_b32_e64 v21, v35, v21, s[0:1]
	v_cndmask_b32_e64 v20, v34, v20, s[0:1]
	v_cndmask_b32_e64 v23, v23, v33, s[0:1]
	v_cndmask_b32_e64 v22, v22, v32, s[0:1]
	v_cndmask_b32_e64 v25, v25, v35, s[0:1]
	v_cndmask_b32_e64 v24, v24, v34, s[0:1]
	v_pk_add_f32 v[20:21], v[14:15], v[20:21]
	v_pk_add_f32 v[18:19], v[12:13], v[18:19]
	v_pk_add_f32 v[24:25], v[10:11], v[24:25]
	v_pk_add_f32 v[22:23], v[8:9], v[22:23]
	v_cvt_pk_bf16_f32 v8, v18, v19
	v_cvt_pk_bf16_f32 v9, v20, v21
	v_mul_f32_e32 v19, v19, v19
	v_cvt_pk_bf16_f32 v10, v22, v23
	v_cvt_pk_bf16_f32 v11, v24, v25
	global_store_dwordx4 v[30:31], v[8:11], off
	global_load_dwordx4 v[8:11], v[26:27], off offset:512
	s_nop 0
	global_load_dwordx4 v[12:15], v[28:29], off offset:512
	v_mul_f32_e32 v21, v21, v21
	v_mul_f32_e32 v23, v23, v23
	v_fmac_f32_e32 v19, v18, v18
	v_fmac_f32_e32 v21, v20, v20
	v_mov_b32_e32 v26, v137
	v_mov_b32_e32 v27, v137
	v_mov_b32_e32 v28, v137
	v_mov_b32_e32 v29, v137
	v_fmac_f32_e32 v23, v22, v22
	v_add_f32_e32 v18, v19, v21
	v_mul_f32_e32 v25, v25, v25
	v_fmac_f32_e32 v25, v24, v24
	v_add_f32_e32 v18, v23, v18
	v_add_f32_e32 v18, v25, v18
	s_waitcnt vmcnt(0)
	v_cndmask_b32_e64 v19, v11, v15, s[0:1]
	v_cndmask_b32_e64 v20, v10, v14, s[0:1]
	v_cndmask_b32_e64 v21, v9, v13, s[0:1]
	v_cndmask_b32_e64 v22, v8, v12, s[0:1]
	v_mov_b32_dpp v28, v20 quad_perm:[1,0,3,2] row_mask:0xf bank_mask:0xf
	v_mov_b32_dpp v27, v21 quad_perm:[1,0,3,2] row_mask:0xf bank_mask:0xf
	v_mov_b32_dpp v26, v22 quad_perm:[1,0,3,2] row_mask:0xf bank_mask:0xf
	v_mov_b32_dpp v29, v19 quad_perm:[1,0,3,2] row_mask:0xf bank_mask:0xf
	v_cndmask_b32_e64 v9, v27, v9, s[0:1]
	v_cndmask_b32_e64 v8, v26, v8, s[0:1]
	v_cndmask_b32_e64 v11, v29, v11, s[0:1]
	v_cndmask_b32_e64 v10, v28, v10, s[0:1]
	v_cndmask_b32_e64 v13, v13, v27, s[0:1]
	v_cndmask_b32_e64 v12, v12, v26, s[0:1]
	v_pk_add_f32 v[6:7], v[6:7], v[10:11]
	v_pk_add_f32 v[4:5], v[4:5], v[8:9]
	v_cndmask_b32_e64 v15, v15, v29, s[0:1]
	v_cndmask_b32_e64 v14, v14, v28, s[0:1]
	v_pk_add_f32 v[10:11], v[0:1], v[12:13]
	v_mul_f32_e32 v0, v5, v5
	v_mul_f32_e32 v1, v7, v7
	v_pk_add_f32 v[8:9], v[2:3], v[14:15]
	v_mul_f32_e32 v2, v11, v11
	v_fmac_f32_e32 v0, v4, v4
	v_fmac_f32_e32 v1, v6, v6
	v_mul_f32_e32 v3, v9, v9
	v_fmac_f32_e32 v2, v10, v10
	v_add_f32_e32 v0, v0, v1
	v_add_f32_e32 v0, v2, v0
	v_fmac_f32_e32 v3, v8, v8
	v_add_f32_e32 v0, v3, v0
	v_add_f32_e32 v0, v18, v0
	v_mov_b32_e32 v1, v0
	s_nop 1
	v_permlane16_swap_b32_e32 v1, v0
	v_cvt_pk_bf16_f32 v2, v4, v5
	v_cvt_pk_bf16_f32 v3, v6, v7
	v_cvt_pk_bf16_f32 v4, v10, v11
	v_cvt_pk_bf16_f32 v5, v8, v9
	s_waitcnt lgkmcnt(0)
	v_add_f32_e32 v0, v0, v1
	v_mov_b32_e32 v1, v0
	s_nop 1
	v_permlane32_swap_b32_e32 v1, v0
	global_store_dwordx4 v[30:31], v[2:5], off offset:256
	s_and_saveexec_b64 s[30:31], s[2:3]
	s_cbranch_execz .LBB0_1021
	v_lshl_add_u64 v[2:3], v[16:17], 2, s[12:13]
	s_waitcnt lgkmcnt(0)
	v_add_f32_e32 v0, v0, v1
	global_atomic_add_f32 v[2:3], v0, off

; __device__ __forceinline__ unsigned cvt_pk_bf16(float lo, float hi) { unsigned r; asm volatile("v_cvt_pk_bf16_f32 %0, %1, %2" : "=v"(r) : "v"(lo), "v"(hi)); return r; }
; __device__ __forceinline__ unsigned dpp_xor1(unsigned v) { return (unsigned)__builtin_amdgcn_update_dpp(0, (int)v, 0xB1, 0xf, 0xf, false); }
;     __device__ __forceinline__ void operator()(const f32x4 (&acc)[2][2][4][2], const Unit& u, int wr, int wc, int fr, int fq) const {
;         if constexpr (ALLBF) {
;             const int row0 = u.pm * BM + wr * 64 + fr, col0 = u.pn * BM + wc * 64 + 16 * fq; const bool odd = (fr & 1) != 0;
; #pragma unroll
;             for (int ai = 0; ai < 2; ++ai)
; #pragma unroll
;                 for (int m = 0; m < 4; ++m) {
;                     const int row = row0 + ai * HALF + m * 16; float s = 0.f;
;                     const bf16_t* pa = baseb + (size_t)(row - (odd ? 1 : 0)) * DM + col0 + (odd ? 8 : 0);
;                     const u32x4 la = *(const u32x4*)pa, lb = *(const u32x4*)(pa + DM);
;                     const u32x4 snd = odd ? la : lb; u32x4 rcv;
;                     rcv.x = dpp_xor1(snd.x); rcv.y = dpp_xor1(snd.y); rcv.z = dpp_xor1(snd.z); rcv.w = dpp_xor1(snd.w);
;                     const u32x4 bw0 = odd ? rcv : la, bw1 = odd ? lb : rcv;
;                     u32x4 pw[2];
; #pragma unroll
;                     for (int bj = 0; bj < 2; ++bj) { const u32x4 bw = bj ? bw1 : bw0;
;                         const f32x4 b0 = (f32x4){bf_lo(bw.x), bf_hi(bw.x), bf_lo(bw.y), bf_hi(bw.y)}, b1 = (f32x4){bf_lo(bw.z), bf_hi(bw.z), bf_lo(bw.w), bf_hi(bw.w)};
;                         const f32x4 v0 = acc[ai][bj][m][0] + b0, v1 = acc[ai][bj][m][1] + b1;
;                         pw[bj].x = cvt_pk_bf16(v0[0], v0[1]); pw[bj].y = cvt_pk_bf16(v0[2], v0[3]); pw[bj].z = cvt_pk_bf16(v1[0], v1[1]); pw[bj].w = cvt_pk_bf16(v1[2], v1[3]);
;                         s += (v0[0] * v0[0] + v0[1] * v0[1]) + (v0[2] * v0[2] + v0[3] * v0[3]) + (v1[0] * v1[0] + v1[1] * v1[1]) + (v1[2] * v1[2] + v1[3] * v1[3]); }
;                     store_pair_rows(HB, (size_t)DM, row, col0, fr, pw[0], pw[1]);
;                     s += __shfl_xor(s, 16); s += __shfl_xor(s, 32);
;                     if (fq == 0) unsafeAtomicAdd(ssn + row, s);
;                 }
.LBB0_1253:
	v_lshl_add_u32 v152, s42, 8, v156
	v_sub_u32_e32 v154, v152, v158
	v_ashrrev_i32_e32 v155, 31, v154
	v_readlane_b32 s22, v254, 25
	v_lshl_or_b32 v150, s43, 8, v159
	v_lshlrev_b64 v[154:155], 12, v[154:155]
	v_readlane_b32 s23, v254, 26
	v_ashrrev_i32_e32 v151, 31, v150
	v_mov_b32_e32 v153, v141
	v_lshl_add_u64 v[154:155], s[22:23], 0, v[154:155]
	v_lshl_add_u64 v[154:155], v[150:151], 1, v[154:155]
	v_lshl_add_u64 v[172:173], v[154:155], 0, v[140:141]
	v_add_co_u32_e32 v154, vcc, 0x1000, v172
	v_mov_b32_e32 v174, v141
	s_nop 0
	v_addc_co_u32_e32 v155, vcc, 0, v173, vcc
	global_load_dwordx4 v[164:167], v[172:173], off
	global_load_dwordx4 v[168:171], v[154:155], off
	v_mov_b32_e32 v176, v141
	v_mov_b32_e32 v175, v141
	v_mov_b32_e32 v183, v141
	v_mov_b32_e32 v184, v141
	v_mov_b32_e32 v182, v141
	s_waitcnt vmcnt(0)
	v_cndmask_b32_e64 v177, v167, v171, s[0:1]
	v_cndmask_b32_e64 v179, v165, v169, s[0:1]
	v_cndmask_b32_e64 v180, v164, v168, s[0:1]
	v_cndmask_b32_e64 v178, v166, v170, s[0:1]
	v_mov_b32_dpp v174, v179 quad_perm:[1,0,3,2] row_mask:0xf bank_mask:0xf
	v_mov_b32_dpp v153, v180 quad_perm:[1,0,3,2] row_mask:0xf bank_mask:0xf
	v_mov_b32_dpp v176, v177 quad_perm:[1,0,3,2] row_mask:0xf bank_mask:0xf
	v_mov_b32_dpp v175, v178 quad_perm:[1,0,3,2] row_mask:0xf bank_mask:0xf
	v_cndmask_b32_e64 v177, v176, v167, s[0:1]
	v_cndmask_b32_e64 v167, v174, v165, s[0:1]
	v_cndmask_b32_e64 v165, v153, v164, s[0:1]
	v_cndmask_b32_e64 v180, v169, v174, s[0:1]
	v_cndmask_b32_e64 v153, v168, v153, s[0:1]
	v_cndmask_b32_e64 v178, v175, v166, s[0:1]
	v_cndmask_b32_e64 v181, v171, v176, s[0:1]
	v_cndmask_b32_e64 v179, v170, v175, s[0:1]
	v_lshlrev_b32_e32 v164, 16, v165
	v_and_b32_e32 v165, 0xffff0000, v165
	v_lshlrev_b32_e32 v166, 16, v167
	v_and_b32_e32 v167, 0xffff0000, v167
	v_lshlrev_b32_e32 v170, 16, v177
	v_and_b32_e32 v171, 0xffff0000, v177
	v_lshlrev_b32_e32 v174, 16, v153
	v_and_b32_e32 v175, 0xffff0000, v153
	v_lshlrev_b32_e32 v176, 16, v180
	v_and_b32_e32 v177, 0xffff0000, v180
	v_lshlrev_b32_e32 v168, 16, v178
	v_and_b32_e32 v169, 0xffff0000, v178
	v_lshlrev_b32_e32 v178, 16, v179
	v_and_b32_e32 v179, 0xffff0000, v179
	v_lshlrev_b32_e32 v180, 16, v181
	v_and_b32_e32 v181, 0xffff0000, v181
	v_pk_add_f32 v[126:127], v[126:127], v[166:167]
	v_pk_add_f32 v[124:125], v[124:125], v[164:165]
	v_pk_add_f32 v[118:119], v[118:119], v[176:177]
	v_pk_add_f32 v[116:117], v[116:117], v[174:175]
	v_pk_add_f32 v[122:123], v[122:123], v[170:171]
	v_pk_add_f32 v[120:121], v[120:121], v[168:169]
	v_pk_add_f32 v[114:115], v[114:115], v[180:181]
	v_pk_add_f32 v[112:113], v[112:113], v[178:179]
	v_cvt_pk_bf16_f32 v153, v124, v125
	v_cvt_pk_bf16_f32 v164, v126, v127
	v_cvt_pk_bf16_f32 v165, v120, v121
	v_cvt_pk_bf16_f32 v166, v122, v123
	v_mul_f32_e32 v125, v125, v125
	v_mul_f32_e32 v127, v127, v127
	v_cvt_pk_bf16_f32 v167, v116, v117
	v_cvt_pk_bf16_f32 v168, v118, v119
	v_mul_f32_e32 v117, v117, v117
	v_mul_f32_e32 v119, v119, v119
	v_mul_f32_e32 v121, v121, v121
	v_cvt_pk_bf16_f32 v169, v112, v113
	v_cvt_pk_bf16_f32 v170, v114, v115
	v_mul_f32_e32 v113, v113, v113
	v_mul_f32_e32 v115, v115, v115
	v_fmac_f32_e32 v125, v124, v124
	v_fmac_f32_e32 v127, v126, v126
	v_fmac_f32_e32 v117, v116, v116
	v_fmac_f32_e32 v119, v118, v118
	v_fmac_f32_e32 v121, v120, v120
	v_fmac_f32_e32 v113, v112, v112
	v_fmac_f32_e32 v115, v114, v114
	v_cndmask_b32_e64 v114, v165, v169, s[0:1]
	v_cndmask_b32_e64 v116, v164, v168, s[0:1]
	v_add_f32_e32 v120, v125, v127
	v_add_f32_e32 v117, v117, v119
	v_cndmask_b32_e64 v112, v166, v170, s[0:1]
	v_mov_b32_dpp v183, v116 quad_perm:[1,0,3,2] row_mask:0xf bank_mask:0xf
	v_add_f32_e32 v116, v121, v120
	v_add_f32_e32 v113, v113, v117
	v_mov_b32_dpp v184, v114 quad_perm:[1,0,3,2] row_mask:0xf bank_mask:0xf
	v_mov_b32_e32 v120, v141
	v_and_b32_e32 v114, 64, v163
	v_mul_f32_e32 v123, v123, v123
	v_add_f32_e32 v113, v115, v113
	v_mov_b32_dpp v120, v112 quad_perm:[1,0,3,2] row_mask:0xf bank_mask:0xf
	v_xor_b32_e32 v112, 16, v163
	v_add_u32_e32 v115, 64, v114
	v_fmac_f32_e32 v123, v122, v122
	v_cmp_lt_i32_e32 vcc, v112, v115
	v_add_f32_e32 v116, v123, v116
	v_add_f32_e32 v113, v116, v113
	v_cndmask_b32_e32 v112, v163, v112, vcc
	v_lshlrev_b32_e32 v114, 2, v112
	v_mov_b32_e32 v112, v113
	s_nop 1
	v_permlane16_swap_b32_e32 v112, v113
	v_cndmask_b32_e64 v118, v153, v167, s[0:1]
	v_cndmask_b32_e64 v117, v183, v164, s[0:1]
	v_cndmask_b32_e64 v119, v120, v166, s[0:1]
	v_mov_b32_dpp v182, v118 quad_perm:[1,0,3,2] row_mask:0xf bank_mask:0xf
	s_waitcnt lgkmcnt(0)
	v_add_f32_e32 v112, v113, v112
	v_xor_b32_e32 v113, 32, v163
	v_cmp_lt_i32_e32 vcc, v113, v115
	v_cndmask_b32_e64 v116, v182, v153, s[0:1]
	v_cndmask_b32_e64 v118, v184, v165, s[0:1]
	v_cndmask_b32_e32 v113, v163, v113, vcc
	v_lshlrev_b32_e32 v115, 2, v113
	v_mov_b32_e32 v113, v112
	s_nop 1
	v_permlane32_swap_b32_e32 v113, v112
	global_store_dwordx4 v[172:173], v[116:119], off
	s_nop 1
	v_cndmask_b32_e64 v116, v167, v182, s[0:1]
	v_cndmask_b32_e64 v117, v168, v183, s[0:1]
	v_cndmask_b32_e64 v118, v169, v184, s[0:1]
	v_cndmask_b32_e64 v119, v170, v120, s[0:1]
	global_store_dwordx4 v[154:155], v[116:119], off
	s_and_saveexec_b64 s[22:23], s[2:3]
	s_cbranch_execz .LBB0_1255
	v_ashrrev_i32_e32 v153, 31, v152
	v_lshl_add_u64 v[116:117], v[152:153], 2, s[12:13]
	s_waitcnt lgkmcnt(0)
	v_add_f32_e32 v112, v112, v113
	global_atomic_add_f32 v[116:117], v112, off
; __device__ __forceinline__ unsigned cvt_pk_bf16(float lo, float hi) { unsigned r; asm volatile("v_cvt_pk_bf16_f32 %0, %1, %2" : "=v"(r) : "v"(lo), "v"(hi)); return r; }
; __device__ __forceinline__ unsigned dpp_xor1(unsigned v) { return (unsigned)__builtin_amdgcn_update_dpp(0, (int)v, 0xB1, 0xf, 0xf, false); }
;     __device__ __forceinline__ void operator()(const f32x4 (&acc)[2][2][4][2], const Unit& u, int wr, int wc, int fr, int fq) const {
;         if constexpr (ALLBF) {
;             const int row0 = u.pm * BM + wr * 64 + fr, col0 = u.pn * BM + wc * 64 + 16 * fq; const bool odd = (fr & 1) != 0;
; #pragma unroll
;             for (int ai = 0; ai < 2; ++ai)
; #pragma unroll
;                 for (int m = 0; m < 4; ++m) {
;                     const int row = row0 + ai * HALF + m * 16; float s = 0.f;
;                     const bf16_t* pa = baseb + (size_t)(row - (odd ? 1 : 0)) * DM + col0 + (odd ? 8 : 0);
;                     const u32x4 la = *(const u32x4*)pa, lb = *(const u32x4*)(pa + DM);
;                     const u32x4 snd = odd ? la : lb; u32x4 rcv;
;                     rcv.x = dpp_xor1(snd.x); rcv.y = dpp_xor1(snd.y); rcv.z = dpp_xor1(snd.z); rcv.w = dpp_xor1(snd.w);
;                     const u32x4 bw0 = odd ? rcv : la, bw1 = odd ? lb : rcv;
;                     u32x4 pw[2];
; #pragma unroll
;                     for (int bj = 0; bj < 2; ++bj) { const u32x4 bw = bj ? bw1 : bw0;
;                         const f32x4 b0 = (f32x4){bf_lo(bw.x), bf_hi(bw.x), bf_lo(bw.y), bf_hi(bw.y)}, b1 = (f32x4){bf_lo(bw.z), bf_hi(bw.z), bf_lo(bw.w), bf_hi(bw.w)};
;                         const f32x4 v0 = acc[ai][bj][m][0] + b0, v1 = acc[ai][bj][m][1] + b1;
;                         pw[bj].x = cvt_pk_bf16(v0[0], v0[1]); pw[bj].y = cvt_pk_bf16(v0[2], v0[3]); pw[bj].z = cvt_pk_bf16(v1[0], v1[1]); pw[bj].w = cvt_pk_bf16(v1[2], v1[3]);
;                         s += (v0[0] * v0[0] + v0[1] * v0[1]) + (v0[2] * v0[2] + v0[3] * v0[3]) + (v1[0] * v1[0] + v1[1] * v1[1]) + (v1[2] * v1[2] + v1[3] * v1[3]); }
;                     store_pair_rows(HB, (size_t)DM, row, col0, fr, pw[0], pw[1]);
;                     s += __shfl_xor(s, 16); s += __shfl_xor(s, 32);
;                     if (fq == 0) unsafeAtomicAdd(ssn + row, s);
;                 }
.LBB0_1255:
	s_or_b64 exec, exec, s[22:23]
	v_or_b32_e32 v112, 16, v152
	v_sub_u32_e32 v116, v112, v158
	v_ashrrev_i32_e32 v117, 31, v116
	v_readlane_b32 s22, v254, 25
	v_lshlrev_b64 v[116:117], 12, v[116:117]
	v_readlane_b32 s23, v254, 26
	s_waitcnt lgkmcnt(0)
	v_mov_b32_e32 v113, v141
	v_mov_b32_e32 v153, v141
	v_lshl_add_u64 v[116:117], s[22:23], 0, v[116:117]
	v_lshl_add_u64 v[116:117], v[150:151], 1, v[116:117]
	v_lshl_add_u64 v[124:125], v[116:117], 0, v[140:141]
	v_add_co_u32_e32 v126, vcc, 0x1000, v124
	v_mov_b32_e32 v154, v141
	s_nop 0
	v_addc_co_u32_e32 v127, vcc, 0, v125, vcc
	global_load_dwordx4 v[116:119], v[124:125], off
	global_load_dwordx4 v[120:123], v[126:127], off
	v_mov_b32_e32 v155, v141
	v_mov_b32_e32 v172, v141
	v_mov_b32_e32 v171, v141
	v_mov_b32_e32 v170, v141
	v_mov_b32_e32 v173, v141
	s_waitcnt vmcnt(0)
	v_cndmask_b32_e64 v164, v119, v123, s[0:1]
	v_cndmask_b32_e64 v165, v118, v122, s[0:1]
	v_cndmask_b32_e64 v166, v117, v121, s[0:1]
	v_cndmask_b32_e64 v167, v116, v120, s[0:1]
	v_mov_b32_dpp v154, v165 quad_perm:[1,0,3,2] row_mask:0xf bank_mask:0xf
	v_mov_b32_dpp v153, v166 quad_perm:[1,0,3,2] row_mask:0xf bank_mask:0xf
	v_mov_b32_dpp v113, v167 quad_perm:[1,0,3,2] row_mask:0xf bank_mask:0xf
	v_mov_b32_dpp v155, v164 quad_perm:[1,0,3,2] row_mask:0xf bank_mask:0xf
	v_cndmask_b32_e64 v164, v155, v119, s[0:1]
	v_cndmask_b32_e64 v165, v154, v118, s[0:1]
	v_cndmask_b32_e64 v119, v153, v117, s[0:1]
	v_cndmask_b32_e64 v117, v113, v116, s[0:1]
	v_cndmask_b32_e64 v153, v121, v153, s[0:1]
	v_cndmask_b32_e64 v113, v120, v113, s[0:1]
	v_cndmask_b32_e64 v169, v123, v155, s[0:1]
	v_cndmask_b32_e64 v167, v122, v154, s[0:1]
	v_lshlrev_b32_e32 v116, 16, v117
	v_and_b32_e32 v117, 0xffff0000, v117
	v_lshlrev_b32_e32 v118, 16, v119
	v_and_b32_e32 v119, 0xffff0000, v119
	v_lshlrev_b32_e32 v120, 16, v165
	v_and_b32_e32 v121, 0xffff0000, v165
	v_lshlrev_b32_e32 v122, 16, v164
	v_and_b32_e32 v123, 0xffff0000, v164
	v_lshlrev_b32_e32 v154, 16, v113
	v_and_b32_e32 v155, 0xffff0000, v113
	v_lshlrev_b32_e32 v164, 16, v153
	v_and_b32_e32 v165, 0xffff0000, v153
	v_lshlrev_b32_e32 v166, 16, v167
	v_and_b32_e32 v167, 0xffff0000, v167
	v_lshlrev_b32_e32 v168, 16, v169
	v_and_b32_e32 v169, 0xffff0000, v169
	v_pk_add_f32 v[110:111], v[110:111], v[118:119]
	v_pk_add_f32 v[108:109], v[108:109], v[116:117]
	v_pk_add_f32 v[102:103], v[102:103], v[164:165]
	v_pk_add_f32 v[100:101], v[100:101], v[154:155]
	v_pk_add_f32 v[106:107], v[106:107], v[122:123]
	v_pk_add_f32 v[104:105], v[104:105], v[120:121]
	v_pk_add_f32 v[98:99], v[98:99], v[168:169]
	v_pk_add_f32 v[96:97], v[96:97], v[166:167]
	v_cvt_pk_bf16_f32 v113, v108, v109
	v_cvt_pk_bf16_f32 v116, v110, v111
	v_cvt_pk_bf16_f32 v117, v104, v105
	v_cvt_pk_bf16_f32 v118, v106, v107
	v_mul_f32_e32 v109, v109, v109
	v_mul_f32_e32 v111, v111, v111
	v_cvt_pk_bf16_f32 v119, v100, v101
	v_cvt_pk_bf16_f32 v120, v102, v103
	v_mul_f32_e32 v101, v101, v101
	v_mul_f32_e32 v103, v103, v103
	v_mul_f32_e32 v105, v105, v105
	v_cvt_pk_bf16_f32 v121, v96, v97
	v_cvt_pk_bf16_f32 v122, v98, v99
	v_mul_f32_e32 v97, v97, v97
	v_mul_f32_e32 v99, v99, v99
	v_fmac_f32_e32 v109, v108, v108
	v_fmac_f32_e32 v111, v110, v110
	v_fmac_f32_e32 v101, v100, v100
	v_fmac_f32_e32 v103, v102, v102
	v_mul_f32_e32 v107, v107, v107
	v_fmac_f32_e32 v105, v104, v104
	v_fmac_f32_e32 v97, v96, v96
	v_fmac_f32_e32 v99, v98, v98
	v_cndmask_b32_e64 v98, v117, v121, s[0:1]
	v_add_f32_e32 v104, v109, v111
	v_add_f32_e32 v101, v101, v103
	v_fmac_f32_e32 v107, v106, v106
	v_mov_b32_dpp v172, v98 quad_perm:[1,0,3,2] row_mask:0xf bank_mask:0xf
	v_add_f32_e32 v98, v105, v104
	v_add_f32_e32 v97, v97, v101
	v_cndmask_b32_e64 v100, v116, v120, s[0:1]
	v_add_f32_e32 v98, v107, v98
	v_add_f32_e32 v97, v99, v97
	v_mov_b32_dpp v171, v100 quad_perm:[1,0,3,2] row_mask:0xf bank_mask:0xf
	v_add_f32_e32 v100, v98, v97
	v_mov_b32_e32 v101, v100
	s_nop 1
	v_permlane16_swap_b32_e32 v101, v100
	v_cndmask_b32_e64 v96, v118, v122, s[0:1]
	v_cndmask_b32_e64 v102, v113, v119, s[0:1]
	v_cndmask_b32_e64 v97, v171, v116, s[0:1]
	v_mov_b32_dpp v173, v96 quad_perm:[1,0,3,2] row_mask:0xf bank_mask:0xf
	v_mov_b32_dpp v170, v102 quad_perm:[1,0,3,2] row_mask:0xf bank_mask:0xf
	v_cndmask_b32_e64 v96, v170, v113, s[0:1]
	v_cndmask_b32_e64 v98, v172, v117, s[0:1]
	v_cndmask_b32_e64 v99, v173, v118, s[0:1]
	global_store_dwordx4 v[124:125], v[96:99], off
	s_waitcnt lgkmcnt(0)
	s_nop 0
	v_add_f32_e32 v96, v100, v101
	v_mov_b32_e32 v97, v96
	s_nop 1
	v_permlane32_swap_b32_e32 v97, v96
	v_cndmask_b32_e64 v98, v119, v170, s[0:1]
	v_cndmask_b32_e64 v99, v120, v171, s[0:1]
	v_cndmask_b32_e64 v100, v121, v172, s[0:1]
	v_cndmask_b32_e64 v101, v122, v173, s[0:1]
	global_store_dwordx4 v[126:127], v[98:101], off
	s_and_saveexec_b64 s[22:23], s[2:3]
	s_cbranch_execz .LBB0_1257
	v_ashrrev_i32_e32 v113, 31, v112
	v_lshl_add_u64 v[98:99], v[112:113], 2, s[12:13]
	s_waitcnt lgkmcnt(0)
	v_add_f32_e32 v96, v96, v97
	global_atomic_add_f32 v[98:99], v96, off
; __device__ __forceinline__ unsigned cvt_pk_bf16(float lo, float hi) { unsigned r; asm volatile("v_cvt_pk_bf16_f32 %0, %1, %2" : "=v"(r) : "v"(lo), "v"(hi)); return r; }
; __device__ __forceinline__ unsigned dpp_xor1(unsigned v) { return (unsigned)__builtin_amdgcn_update_dpp(0, (int)v, 0xB1, 0xf, 0xf, false); }
;     __device__ __forceinline__ void operator()(const f32x4 (&acc)[2][2][4][2], const Unit& u, int wr, int wc, int fr, int fq) const {
;         if constexpr (ALLBF) {
;             const int row0 = u.pm * BM + wr * 64 + fr, col0 = u.pn * BM + wc * 64 + 16 * fq; const bool odd = (fr & 1) != 0;
; #pragma unroll
;             for (int ai = 0; ai < 2; ++ai)
; #pragma unroll
;                 for (int m = 0; m < 4; ++m) {
;                     const int row = row0 + ai * HALF + m * 16; float s = 0.f;
;                     const bf16_t* pa = baseb + (size_t)(row - (odd ? 1 : 0)) * DM + col0 + (odd ? 8 : 0);
;                     const u32x4 la = *(const u32x4*)pa, lb = *(const u32x4*)(pa + DM);
;                     const u32x4 snd = odd ? la : lb; u32x4 rcv;
;                     rcv.x = dpp_xor1(snd.x); rcv.y = dpp_xor1(snd.y); rcv.z = dpp_xor1(snd.z); rcv.w = dpp_xor1(snd.w);
;                     const u32x4 bw0 = odd ? rcv : la, bw1 = odd ? lb : rcv;
;                     u32x4 pw[2];
; #pragma unroll
;                     for (int bj = 0; bj < 2; ++bj) { const u32x4 bw = bj ? bw1 : bw0;
;                         const f32x4 b0 = (f32x4){bf_lo(bw.x), bf_hi(bw.x), bf_lo(bw.y), bf_hi(bw.y)}, b1 = (f32x4){bf_lo(bw.z), bf_hi(bw.z), bf_lo(bw.w), bf_hi(bw.w)};
;                         const f32x4 v0 = acc[ai][bj][m][0] + b0, v1 = acc[ai][bj][m][1] + b1;
;                         pw[bj].x = cvt_pk_bf16(v0[0], v0[1]); pw[bj].y = cvt_pk_bf16(v0[2], v0[3]); pw[bj].z = cvt_pk_bf16(v1[0], v1[1]); pw[bj].w = cvt_pk_bf16(v1[2], v1[3]);
;                         s += (v0[0] * v0[0] + v0[1] * v0[1]) + (v0[2] * v0[2] + v0[3] * v0[3]) + (v1[0] * v1[0] + v1[1] * v1[1]) + (v1[2] * v1[2] + v1[3] * v1[3]); }
;                     store_pair_rows(HB, (size_t)DM, row, col0, fr, pw[0], pw[1]);
;                     s += __shfl_xor(s, 16); s += __shfl_xor(s, 32);
;                     if (fq == 0) unsafeAtomicAdd(ssn + row, s);
;                 }
.LBB0_1257:
	s_or_b64 exec, exec, s[22:23]
	v_or_b32_e32 v96, 32, v152
	v_sub_u32_e32 v98, v96, v158
	v_ashrrev_i32_e32 v99, 31, v98
	v_readlane_b32 s22, v254, 25
	v_lshlrev_b64 v[98:99], 12, v[98:99]
	v_readlane_b32 s23, v254, 26
	s_waitcnt lgkmcnt(0)
	v_mov_b32_e32 v97, v141
	v_mov_b32_e32 v110, v141
	v_lshl_add_u64 v[98:99], s[22:23], 0, v[98:99]
	v_lshl_add_u64 v[98:99], v[150:151], 1, v[98:99]
	v_lshl_add_u64 v[106:107], v[98:99], 0, v[140:141]
	v_add_co_u32_e32 v108, vcc, 0x1000, v106
	v_mov_b32_e32 v112, v141
	s_nop 0
	v_addc_co_u32_e32 v109, vcc, 0, v107, vcc
	global_load_dwordx4 v[98:101], v[106:107], off
	global_load_dwordx4 v[102:105], v[108:109], off
	v_mov_b32_e32 v111, v141
	v_mov_b32_e32 v122, v141
	v_mov_b32_e32 v121, v141
	v_mov_b32_e32 v120, v141
	v_mov_b32_e32 v123, v141
	s_waitcnt vmcnt(0)
	v_cndmask_b32_e64 v113, v101, v105, s[0:1]
	v_cndmask_b32_e64 v117, v99, v103, s[0:1]
	v_cndmask_b32_e64 v118, v98, v102, s[0:1]
	v_cndmask_b32_e64 v116, v100, v104, s[0:1]
	v_mov_b32_dpp v110, v117 quad_perm:[1,0,3,2] row_mask:0xf bank_mask:0xf
	v_mov_b32_dpp v97, v118 quad_perm:[1,0,3,2] row_mask:0xf bank_mask:0xf
	v_mov_b32_dpp v112, v113 quad_perm:[1,0,3,2] row_mask:0xf bank_mask:0xf
	v_mov_b32_dpp v111, v116 quad_perm:[1,0,3,2] row_mask:0xf bank_mask:0xf
	v_cndmask_b32_e64 v113, v112, v101, s[0:1]
	v_cndmask_b32_e64 v101, v110, v99, s[0:1]
	v_cndmask_b32_e64 v99, v97, v98, s[0:1]
	v_cndmask_b32_e64 v118, v103, v110, s[0:1]
	v_cndmask_b32_e64 v97, v102, v97, s[0:1]
	v_cndmask_b32_e64 v116, v111, v100, s[0:1]
	v_cndmask_b32_e64 v119, v105, v112, s[0:1]
	v_cndmask_b32_e64 v117, v104, v111, s[0:1]
	v_lshlrev_b32_e32 v98, 16, v99
	v_and_b32_e32 v99, 0xffff0000, v99
	v_lshlrev_b32_e32 v100, 16, v101
	v_and_b32_e32 v101, 0xffff0000, v101
	v_lshlrev_b32_e32 v104, 16, v113
	v_and_b32_e32 v105, 0xffff0000, v113
	v_lshlrev_b32_e32 v110, 16, v97
	v_and_b32_e32 v111, 0xffff0000, v97
	v_lshlrev_b32_e32 v112, 16, v118
	v_and_b32_e32 v113, 0xffff0000, v118
	v_lshlrev_b32_e32 v102, 16, v116
	v_and_b32_e32 v103, 0xffff0000, v116
	v_lshlrev_b32_e32 v116, 16, v117
	v_and_b32_e32 v117, 0xffff0000, v117
	v_lshlrev_b32_e32 v118, 16, v119
	v_and_b32_e32 v119, 0xffff0000, v119
	v_pk_add_f32 v[94:95], v[94:95], v[100:101]
	v_pk_add_f32 v[92:93], v[92:93], v[98:99]
	v_pk_add_f32 v[86:87], v[86:87], v[112:113]
	v_pk_add_f32 v[84:85], v[84:85], v[110:111]
	v_pk_add_f32 v[90:91], v[90:91], v[104:105]
	v_pk_add_f32 v[88:89], v[88:89], v[102:103]
	v_pk_add_f32 v[82:83], v[82:83], v[118:119]
	v_pk_add_f32 v[80:81], v[80:81], v[116:117]
	v_cvt_pk_bf16_f32 v97, v92, v93
	v_cvt_pk_bf16_f32 v98, v94, v95
	v_cvt_pk_bf16_f32 v99, v88, v89
	v_cvt_pk_bf16_f32 v100, v90, v91
	v_mul_f32_e32 v93, v93, v93
	v_mul_f32_e32 v95, v95, v95
	v_cvt_pk_bf16_f32 v101, v84, v85
	v_cvt_pk_bf16_f32 v102, v86, v87
	v_mul_f32_e32 v85, v85, v85
	v_mul_f32_e32 v87, v87, v87
	v_mul_f32_e32 v89, v89, v89
	v_cvt_pk_bf16_f32 v103, v80, v81
	v_cvt_pk_bf16_f32 v104, v82, v83
	v_mul_f32_e32 v81, v81, v81
	v_mul_f32_e32 v83, v83, v83
	v_fmac_f32_e32 v93, v92, v92
	v_fmac_f32_e32 v95, v94, v94
	v_fmac_f32_e32 v85, v84, v84
	v_fmac_f32_e32 v87, v86, v86
	v_mul_f32_e32 v91, v91, v91
	v_fmac_f32_e32 v89, v88, v88
	v_fmac_f32_e32 v81, v80, v80
	v_fmac_f32_e32 v83, v82, v82
	v_cndmask_b32_e64 v82, v99, v103, s[0:1]
	v_add_f32_e32 v88, v93, v95
	v_add_f32_e32 v85, v85, v87
	v_fmac_f32_e32 v91, v90, v90
	v_mov_b32_dpp v122, v82 quad_perm:[1,0,3,2] row_mask:0xf bank_mask:0xf
	v_add_f32_e32 v82, v89, v88
	v_add_f32_e32 v81, v81, v85
	v_cndmask_b32_e64 v84, v98, v102, s[0:1]
	v_add_f32_e32 v82, v91, v82
	v_add_f32_e32 v81, v83, v81
	v_mov_b32_dpp v121, v84 quad_perm:[1,0,3,2] row_mask:0xf bank_mask:0xf
	v_add_f32_e32 v84, v82, v81
	v_mov_b32_e32 v85, v84
	s_nop 1
	v_permlane16_swap_b32_e32 v85, v84
	v_cndmask_b32_e64 v80, v100, v104, s[0:1]
	v_cndmask_b32_e64 v86, v97, v101, s[0:1]
	v_cndmask_b32_e64 v81, v121, v98, s[0:1]
	v_mov_b32_dpp v123, v80 quad_perm:[1,0,3,2] row_mask:0xf bank_mask:0xf
	v_mov_b32_dpp v120, v86 quad_perm:[1,0,3,2] row_mask:0xf bank_mask:0xf
	v_cndmask_b32_e64 v80, v120, v97, s[0:1]
	v_cndmask_b32_e64 v82, v122, v99, s[0:1]
	v_cndmask_b32_e64 v83, v123, v100, s[0:1]
	global_store_dwordx4 v[106:107], v[80:83], off
	s_waitcnt lgkmcnt(0)
	s_nop 0
	v_add_f32_e32 v80, v84, v85
	v_mov_b32_e32 v81, v80
	s_nop 1
	v_permlane32_swap_b32_e32 v81, v80
	v_cndmask_b32_e64 v82, v101, v120, s[0:1]
	v_cndmask_b32_e64 v83, v102, v121, s[0:1]
	v_cndmask_b32_e64 v84, v103, v122, s[0:1]
	v_cndmask_b32_e64 v85, v104, v123, s[0:1]
	global_store_dwordx4 v[108:109], v[82:85], off
	s_and_saveexec_b64 s[22:23], s[2:3]
	s_cbranch_execz .LBB0_1259
	v_ashrrev_i32_e32 v97, 31, v96
	v_lshl_add_u64 v[82:83], v[96:97], 2, s[12:13]
	s_waitcnt lgkmcnt(0)
	v_add_f32_e32 v80, v80, v81
	global_atomic_add_f32 v[82:83], v80, off
; __device__ __forceinline__ unsigned cvt_pk_bf16(float lo, float hi) { unsigned r; asm volatile("v_cvt_pk_bf16_f32 %0, %1, %2" : "=v"(r) : "v"(lo), "v"(hi)); return r; }
; __device__ __forceinline__ unsigned dpp_xor1(unsigned v) { return (unsigned)__builtin_amdgcn_update_dpp(0, (int)v, 0xB1, 0xf, 0xf, false); }
;     __device__ __forceinline__ void operator()(const f32x4 (&acc)[2][2][4][2], const Unit& u, int wr, int wc, int fr, int fq) const {
;         if constexpr (ALLBF) {
;             const int row0 = u.pm * BM + wr * 64 + fr, col0 = u.pn * BM + wc * 64 + 16 * fq; const bool odd = (fr & 1) != 0;
; #pragma unroll
;             for (int ai = 0; ai < 2; ++ai)
; #pragma unroll
;                 for (int m = 0; m < 4; ++m) {
;                     const int row = row0 + ai * HALF + m * 16; float s = 0.f;
;                     const bf16_t* pa = baseb + (size_t)(row - (odd ? 1 : 0)) * DM + col0 + (odd ? 8 : 0);
;                     const u32x4 la = *(const u32x4*)pa, lb = *(const u32x4*)(pa + DM);
;                     const u32x4 snd = odd ? la : lb; u32x4 rcv;
;                     rcv.x = dpp_xor1(snd.x); rcv.y = dpp_xor1(snd.y); rcv.z = dpp_xor1(snd.z); rcv.w = dpp_xor1(snd.w);
;                     const u32x4 bw0 = odd ? rcv : la, bw1 = odd ? lb : rcv;
;                     u32x4 pw[2];
; #pragma unroll
;                     for (int bj = 0; bj < 2; ++bj) { const u32x4 bw = bj ? bw1 : bw0;
;                         const f32x4 b0 = (f32x4){bf_lo(bw.x), bf_hi(bw.x), bf_lo(bw.y), bf_hi(bw.y)}, b1 = (f32x4){bf_lo(bw.z), bf_hi(bw.z), bf_lo(bw.w), bf_hi(bw.w)};
;                         const f32x4 v0 = acc[ai][bj][m][0] + b0, v1 = acc[ai][bj][m][1] + b1;
;                         pw[bj].x = cvt_pk_bf16(v0[0], v0[1]); pw[bj].y = cvt_pk_bf16(v0[2], v0[3]); pw[bj].z = cvt_pk_bf16(v1[0], v1[1]); pw[bj].w = cvt_pk_bf16(v1[2], v1[3]);
;                         s += (v0[0] * v0[0] + v0[1] * v0[1]) + (v0[2] * v0[2] + v0[3] * v0[3]) + (v1[0] * v1[0] + v1[1] * v1[1]) + (v1[2] * v1[2] + v1[3] * v1[3]); }
;                     store_pair_rows(HB, (size_t)DM, row, col0, fr, pw[0], pw[1]);
;                     s += __shfl_xor(s, 16); s += __shfl_xor(s, 32);
;                     if (fq == 0) unsafeAtomicAdd(ssn + row, s);
;                 }
.LBB0_1259:
	s_or_b64 exec, exec, s[22:23]
	v_or_b32_e32 v80, 48, v152
	v_sub_u32_e32 v82, v80, v158
	v_ashrrev_i32_e32 v83, 31, v82
	v_readlane_b32 s22, v254, 25
	v_lshlrev_b64 v[82:83], 12, v[82:83]
	v_readlane_b32 s23, v254, 26
	s_waitcnt lgkmcnt(0)
	v_mov_b32_e32 v81, v141
	v_mov_b32_e32 v94, v141
	v_lshl_add_u64 v[82:83], s[22:23], 0, v[82:83]
	v_lshl_add_u64 v[82:83], v[150:151], 1, v[82:83]
	v_lshl_add_u64 v[90:91], v[82:83], 0, v[140:141]
	v_add_co_u32_e32 v92, vcc, 0x1000, v90
	v_mov_b32_e32 v96, v141
	s_nop 0
	v_addc_co_u32_e32 v93, vcc, 0, v91, vcc
	global_load_dwordx4 v[82:85], v[90:91], off
	global_load_dwordx4 v[86:89], v[92:93], off
	v_mov_b32_e32 v95, v141
	v_mov_b32_e32 v104, v141
	v_mov_b32_e32 v103, v141
	v_mov_b32_e32 v102, v141
	v_mov_b32_e32 v105, v141
	s_waitcnt vmcnt(0)
	v_cndmask_b32_e64 v97, v85, v89, s[0:1]
	v_cndmask_b32_e64 v99, v83, v87, s[0:1]
	v_cndmask_b32_e64 v100, v82, v86, s[0:1]
	v_cndmask_b32_e64 v98, v84, v88, s[0:1]
	v_mov_b32_dpp v94, v99 quad_perm:[1,0,3,2] row_mask:0xf bank_mask:0xf
	v_mov_b32_dpp v81, v100 quad_perm:[1,0,3,2] row_mask:0xf bank_mask:0xf
	v_mov_b32_dpp v96, v97 quad_perm:[1,0,3,2] row_mask:0xf bank_mask:0xf
	v_mov_b32_dpp v95, v98 quad_perm:[1,0,3,2] row_mask:0xf bank_mask:0xf
	v_cndmask_b32_e64 v97, v96, v85, s[0:1]
	v_cndmask_b32_e64 v85, v94, v83, s[0:1]
	v_cndmask_b32_e64 v83, v81, v82, s[0:1]
	v_cndmask_b32_e64 v100, v87, v94, s[0:1]
	v_cndmask_b32_e64 v81, v86, v81, s[0:1]
	v_cndmask_b32_e64 v98, v95, v84, s[0:1]
	v_cndmask_b32_e64 v101, v89, v96, s[0:1]
	v_cndmask_b32_e64 v99, v88, v95, s[0:1]
	v_lshlrev_b32_e32 v82, 16, v83
	v_and_b32_e32 v83, 0xffff0000, v83
	v_lshlrev_b32_e32 v84, 16, v85
	v_and_b32_e32 v85, 0xffff0000, v85
	v_lshlrev_b32_e32 v88, 16, v97
	v_and_b32_e32 v89, 0xffff0000, v97
	v_lshlrev_b32_e32 v94, 16, v81
	v_and_b32_e32 v95, 0xffff0000, v81
	v_lshlrev_b32_e32 v96, 16, v100
	v_and_b32_e32 v97, 0xffff0000, v100
	v_lshlrev_b32_e32 v86, 16, v98
	v_and_b32_e32 v87, 0xffff0000, v98
	v_lshlrev_b32_e32 v98, 16, v99
	v_and_b32_e32 v99, 0xffff0000, v99
	v_lshlrev_b32_e32 v100, 16, v101
	v_and_b32_e32 v101, 0xffff0000, v101
	v_pk_add_f32 v[78:79], v[78:79], v[84:85]
	v_pk_add_f32 v[76:77], v[76:77], v[82:83]
	v_pk_add_f32 v[70:71], v[70:71], v[96:97]
	v_pk_add_f32 v[68:69], v[68:69], v[94:95]
	v_pk_add_f32 v[74:75], v[74:75], v[88:89]
	v_pk_add_f32 v[72:73], v[72:73], v[86:87]
	v_pk_add_f32 v[66:67], v[66:67], v[100:101]
	v_pk_add_f32 v[64:65], v[64:65], v[98:99]
	v_cvt_pk_bf16_f32 v81, v76, v77
	v_cvt_pk_bf16_f32 v82, v78, v79
	v_cvt_pk_bf16_f32 v83, v72, v73
	v_cvt_pk_bf16_f32 v84, v74, v75
	v_mul_f32_e32 v77, v77, v77
	v_mul_f32_e32 v79, v79, v79
	v_cvt_pk_bf16_f32 v85, v68, v69
	v_cvt_pk_bf16_f32 v86, v70, v71
	v_mul_f32_e32 v69, v69, v69
	v_mul_f32_e32 v71, v71, v71
	v_mul_f32_e32 v73, v73, v73
	v_cvt_pk_bf16_f32 v87, v64, v65
	v_cvt_pk_bf16_f32 v88, v66, v67
	v_mul_f32_e32 v65, v65, v65
	v_mul_f32_e32 v67, v67, v67
	v_fmac_f32_e32 v77, v76, v76
	v_fmac_f32_e32 v79, v78, v78
	v_fmac_f32_e32 v69, v68, v68
	v_fmac_f32_e32 v71, v70, v70
	v_mul_f32_e32 v75, v75, v75
	v_fmac_f32_e32 v73, v72, v72
	v_fmac_f32_e32 v65, v64, v64
	v_fmac_f32_e32 v67, v66, v66
	v_cndmask_b32_e64 v66, v83, v87, s[0:1]
	v_add_f32_e32 v72, v77, v79
	v_add_f32_e32 v69, v69, v71
	v_fmac_f32_e32 v75, v74, v74
	v_mov_b32_dpp v104, v66 quad_perm:[1,0,3,2] row_mask:0xf bank_mask:0xf
	v_add_f32_e32 v66, v73, v72
	v_add_f32_e32 v65, v65, v69
	v_cndmask_b32_e64 v68, v82, v86, s[0:1]
	v_add_f32_e32 v66, v75, v66
	v_add_f32_e32 v65, v67, v65
	v_mov_b32_dpp v103, v68 quad_perm:[1,0,3,2] row_mask:0xf bank_mask:0xf
	v_add_f32_e32 v68, v66, v65
	v_mov_b32_e32 v69, v68
	s_nop 1
	v_permlane16_swap_b32_e32 v69, v68
	v_cndmask_b32_e64 v64, v84, v88, s[0:1]
	v_cndmask_b32_e64 v70, v81, v85, s[0:1]
	v_cndmask_b32_e64 v65, v103, v82, s[0:1]
	v_mov_b32_dpp v105, v64 quad_perm:[1,0,3,2] row_mask:0xf bank_mask:0xf
	v_mov_b32_dpp v102, v70 quad_perm:[1,0,3,2] row_mask:0xf bank_mask:0xf
	v_cndmask_b32_e64 v64, v102, v81, s[0:1]
	v_cndmask_b32_e64 v66, v104, v83, s[0:1]
	v_cndmask_b32_e64 v67, v105, v84, s[0:1]
	global_store_dwordx4 v[90:91], v[64:67], off
	s_waitcnt lgkmcnt(0)
	s_nop 0
	v_add_f32_e32 v64, v68, v69
	v_mov_b32_e32 v65, v64
	s_nop 1
	v_permlane32_swap_b32_e32 v65, v64
	v_cndmask_b32_e64 v66, v85, v102, s[0:1]
	v_cndmask_b32_e64 v67, v86, v103, s[0:1]
	v_cndmask_b32_e64 v68, v87, v104, s[0:1]
	v_cndmask_b32_e64 v69, v88, v105, s[0:1]
	global_store_dwordx4 v[92:93], v[66:69], off
	s_and_saveexec_b64 s[22:23], s[2:3]
	s_cbranch_execz .LBB0_1261
	v_ashrrev_i32_e32 v81, 31, v80
	v_lshl_add_u64 v[66:67], v[80:81], 2, s[12:13]
	s_waitcnt lgkmcnt(0)
	v_add_f32_e32 v64, v64, v65
	global_atomic_add_f32 v[66:67], v64, off
; __device__ __forceinline__ unsigned cvt_pk_bf16(float lo, float hi) { unsigned r; asm volatile("v_cvt_pk_bf16_f32 %0, %1, %2" : "=v"(r) : "v"(lo), "v"(hi)); return r; }
; __device__ __forceinline__ unsigned dpp_xor1(unsigned v) { return (unsigned)__builtin_amdgcn_update_dpp(0, (int)v, 0xB1, 0xf, 0xf, false); }
;     __device__ __forceinline__ void operator()(const f32x4 (&acc)[2][2][4][2], const Unit& u, int wr, int wc, int fr, int fq) const {
;         if constexpr (ALLBF) {
;             const int row0 = u.pm * BM + wr * 64 + fr, col0 = u.pn * BM + wc * 64 + 16 * fq; const bool odd = (fr & 1) != 0;
; #pragma unroll
;             for (int ai = 0; ai < 2; ++ai)
; #pragma unroll
;                 for (int m = 0; m < 4; ++m) {
;                     const int row = row0 + ai * HALF + m * 16; float s = 0.f;
;                     const bf16_t* pa = baseb + (size_t)(row - (odd ? 1 : 0)) * DM + col0 + (odd ? 8 : 0);
;                     const u32x4 la = *(const u32x4*)pa, lb = *(const u32x4*)(pa + DM);
;                     const u32x4 snd = odd ? la : lb; u32x4 rcv;
;                     rcv.x = dpp_xor1(snd.x); rcv.y = dpp_xor1(snd.y); rcv.z = dpp_xor1(snd.z); rcv.w = dpp_xor1(snd.w);
;                     const u32x4 bw0 = odd ? rcv : la, bw1 = odd ? lb : rcv;
;                     u32x4 pw[2];
; #pragma unroll
;                     for (int bj = 0; bj < 2; ++bj) { const u32x4 bw = bj ? bw1 : bw0;
;                         const f32x4 b0 = (f32x4){bf_lo(bw.x), bf_hi(bw.x), bf_lo(bw.y), bf_hi(bw.y)}, b1 = (f32x4){bf_lo(bw.z), bf_hi(bw.z), bf_lo(bw.w), bf_hi(bw.w)};
;                         const f32x4 v0 = acc[ai][bj][m][0] + b0, v1 = acc[ai][bj][m][1] + b1;
;                         pw[bj].x = cvt_pk_bf16(v0[0], v0[1]); pw[bj].y = cvt_pk_bf16(v0[2], v0[3]); pw[bj].z = cvt_pk_bf16(v1[0], v1[1]); pw[bj].w = cvt_pk_bf16(v1[2], v1[3]);
;                         s += (v0[0] * v0[0] + v0[1] * v0[1]) + (v0[2] * v0[2] + v0[3] * v0[3]) + (v1[0] * v1[0] + v1[1] * v1[1]) + (v1[2] * v1[2] + v1[3] * v1[3]); }
;                     store_pair_rows(HB, (size_t)DM, row, col0, fr, pw[0], pw[1]);
;                     s += __shfl_xor(s, 16); s += __shfl_xor(s, 32);
;                     if (fq == 0) unsafeAtomicAdd(ssn + row, s);
;                 }
.LBB0_1261:
	s_or_b64 exec, exec, s[22:23]
	v_add_u32_e32 v64, 0x80, v152
	v_sub_u32_e32 v66, v64, v158
	v_ashrrev_i32_e32 v67, 31, v66
	v_readlane_b32 s22, v254, 25
	v_lshlrev_b64 v[66:67], 12, v[66:67]
	v_readlane_b32 s23, v254, 26
	s_waitcnt lgkmcnt(0)
	v_mov_b32_e32 v65, v141
	v_mov_b32_e32 v78, v141
	v_lshl_add_u64 v[66:67], s[22:23], 0, v[66:67]
	v_lshl_add_u64 v[66:67], v[150:151], 1, v[66:67]
	v_lshl_add_u64 v[74:75], v[66:67], 0, v[140:141]
	v_add_co_u32_e32 v76, vcc, 0x1000, v74
	v_mov_b32_e32 v80, v141
	s_nop 0
	v_addc_co_u32_e32 v77, vcc, 0, v75, vcc
	global_load_dwordx4 v[66:69], v[74:75], off
	global_load_dwordx4 v[70:73], v[76:77], off
	v_mov_b32_e32 v79, v141
	v_mov_b32_e32 v88, v141
	v_mov_b32_e32 v87, v141
	v_mov_b32_e32 v86, v141
	v_mov_b32_e32 v89, v141
	s_waitcnt vmcnt(0)
	v_cndmask_b32_e64 v81, v69, v73, s[0:1]
	v_cndmask_b32_e64 v83, v67, v71, s[0:1]
	v_cndmask_b32_e64 v84, v66, v70, s[0:1]
	v_cndmask_b32_e64 v82, v68, v72, s[0:1]
	v_mov_b32_dpp v78, v83 quad_perm:[1,0,3,2] row_mask:0xf bank_mask:0xf
	v_mov_b32_dpp v65, v84 quad_perm:[1,0,3,2] row_mask:0xf bank_mask:0xf
	v_mov_b32_dpp v80, v81 quad_perm:[1,0,3,2] row_mask:0xf bank_mask:0xf
	v_mov_b32_dpp v79, v82 quad_perm:[1,0,3,2] row_mask:0xf bank_mask:0xf
	v_cndmask_b32_e64 v81, v80, v69, s[0:1]
	v_cndmask_b32_e64 v69, v78, v67, s[0:1]
	v_cndmask_b32_e64 v67, v65, v66, s[0:1]
	v_cndmask_b32_e64 v84, v71, v78, s[0:1]
	v_cndmask_b32_e64 v65, v70, v65, s[0:1]
	v_cndmask_b32_e64 v82, v79, v68, s[0:1]
	v_cndmask_b32_e64 v85, v73, v80, s[0:1]
	v_cndmask_b32_e64 v83, v72, v79, s[0:1]
	v_lshlrev_b32_e32 v66, 16, v67
	v_and_b32_e32 v67, 0xffff0000, v67
	v_lshlrev_b32_e32 v68, 16, v69
	v_and_b32_e32 v69, 0xffff0000, v69
	v_lshlrev_b32_e32 v72, 16, v81
	v_and_b32_e32 v73, 0xffff0000, v81
	v_lshlrev_b32_e32 v78, 16, v65
	v_and_b32_e32 v79, 0xffff0000, v65
	v_lshlrev_b32_e32 v80, 16, v84
	v_and_b32_e32 v81, 0xffff0000, v84
	v_lshlrev_b32_e32 v70, 16, v82
	v_and_b32_e32 v71, 0xffff0000, v82
	v_lshlrev_b32_e32 v82, 16, v83
	v_and_b32_e32 v83, 0xffff0000, v83
	v_lshlrev_b32_e32 v84, 16, v85
	v_and_b32_e32 v85, 0xffff0000, v85
	v_pk_add_f32 v[62:63], v[62:63], v[68:69]
	v_pk_add_f32 v[60:61], v[60:61], v[66:67]
	v_pk_add_f32 v[54:55], v[54:55], v[80:81]
	v_pk_add_f32 v[52:53], v[52:53], v[78:79]
	v_pk_add_f32 v[58:59], v[58:59], v[72:73]
	v_pk_add_f32 v[56:57], v[56:57], v[70:71]
	v_pk_add_f32 v[50:51], v[50:51], v[84:85]
	v_pk_add_f32 v[48:49], v[48:49], v[82:83]
	v_cvt_pk_bf16_f32 v65, v60, v61
	v_cvt_pk_bf16_f32 v66, v62, v63
	v_cvt_pk_bf16_f32 v67, v56, v57
	v_cvt_pk_bf16_f32 v68, v58, v59
	v_mul_f32_e32 v61, v61, v61
	v_mul_f32_e32 v63, v63, v63
	v_cvt_pk_bf16_f32 v69, v52, v53
	v_cvt_pk_bf16_f32 v70, v54, v55
	v_mul_f32_e32 v53, v53, v53
	v_mul_f32_e32 v55, v55, v55
	v_mul_f32_e32 v57, v57, v57
	v_cvt_pk_bf16_f32 v71, v48, v49
	v_cvt_pk_bf16_f32 v72, v50, v51
	v_mul_f32_e32 v49, v49, v49
	v_mul_f32_e32 v51, v51, v51
	v_fmac_f32_e32 v61, v60, v60
	v_fmac_f32_e32 v63, v62, v62
	v_fmac_f32_e32 v53, v52, v52
	v_fmac_f32_e32 v55, v54, v54
	v_mul_f32_e32 v59, v59, v59
	v_fmac_f32_e32 v57, v56, v56
	v_fmac_f32_e32 v49, v48, v48
	v_fmac_f32_e32 v51, v50, v50
	v_cndmask_b32_e64 v50, v67, v71, s[0:1]
	v_add_f32_e32 v56, v61, v63
	v_add_f32_e32 v53, v53, v55
	v_fmac_f32_e32 v59, v58, v58
	v_mov_b32_dpp v88, v50 quad_perm:[1,0,3,2] row_mask:0xf bank_mask:0xf
	v_add_f32_e32 v50, v57, v56
	v_add_f32_e32 v49, v49, v53
	v_cndmask_b32_e64 v52, v66, v70, s[0:1]
	v_add_f32_e32 v50, v59, v50
	v_add_f32_e32 v49, v51, v49
	v_mov_b32_dpp v87, v52 quad_perm:[1,0,3,2] row_mask:0xf bank_mask:0xf
	v_add_f32_e32 v52, v50, v49
	v_mov_b32_e32 v53, v52
	s_nop 1
	v_permlane16_swap_b32_e32 v53, v52
	v_cndmask_b32_e64 v48, v68, v72, s[0:1]
	v_cndmask_b32_e64 v54, v65, v69, s[0:1]
	v_cndmask_b32_e64 v49, v87, v66, s[0:1]
	v_mov_b32_dpp v89, v48 quad_perm:[1,0,3,2] row_mask:0xf bank_mask:0xf
	v_mov_b32_dpp v86, v54 quad_perm:[1,0,3,2] row_mask:0xf bank_mask:0xf
	v_cndmask_b32_e64 v48, v86, v65, s[0:1]
	v_cndmask_b32_e64 v50, v88, v67, s[0:1]
	v_cndmask_b32_e64 v51, v89, v68, s[0:1]
	global_store_dwordx4 v[74:75], v[48:51], off
	s_waitcnt lgkmcnt(0)
	s_nop 0
	v_add_f32_e32 v48, v52, v53
	v_mov_b32_e32 v49, v48
	s_nop 1
	v_permlane32_swap_b32_e32 v49, v48
	v_cndmask_b32_e64 v50, v69, v86, s[0:1]
	v_cndmask_b32_e64 v51, v70, v87, s[0:1]
	v_cndmask_b32_e64 v52, v71, v88, s[0:1]
	v_cndmask_b32_e64 v53, v72, v89, s[0:1]
	global_store_dwordx4 v[76:77], v[50:53], off
	s_and_saveexec_b64 s[22:23], s[2:3]
	s_cbranch_execz .LBB0_1263
	v_ashrrev_i32_e32 v65, 31, v64
	v_lshl_add_u64 v[50:51], v[64:65], 2, s[12:13]
	s_waitcnt lgkmcnt(0)
	v_add_f32_e32 v48, v48, v49
	global_atomic_add_f32 v[50:51], v48, off
; __device__ __forceinline__ unsigned cvt_pk_bf16(float lo, float hi) { unsigned r; asm volatile("v_cvt_pk_bf16_f32 %0, %1, %2" : "=v"(r) : "v"(lo), "v"(hi)); return r; }
; __device__ __forceinline__ unsigned dpp_xor1(unsigned v) { return (unsigned)__builtin_amdgcn_update_dpp(0, (int)v, 0xB1, 0xf, 0xf, false); }
;     __device__ __forceinline__ void operator()(const f32x4 (&acc)[2][2][4][2], const Unit& u, int wr, int wc, int fr, int fq) const {
;         if constexpr (ALLBF) {
;             const int row0 = u.pm * BM + wr * 64 + fr, col0 = u.pn * BM + wc * 64 + 16 * fq; const bool odd = (fr & 1) != 0;
; #pragma unroll
;             for (int ai = 0; ai < 2; ++ai)
; #pragma unroll
;                 for (int m = 0; m < 4; ++m) {
;                     const int row = row0 + ai * HALF + m * 16; float s = 0.f;
;                     const bf16_t* pa = baseb + (size_t)(row - (odd ? 1 : 0)) * DM + col0 + (odd ? 8 : 0);
;                     const u32x4 la = *(const u32x4*)pa, lb = *(const u32x4*)(pa + DM);
;                     const u32x4 snd = odd ? la : lb; u32x4 rcv;
;                     rcv.x = dpp_xor1(snd.x); rcv.y = dpp_xor1(snd.y); rcv.z = dpp_xor1(snd.z); rcv.w = dpp_xor1(snd.w);
;                     const u32x4 bw0 = odd ? rcv : la, bw1 = odd ? lb : rcv;
;                     u32x4 pw[2];
; #pragma unroll
;                     for (int bj = 0; bj < 2; ++bj) { const u32x4 bw = bj ? bw1 : bw0;
;                         const f32x4 b0 = (f32x4){bf_lo(bw.x), bf_hi(bw.x), bf_lo(bw.y), bf_hi(bw.y)}, b1 = (f32x4){bf_lo(bw.z), bf_hi(bw.z), bf_lo(bw.w), bf_hi(bw.w)};
;                         const f32x4 v0 = acc[ai][bj][m][0] + b0, v1 = acc[ai][bj][m][1] + b1;
;                         pw[bj].x = cvt_pk_bf16(v0[0], v0[1]); pw[bj].y = cvt_pk_bf16(v0[2], v0[3]); pw[bj].z = cvt_pk_bf16(v1[0], v1[1]); pw[bj].w = cvt_pk_bf16(v1[2], v1[3]);
;                         s += (v0[0] * v0[0] + v0[1] * v0[1]) + (v0[2] * v0[2] + v0[3] * v0[3]) + (v1[0] * v1[0] + v1[1] * v1[1]) + (v1[2] * v1[2] + v1[3] * v1[3]); }
;                     store_pair_rows(HB, (size_t)DM, row, col0, fr, pw[0], pw[1]);
;                     s += __shfl_xor(s, 16); s += __shfl_xor(s, 32);
;                     if (fq == 0) unsafeAtomicAdd(ssn + row, s);
;                 }
.LBB0_1263:
	s_or_b64 exec, exec, s[22:23]
	v_add_u32_e32 v48, 0x90, v152
	v_sub_u32_e32 v50, v48, v158
	v_ashrrev_i32_e32 v51, 31, v50
	v_readlane_b32 s22, v254, 25
	v_lshlrev_b64 v[50:51], 12, v[50:51]
	v_readlane_b32 s23, v254, 26
	s_waitcnt lgkmcnt(0)
	v_mov_b32_e32 v49, v141
	v_mov_b32_e32 v62, v141
	v_lshl_add_u64 v[50:51], s[22:23], 0, v[50:51]
	v_lshl_add_u64 v[50:51], v[150:151], 1, v[50:51]
	v_lshl_add_u64 v[58:59], v[50:51], 0, v[140:141]
	v_add_co_u32_e32 v60, vcc, 0x1000, v58
	v_mov_b32_e32 v64, v141
	s_nop 0
	v_addc_co_u32_e32 v61, vcc, 0, v59, vcc
	global_load_dwordx4 v[50:53], v[58:59], off
	global_load_dwordx4 v[54:57], v[60:61], off
	v_mov_b32_e32 v63, v141
	v_mov_b32_e32 v72, v141
	v_mov_b32_e32 v71, v141
	v_mov_b32_e32 v70, v141
	v_mov_b32_e32 v73, v141
	s_waitcnt vmcnt(0)
	v_cndmask_b32_e64 v65, v53, v57, s[0:1]
	v_cndmask_b32_e64 v67, v51, v55, s[0:1]
	v_cndmask_b32_e64 v68, v50, v54, s[0:1]
	v_cndmask_b32_e64 v66, v52, v56, s[0:1]
	v_mov_b32_dpp v62, v67 quad_perm:[1,0,3,2] row_mask:0xf bank_mask:0xf
	v_mov_b32_dpp v49, v68 quad_perm:[1,0,3,2] row_mask:0xf bank_mask:0xf
	v_mov_b32_dpp v64, v65 quad_perm:[1,0,3,2] row_mask:0xf bank_mask:0xf
	v_mov_b32_dpp v63, v66 quad_perm:[1,0,3,2] row_mask:0xf bank_mask:0xf
	v_cndmask_b32_e64 v65, v64, v53, s[0:1]
	v_cndmask_b32_e64 v53, v62, v51, s[0:1]
	v_cndmask_b32_e64 v51, v49, v50, s[0:1]
	v_cndmask_b32_e64 v68, v55, v62, s[0:1]
	v_cndmask_b32_e64 v49, v54, v49, s[0:1]
	v_cndmask_b32_e64 v66, v63, v52, s[0:1]
	v_cndmask_b32_e64 v69, v57, v64, s[0:1]
	v_cndmask_b32_e64 v67, v56, v63, s[0:1]
	v_lshlrev_b32_e32 v50, 16, v51
	v_and_b32_e32 v51, 0xffff0000, v51
	v_lshlrev_b32_e32 v52, 16, v53
	v_and_b32_e32 v53, 0xffff0000, v53
	v_lshlrev_b32_e32 v56, 16, v65
	v_and_b32_e32 v57, 0xffff0000, v65
	v_lshlrev_b32_e32 v62, 16, v49
	v_and_b32_e32 v63, 0xffff0000, v49
	v_lshlrev_b32_e32 v64, 16, v68
	v_and_b32_e32 v65, 0xffff0000, v68
	v_lshlrev_b32_e32 v54, 16, v66
	v_and_b32_e32 v55, 0xffff0000, v66
	v_lshlrev_b32_e32 v66, 16, v67
	v_and_b32_e32 v67, 0xffff0000, v67
	v_lshlrev_b32_e32 v68, 16, v69
	v_and_b32_e32 v69, 0xffff0000, v69
	v_pk_add_f32 v[46:47], v[46:47], v[52:53]
	v_pk_add_f32 v[44:45], v[44:45], v[50:51]
	v_pk_add_f32 v[38:39], v[38:39], v[64:65]
	v_pk_add_f32 v[36:37], v[36:37], v[62:63]
	v_pk_add_f32 v[42:43], v[42:43], v[56:57]
	v_pk_add_f32 v[40:41], v[40:41], v[54:55]
	v_pk_add_f32 v[34:35], v[34:35], v[68:69]
	v_pk_add_f32 v[32:33], v[32:33], v[66:67]
	v_cvt_pk_bf16_f32 v49, v44, v45
	v_cvt_pk_bf16_f32 v50, v46, v47
	v_cvt_pk_bf16_f32 v51, v40, v41
	v_cvt_pk_bf16_f32 v52, v42, v43
	v_mul_f32_e32 v45, v45, v45
	v_mul_f32_e32 v47, v47, v47
	v_cvt_pk_bf16_f32 v53, v36, v37
	v_cvt_pk_bf16_f32 v54, v38, v39
	v_mul_f32_e32 v37, v37, v37
	v_mul_f32_e32 v39, v39, v39
	v_mul_f32_e32 v41, v41, v41
	v_cvt_pk_bf16_f32 v55, v32, v33
	v_cvt_pk_bf16_f32 v56, v34, v35
	v_mul_f32_e32 v33, v33, v33
	v_mul_f32_e32 v35, v35, v35
	v_fmac_f32_e32 v45, v44, v44
	v_fmac_f32_e32 v47, v46, v46
	v_fmac_f32_e32 v37, v36, v36
	v_fmac_f32_e32 v39, v38, v38
	v_mul_f32_e32 v43, v43, v43
	v_fmac_f32_e32 v41, v40, v40
	v_fmac_f32_e32 v33, v32, v32
	v_fmac_f32_e32 v35, v34, v34
	v_cndmask_b32_e64 v34, v51, v55, s[0:1]
	v_add_f32_e32 v40, v45, v47
	v_add_f32_e32 v37, v37, v39
	v_fmac_f32_e32 v43, v42, v42
	v_mov_b32_dpp v72, v34 quad_perm:[1,0,3,2] row_mask:0xf bank_mask:0xf
	v_add_f32_e32 v34, v41, v40
	v_add_f32_e32 v33, v33, v37
	v_cndmask_b32_e64 v36, v50, v54, s[0:1]
	v_add_f32_e32 v34, v43, v34
	v_add_f32_e32 v33, v35, v33
	v_mov_b32_dpp v71, v36 quad_perm:[1,0,3,2] row_mask:0xf bank_mask:0xf
	v_add_f32_e32 v36, v34, v33
	v_mov_b32_e32 v37, v36
	s_nop 1
	v_permlane16_swap_b32_e32 v37, v36
	v_cndmask_b32_e64 v32, v52, v56, s[0:1]
	v_cndmask_b32_e64 v38, v49, v53, s[0:1]
	v_cndmask_b32_e64 v33, v71, v50, s[0:1]
	v_mov_b32_dpp v73, v32 quad_perm:[1,0,3,2] row_mask:0xf bank_mask:0xf
	v_mov_b32_dpp v70, v38 quad_perm:[1,0,3,2] row_mask:0xf bank_mask:0xf
	v_cndmask_b32_e64 v32, v70, v49, s[0:1]
	v_cndmask_b32_e64 v34, v72, v51, s[0:1]
	v_cndmask_b32_e64 v35, v73, v52, s[0:1]
	global_store_dwordx4 v[58:59], v[32:35], off
	s_waitcnt lgkmcnt(0)
	s_nop 0
	v_add_f32_e32 v32, v36, v37
	v_mov_b32_e32 v33, v32
	s_nop 1
	v_permlane32_swap_b32_e32 v33, v32
	v_cndmask_b32_e64 v34, v53, v70, s[0:1]
	v_cndmask_b32_e64 v35, v54, v71, s[0:1]
	v_cndmask_b32_e64 v36, v55, v72, s[0:1]
	v_cndmask_b32_e64 v37, v56, v73, s[0:1]
	global_store_dwordx4 v[60:61], v[34:37], off
	s_and_saveexec_b64 s[22:23], s[2:3]
	s_cbranch_execz .LBB0_1265
	v_ashrrev_i32_e32 v49, 31, v48
	v_lshl_add_u64 v[34:35], v[48:49], 2, s[12:13]
	s_waitcnt lgkmcnt(0)
	v_add_f32_e32 v32, v32, v33
	global_atomic_add_f32 v[34:35], v32, off
; __device__ __forceinline__ unsigned cvt_pk_bf16(float lo, float hi) { unsigned r; asm volatile("v_cvt_pk_bf16_f32 %0, %1, %2" : "=v"(r) : "v"(lo), "v"(hi)); return r; }
; __device__ __forceinline__ unsigned dpp_xor1(unsigned v) { return (unsigned)__builtin_amdgcn_update_dpp(0, (int)v, 0xB1, 0xf, 0xf, false); }
; __device__ __forceinline__ float dpp_xor1(float v) { return __int_as_float(__builtin_amdgcn_update_dpp(0, __float_as_int(v), 0xB1, 0xf, 0xf, false)); }
;     __device__ __forceinline__ void operator()(const f32x4 (&acc)[2][2][4][2], const Unit& u, int wr, int wc, int fr, int fq) const {
;     ...
;                     const int row = row0 + ai * HALF + m * 16; float s = 0.f;
;                     const bf16_t* pa = baseb + (size_t)(row - (odd ? 1 : 0)) * DM + col0 + (odd ? 8 : 0);
;                     const u32x4 la = *(const u32x4*)pa, lb = *(const u32x4*)(pa + DM);
;                     const u32x4 snd = odd ? la : lb; u32x4 rcv;
;                     rcv.x = dpp_xor1(snd.x); rcv.y = dpp_xor1(snd.y); rcv.z = dpp_xor1(snd.z); rcv.w = dpp_xor1(snd.w);
;                     const u32x4 bw0 = odd ? rcv : la, bw1 = odd ? lb : rcv;
;                     u32x4 pw[2];
; #pragma unroll
;                     for (int bj = 0; bj < 2; ++bj) { const u32x4 bw = bj ? bw1 : bw0;
;                         const f32x4 b0 = (f32x4){bf_lo(bw.x), bf_hi(bw.x), bf_lo(bw.y), bf_hi(bw.y)}, b1 = (f32x4){bf_lo(bw.z), bf_hi(bw.z), bf_lo(bw.w), bf_hi(bw.w)};
;                         const f32x4 v0 = acc[ai][bj][m][0] + b0, v1 = acc[ai][bj][m][1] + b1;
;                         pw[bj].x = cvt_pk_bf16(v0[0], v0[1]); pw[bj].y = cvt_pk_bf16(v0[2], v0[3]); pw[bj].z = cvt_pk_bf16(v1[0], v1[1]); pw[bj].w = cvt_pk_bf16(v1[2], v1[3]);
;                         s += (v0[0] * v0[0] + v0[1] * v0[1]) + (v0[2] * v0[2] + v0[3] * v0[3]) + (v1[0] * v1[0] + v1[1] * v1[1]) + (v1[2] * v1[2] + v1[3] * v1[3]); }
;                     store_pair_rows(HB, (size_t)DM, row, col0, fr, pw[0], pw[1]);
;                     s += __shfl_xor(s, 16); s += __shfl_xor(s, 32);
;                     if (fq == 0) unsafeAtomicAdd(ssn + row, s);
.LBB0_1265:
	s_or_b64 exec, exec, s[22:23]
	v_add_u32_e32 v32, 0xa0, v152
	v_sub_u32_e32 v34, v32, v158
	v_ashrrev_i32_e32 v35, 31, v34
	v_readlane_b32 s22, v254, 25
	v_lshlrev_b64 v[34:35], 12, v[34:35]
	v_readlane_b32 s23, v254, 26
	s_waitcnt lgkmcnt(0)
	v_mov_b32_e32 v33, v141
	v_mov_b32_e32 v46, v141
	v_lshl_add_u64 v[34:35], s[22:23], 0, v[34:35]
	v_lshl_add_u64 v[34:35], v[150:151], 1, v[34:35]
	v_lshl_add_u64 v[42:43], v[34:35], 0, v[140:141]
	v_add_co_u32_e32 v44, vcc, 0x1000, v42
	v_mov_b32_e32 v48, v141
	s_nop 0
	v_addc_co_u32_e32 v45, vcc, 0, v43, vcc
	global_load_dwordx4 v[34:37], v[42:43], off
	global_load_dwordx4 v[38:41], v[44:45], off
	v_mov_b32_e32 v47, v141
	v_mov_b32_e32 v56, v141
	v_mov_b32_e32 v55, v141
	v_mov_b32_e32 v54, v141
	v_mov_b32_e32 v57, v141
	s_waitcnt vmcnt(0)
	v_cndmask_b32_e64 v49, v37, v41, s[0:1]
	v_cndmask_b32_e64 v51, v35, v39, s[0:1]
	v_cndmask_b32_e64 v52, v34, v38, s[0:1]
	v_cndmask_b32_e64 v50, v36, v40, s[0:1]
	v_mov_b32_dpp v46, v51 quad_perm:[1,0,3,2] row_mask:0xf bank_mask:0xf
	v_mov_b32_dpp v33, v52 quad_perm:[1,0,3,2] row_mask:0xf bank_mask:0xf
	v_mov_b32_dpp v48, v49 quad_perm:[1,0,3,2] row_mask:0xf bank_mask:0xf
	v_mov_b32_dpp v47, v50 quad_perm:[1,0,3,2] row_mask:0xf bank_mask:0xf
	v_cndmask_b32_e64 v49, v48, v37, s[0:1]
	v_cndmask_b32_e64 v37, v46, v35, s[0:1]
	v_cndmask_b32_e64 v35, v33, v34, s[0:1]
	v_cndmask_b32_e64 v52, v39, v46, s[0:1]
	v_cndmask_b32_e64 v33, v38, v33, s[0:1]
	v_cndmask_b32_e64 v50, v47, v36, s[0:1]
	v_cndmask_b32_e64 v53, v41, v48, s[0:1]
	v_cndmask_b32_e64 v51, v40, v47, s[0:1]
	v_lshlrev_b32_e32 v34, 16, v35
	v_and_b32_e32 v35, 0xffff0000, v35
	v_lshlrev_b32_e32 v36, 16, v37
	v_and_b32_e32 v37, 0xffff0000, v37
	v_lshlrev_b32_e32 v40, 16, v49
	v_and_b32_e32 v41, 0xffff0000, v49
	v_lshlrev_b32_e32 v46, 16, v33
	v_and_b32_e32 v47, 0xffff0000, v33
	v_lshlrev_b32_e32 v48, 16, v52
	v_and_b32_e32 v49, 0xffff0000, v52
	v_lshlrev_b32_e32 v38, 16, v50
	v_and_b32_e32 v39, 0xffff0000, v50
	v_lshlrev_b32_e32 v50, 16, v51
	v_and_b32_e32 v51, 0xffff0000, v51
	v_lshlrev_b32_e32 v52, 16, v53
	v_and_b32_e32 v53, 0xffff0000, v53
	v_pk_add_f32 v[30:31], v[30:31], v[36:37]
	v_pk_add_f32 v[28:29], v[28:29], v[34:35]
	v_pk_add_f32 v[22:23], v[22:23], v[48:49]
	v_pk_add_f32 v[20:21], v[20:21], v[46:47]
	v_pk_add_f32 v[26:27], v[26:27], v[40:41]
	v_pk_add_f32 v[24:25], v[24:25], v[38:39]
	v_pk_add_f32 v[18:19], v[18:19], v[52:53]
	v_pk_add_f32 v[16:17], v[16:17], v[50:51]
	v_cvt_pk_bf16_f32 v33, v28, v29
	v_cvt_pk_bf16_f32 v34, v30, v31
	v_cvt_pk_bf16_f32 v35, v24, v25
	v_cvt_pk_bf16_f32 v36, v26, v27
	v_mul_f32_e32 v29, v29, v29
	v_mul_f32_e32 v31, v31, v31
	v_cvt_pk_bf16_f32 v37, v20, v21
	v_cvt_pk_bf16_f32 v38, v22, v23
	v_mul_f32_e32 v21, v21, v21
	v_mul_f32_e32 v23, v23, v23
	v_mul_f32_e32 v25, v25, v25
	v_cvt_pk_bf16_f32 v39, v16, v17
	v_cvt_pk_bf16_f32 v40, v18, v19
	v_mul_f32_e32 v17, v17, v17
	v_mul_f32_e32 v19, v19, v19
	v_fmac_f32_e32 v29, v28, v28
	v_fmac_f32_e32 v31, v30, v30
	v_fmac_f32_e32 v21, v20, v20
	v_fmac_f32_e32 v23, v22, v22
	v_mul_f32_e32 v27, v27, v27
	v_fmac_f32_e32 v25, v24, v24
	v_fmac_f32_e32 v17, v16, v16
	v_fmac_f32_e32 v19, v18, v18
	v_cndmask_b32_e64 v18, v35, v39, s[0:1]
	v_add_f32_e32 v24, v29, v31
	v_add_f32_e32 v21, v21, v23
	v_fmac_f32_e32 v27, v26, v26
	v_mov_b32_dpp v56, v18 quad_perm:[1,0,3,2] row_mask:0xf bank_mask:0xf
	v_add_f32_e32 v18, v25, v24
	v_add_f32_e32 v17, v17, v21
	v_cndmask_b32_e64 v20, v34, v38, s[0:1]
	v_add_f32_e32 v18, v27, v18
	v_add_f32_e32 v17, v19, v17
	v_mov_b32_dpp v55, v20 quad_perm:[1,0,3,2] row_mask:0xf bank_mask:0xf
	v_add_f32_e32 v20, v18, v17
	v_mov_b32_e32 v21, v20
	s_nop 1
	v_permlane16_swap_b32_e32 v21, v20
	v_cndmask_b32_e64 v16, v36, v40, s[0:1]
	v_cndmask_b32_e64 v22, v33, v37, s[0:1]
	v_cndmask_b32_e64 v17, v55, v34, s[0:1]
	v_mov_b32_dpp v57, v16 quad_perm:[1,0,3,2] row_mask:0xf bank_mask:0xf
	v_mov_b32_dpp v54, v22 quad_perm:[1,0,3,2] row_mask:0xf bank_mask:0xf
	v_cndmask_b32_e64 v16, v54, v33, s[0:1]
	v_cndmask_b32_e64 v18, v56, v35, s[0:1]
	v_cndmask_b32_e64 v19, v57, v36, s[0:1]
	global_store_dwordx4 v[42:43], v[16:19], off
	s_waitcnt lgkmcnt(0)
	s_nop 0
	v_add_f32_e32 v16, v20, v21
	v_mov_b32_e32 v17, v16
	s_nop 1
	v_permlane32_swap_b32_e32 v17, v16
	v_cndmask_b32_e64 v18, v37, v54, s[0:1]
	v_cndmask_b32_e64 v19, v38, v55, s[0:1]
	v_cndmask_b32_e64 v20, v39, v56, s[0:1]
	v_cndmask_b32_e64 v21, v40, v57, s[0:1]
	global_store_dwordx4 v[44:45], v[18:21], off
	s_and_saveexec_b64 s[22:23], s[2:3]
	s_cbranch_execz .LBB0_1267
	v_ashrrev_i32_e32 v33, 31, v32
	v_lshl_add_u64 v[18:19], v[32:33], 2, s[12:13]
	s_waitcnt lgkmcnt(0)
	v_add_f32_e32 v16, v16, v17
	global_atomic_add_f32 v[18:19], v16, off
; __device__ __forceinline__ unsigned cvt_pk_bf16(float lo, float hi) { unsigned r; asm volatile("v_cvt_pk_bf16_f32 %0, %1, %2" : "=v"(r) : "v"(lo), "v"(hi)); return r; }
; __device__ __forceinline__ unsigned dpp_xor1(unsigned v) { return (unsigned)__builtin_amdgcn_update_dpp(0, (int)v, 0xB1, 0xf, 0xf, false); }
; __device__ __forceinline__ float dpp_xor1(float v) { return __int_as_float(__builtin_amdgcn_update_dpp(0, __float_as_int(v), 0xB1, 0xf, 0xf, false)); }
;     __device__ __forceinline__ void operator()(const f32x4 (&acc)[2][2][4][2], const Unit& u, int wr, int wc, int fr, int fq) const {
;     ...
;                     const int row = row0 + ai * HALF + m * 16; float s = 0.f;
;                     const bf16_t* pa = baseb + (size_t)(row - (odd ? 1 : 0)) * DM + col0 + (odd ? 8 : 0);
;                     const u32x4 la = *(const u32x4*)pa, lb = *(const u32x4*)(pa + DM);
;                     const u32x4 snd = odd ? la : lb; u32x4 rcv;
;                     rcv.x = dpp_xor1(snd.x); rcv.y = dpp_xor1(snd.y); rcv.z = dpp_xor1(snd.z); rcv.w = dpp_xor1(snd.w);
;                     const u32x4 bw0 = odd ? rcv : la, bw1 = odd ? lb : rcv;
;                     u32x4 pw[2];
; #pragma unroll
;                     for (int bj = 0; bj < 2; ++bj) { const u32x4 bw = bj ? bw1 : bw0;
;                         const f32x4 b0 = (f32x4){bf_lo(bw.x), bf_hi(bw.x), bf_lo(bw.y), bf_hi(bw.y)}, b1 = (f32x4){bf_lo(bw.z), bf_hi(bw.z), bf_lo(bw.w), bf_hi(bw.w)};
;                         const f32x4 v0 = acc[ai][bj][m][0] + b0, v1 = acc[ai][bj][m][1] + b1;
;                         pw[bj].x = cvt_pk_bf16(v0[0], v0[1]); pw[bj].y = cvt_pk_bf16(v0[2], v0[3]); pw[bj].z = cvt_pk_bf16(v1[0], v1[1]); pw[bj].w = cvt_pk_bf16(v1[2], v1[3]);
;                         s += (v0[0] * v0[0] + v0[1] * v0[1]) + (v0[2] * v0[2] + v0[3] * v0[3]) + (v1[0] * v1[0] + v1[1] * v1[1]) + (v1[2] * v1[2] + v1[3] * v1[3]); }
;                     store_pair_rows(HB, (size_t)DM, row, col0, fr, pw[0], pw[1]);
;                     s += __shfl_xor(s, 16); s += __shfl_xor(s, 32);
;                     if (fq == 0) unsafeAtomicAdd(ssn + row, s);
.LBB0_1267:
	s_or_b64 exec, exec, s[22:23]
	v_add_u32_e32 v16, 0xb0, v152
	v_sub_u32_e32 v18, v16, v158
	v_ashrrev_i32_e32 v19, 31, v18
	v_readlane_b32 s22, v254, 25
	v_lshlrev_b64 v[18:19], 12, v[18:19]
	v_readlane_b32 s23, v254, 26
	s_waitcnt lgkmcnt(0)
	v_mov_b32_e32 v17, v141
	v_mov_b32_e32 v30, v141
	v_lshl_add_u64 v[18:19], s[22:23], 0, v[18:19]
	v_lshl_add_u64 v[18:19], v[150:151], 1, v[18:19]
	v_lshl_add_u64 v[26:27], v[18:19], 0, v[140:141]
	v_add_co_u32_e32 v28, vcc, 0x1000, v26
	v_mov_b32_e32 v32, v141
	s_nop 0
	v_addc_co_u32_e32 v29, vcc, 0, v27, vcc
	global_load_dwordx4 v[18:21], v[26:27], off
	global_load_dwordx4 v[22:25], v[28:29], off
	v_mov_b32_e32 v31, v141
	v_mov_b32_e32 v40, v141
	v_mov_b32_e32 v39, v141
	v_mov_b32_e32 v38, v141
	v_mov_b32_e32 v41, v141
	s_waitcnt vmcnt(0)
	v_cndmask_b32_e64 v33, v21, v25, s[0:1]
	v_cndmask_b32_e64 v35, v19, v23, s[0:1]
	v_cndmask_b32_e64 v36, v18, v22, s[0:1]
	v_cndmask_b32_e64 v34, v20, v24, s[0:1]
	v_mov_b32_dpp v30, v35 quad_perm:[1,0,3,2] row_mask:0xf bank_mask:0xf
	v_mov_b32_dpp v17, v36 quad_perm:[1,0,3,2] row_mask:0xf bank_mask:0xf
	v_mov_b32_dpp v32, v33 quad_perm:[1,0,3,2] row_mask:0xf bank_mask:0xf
	v_mov_b32_dpp v31, v34 quad_perm:[1,0,3,2] row_mask:0xf bank_mask:0xf
	v_cndmask_b32_e64 v33, v32, v21, s[0:1]
	v_cndmask_b32_e64 v21, v30, v19, s[0:1]
	v_cndmask_b32_e64 v19, v17, v18, s[0:1]
	v_cndmask_b32_e64 v36, v23, v30, s[0:1]
	v_cndmask_b32_e64 v17, v22, v17, s[0:1]
	v_cndmask_b32_e64 v34, v31, v20, s[0:1]
	v_cndmask_b32_e64 v37, v25, v32, s[0:1]
	v_cndmask_b32_e64 v35, v24, v31, s[0:1]
	v_lshlrev_b32_e32 v18, 16, v19
	v_and_b32_e32 v19, 0xffff0000, v19
	v_lshlrev_b32_e32 v20, 16, v21
	v_and_b32_e32 v21, 0xffff0000, v21
	v_lshlrev_b32_e32 v24, 16, v33
	v_and_b32_e32 v25, 0xffff0000, v33
	v_lshlrev_b32_e32 v30, 16, v17
	v_and_b32_e32 v31, 0xffff0000, v17
	v_lshlrev_b32_e32 v32, 16, v36
	v_and_b32_e32 v33, 0xffff0000, v36
	v_lshlrev_b32_e32 v22, 16, v34
	v_and_b32_e32 v23, 0xffff0000, v34
	v_lshlrev_b32_e32 v34, 16, v35
	v_and_b32_e32 v35, 0xffff0000, v35
	v_lshlrev_b32_e32 v36, 16, v37
	v_and_b32_e32 v37, 0xffff0000, v37
	v_pk_add_f32 v[14:15], v[14:15], v[20:21]
	v_pk_add_f32 v[12:13], v[12:13], v[18:19]
	v_pk_add_f32 v[6:7], v[6:7], v[32:33]
	v_pk_add_f32 v[4:5], v[4:5], v[30:31]
	v_pk_add_f32 v[10:11], v[10:11], v[24:25]
	v_pk_add_f32 v[8:9], v[8:9], v[22:23]
	v_pk_add_f32 v[2:3], v[2:3], v[36:37]
	v_pk_add_f32 v[0:1], v[0:1], v[34:35]
	v_cvt_pk_bf16_f32 v17, v12, v13
	v_cvt_pk_bf16_f32 v18, v14, v15
	v_cvt_pk_bf16_f32 v19, v8, v9
	v_cvt_pk_bf16_f32 v20, v10, v11
	v_mul_f32_e32 v13, v13, v13
	v_mul_f32_e32 v15, v15, v15
	v_cvt_pk_bf16_f32 v21, v4, v5
	v_cvt_pk_bf16_f32 v22, v6, v7
	v_mul_f32_e32 v5, v5, v5
	v_mul_f32_e32 v7, v7, v7
	v_mul_f32_e32 v9, v9, v9
	v_cvt_pk_bf16_f32 v23, v0, v1
	v_cvt_pk_bf16_f32 v24, v2, v3
	v_mul_f32_e32 v1, v1, v1
	v_mul_f32_e32 v3, v3, v3
	v_fmac_f32_e32 v13, v12, v12
	v_fmac_f32_e32 v15, v14, v14
	v_fmac_f32_e32 v5, v4, v4
	v_fmac_f32_e32 v7, v6, v6
	v_mul_f32_e32 v11, v11, v11
	v_fmac_f32_e32 v9, v8, v8
	v_fmac_f32_e32 v1, v0, v0
	v_fmac_f32_e32 v3, v2, v2
	v_cndmask_b32_e64 v2, v19, v23, s[0:1]
	v_add_f32_e32 v8, v13, v15
	v_add_f32_e32 v5, v5, v7
	v_fmac_f32_e32 v11, v10, v10
	v_mov_b32_dpp v40, v2 quad_perm:[1,0,3,2] row_mask:0xf bank_mask:0xf
	v_add_f32_e32 v2, v9, v8
	v_add_f32_e32 v1, v1, v5
	v_cndmask_b32_e64 v4, v18, v22, s[0:1]
	v_add_f32_e32 v2, v11, v2
	v_add_f32_e32 v1, v3, v1
	v_mov_b32_dpp v39, v4 quad_perm:[1,0,3,2] row_mask:0xf bank_mask:0xf
	v_add_f32_e32 v4, v2, v1
	v_mov_b32_e32 v5, v4
	s_nop 1
	v_permlane16_swap_b32_e32 v5, v4
	v_cndmask_b32_e64 v0, v20, v24, s[0:1]
	v_cndmask_b32_e64 v6, v17, v21, s[0:1]
	v_cndmask_b32_e64 v1, v39, v18, s[0:1]
	v_mov_b32_dpp v41, v0 quad_perm:[1,0,3,2] row_mask:0xf bank_mask:0xf
	v_mov_b32_dpp v38, v6 quad_perm:[1,0,3,2] row_mask:0xf bank_mask:0xf
	v_cndmask_b32_e64 v0, v38, v17, s[0:1]
	v_cndmask_b32_e64 v2, v40, v19, s[0:1]
	v_cndmask_b32_e64 v3, v41, v20, s[0:1]
	global_store_dwordx4 v[26:27], v[0:3], off
	s_waitcnt lgkmcnt(0)
	s_nop 0
	v_add_f32_e32 v0, v4, v5
	v_mov_b32_e32 v1, v0
	s_nop 1
	v_permlane32_swap_b32_e32 v1, v0
	v_cndmask_b32_e64 v2, v21, v38, s[0:1]
	v_cndmask_b32_e64 v3, v22, v39, s[0:1]
	v_cndmask_b32_e64 v4, v23, v40, s[0:1]
	v_cndmask_b32_e64 v5, v24, v41, s[0:1]
	global_store_dwordx4 v[28:29], v[2:5], off
	s_and_saveexec_b64 s[22:23], s[2:3]
	s_cbranch_execz .LBB0_1269
	v_ashrrev_i32_e32 v17, 31, v16
	v_lshl_add_u64 v[2:3], v[16:17], 2, s[12:13]
	s_waitcnt lgkmcnt(0)
	v_add_f32_e32 v0, v0, v1
	global_atomic_add_f32 v[2:3], v0, off

; __device__ __forceinline__ unsigned cvt_pk_bf16(float lo, float hi) { unsigned r; asm volatile("v_cvt_pk_bf16_f32 %0, %1, %2" : "=v"(r) : "v"(lo), "v"(hi)); return r; }
; __device__ __forceinline__ unsigned dpp_xor1(unsigned v) { return (unsigned)__builtin_amdgcn_update_dpp(0, (int)v, 0xB1, 0xf, 0xf, false); }
; __device__ __forceinline__ float dpp_xor1(float v) { return __int_as_float(__builtin_amdgcn_update_dpp(0, __float_as_int(v), 0xB1, 0xf, 0xf, false)); }
;     __device__ __forceinline__ void operator()(const f32x4 (&acc)[2][2][4][2], const Unit& u, int wr, int wc, int fr, int fq) const {
;     ...
;             const int row0 = u.pm * BM + wr * 64 + fr, col0 = u.pn * BM + wc * 64 + 16 * fq; const bool odd = (fr & 1) != 0;
; #pragma unroll
;             for (int ai = 0; ai < 2; ++ai)
; #pragma unroll
;                 for (int m = 0; m < 4; ++m) {
;                     const int row = row0 + ai * HALF + m * 16; float s = 0.f;
;                     const bf16_t* pa = baseb + (size_t)(row - (odd ? 1 : 0)) * DM + col0 + (odd ? 8 : 0);
;                     const u32x4 la = *(const u32x4*)pa, lb = *(const u32x4*)(pa + DM);
;                     const u32x4 snd = odd ? la : lb; u32x4 rcv;
;                     rcv.x = dpp_xor1(snd.x); rcv.y = dpp_xor1(snd.y); rcv.z = dpp_xor1(snd.z); rcv.w = dpp_xor1(snd.w);
;                     const u32x4 bw0 = odd ? rcv : la, bw1 = odd ? lb : rcv;
;                     u32x4 pw[2];
; #pragma unroll
;                     for (int bj = 0; bj < 2; ++bj) { const u32x4 bw = bj ? bw1 : bw0;
;                         const f32x4 b0 = (f32x4){bf_lo(bw.x), bf_hi(bw.x), bf_lo(bw.y), bf_hi(bw.y)}, b1 = (f32x4){bf_lo(bw.z), bf_hi(bw.z), bf_lo(bw.w), bf_hi(bw.w)};
;                         const f32x4 v0 = acc[ai][bj][m][0] + b0, v1 = acc[ai][bj][m][1] + b1;
;                         pw[bj].x = cvt_pk_bf16(v0[0], v0[1]); pw[bj].y = cvt_pk_bf16(v0[2], v0[3]); pw[bj].z = cvt_pk_bf16(v1[0], v1[1]); pw[bj].w = cvt_pk_bf16(v1[2], v1[3]);
;                         s += (v0[0] * v0[0] + v0[1] * v0[1]) + (v0[2] * v0[2] + v0[3] * v0[3]) + (v1[0] * v1[0] + v1[1] * v1[1]) + (v1[2] * v1[2] + v1[3] * v1[3]); }
;                     store_pair_rows(HB, (size_t)DM, row, col0, fr, pw[0], pw[1]);
;                     s += __shfl_xor(s, 16); s += __shfl_xor(s, 32);
;                     if (fq == 0) unsafeAtomicAdd(ssn + row, s);
.LBB0_1942:
	v_lshl_add_u32 v152, s24, 8, v156
	v_sub_u32_e32 v154, v152, v158
	v_ashrrev_i32_e32 v155, 31, v154
	v_readlane_b32 s24, v254, 25
	v_lshl_or_b32 v150, s26, 8, v159
	v_lshlrev_b64 v[154:155], 12, v[154:155]
	v_readlane_b32 s25, v254, 26
	v_ashrrev_i32_e32 v151, 31, v150
	v_mov_b32_e32 v153, v141
	v_lshl_add_u64 v[154:155], s[24:25], 0, v[154:155]
	v_lshl_add_u64 v[154:155], v[150:151], 1, v[154:155]
	v_lshl_add_u64 v[172:173], v[154:155], 0, v[140:141]
	v_add_co_u32_e32 v154, vcc, 0x1000, v172
	v_mov_b32_e32 v174, v141
	s_nop 0
	v_addc_co_u32_e32 v155, vcc, 0, v173, vcc
	global_load_dwordx4 v[164:167], v[172:173], off
	global_load_dwordx4 v[168:171], v[154:155], off
	v_mov_b32_e32 v176, v141
	v_mov_b32_e32 v175, v141
	v_mov_b32_e32 v183, v141
	v_mov_b32_e32 v184, v141
	v_mov_b32_e32 v182, v141
	s_waitcnt vmcnt(0)
	v_cndmask_b32_e64 v177, v167, v171, s[0:1]
	v_cndmask_b32_e64 v179, v165, v169, s[0:1]
	v_cndmask_b32_e64 v180, v164, v168, s[0:1]
	v_cndmask_b32_e64 v178, v166, v170, s[0:1]
	v_mov_b32_dpp v174, v179 quad_perm:[1,0,3,2] row_mask:0xf bank_mask:0xf
	v_mov_b32_dpp v153, v180 quad_perm:[1,0,3,2] row_mask:0xf bank_mask:0xf
	v_mov_b32_dpp v176, v177 quad_perm:[1,0,3,2] row_mask:0xf bank_mask:0xf
	v_mov_b32_dpp v175, v178 quad_perm:[1,0,3,2] row_mask:0xf bank_mask:0xf
	v_cndmask_b32_e64 v177, v176, v167, s[0:1]
	v_cndmask_b32_e64 v167, v174, v165, s[0:1]
	v_cndmask_b32_e64 v165, v153, v164, s[0:1]
	v_cndmask_b32_e64 v180, v169, v174, s[0:1]
	v_cndmask_b32_e64 v153, v168, v153, s[0:1]
	v_cndmask_b32_e64 v178, v175, v166, s[0:1]
	v_cndmask_b32_e64 v181, v171, v176, s[0:1]
	v_cndmask_b32_e64 v179, v170, v175, s[0:1]
	v_lshlrev_b32_e32 v164, 16, v165
	v_and_b32_e32 v165, 0xffff0000, v165
	v_lshlrev_b32_e32 v166, 16, v167
	v_and_b32_e32 v167, 0xffff0000, v167
	v_lshlrev_b32_e32 v170, 16, v177
	v_and_b32_e32 v171, 0xffff0000, v177
	v_lshlrev_b32_e32 v174, 16, v153
	v_and_b32_e32 v175, 0xffff0000, v153
	v_lshlrev_b32_e32 v176, 16, v180
	v_and_b32_e32 v177, 0xffff0000, v180
	v_lshlrev_b32_e32 v168, 16, v178
	v_and_b32_e32 v169, 0xffff0000, v178
	v_lshlrev_b32_e32 v178, 16, v179
	v_and_b32_e32 v179, 0xffff0000, v179
	v_lshlrev_b32_e32 v180, 16, v181
	v_and_b32_e32 v181, 0xffff0000, v181
	v_pk_add_f32 v[126:127], v[126:127], v[166:167]
	v_pk_add_f32 v[124:125], v[124:125], v[164:165]
	v_pk_add_f32 v[118:119], v[118:119], v[176:177]
	v_pk_add_f32 v[116:117], v[116:117], v[174:175]
	v_pk_add_f32 v[122:123], v[122:123], v[170:171]
	v_pk_add_f32 v[120:121], v[120:121], v[168:169]
	v_pk_add_f32 v[114:115], v[114:115], v[180:181]
	v_pk_add_f32 v[112:113], v[112:113], v[178:179]
	v_cvt_pk_bf16_f32 v153, v124, v125
	v_cvt_pk_bf16_f32 v164, v126, v127
	v_cvt_pk_bf16_f32 v165, v120, v121
	v_cvt_pk_bf16_f32 v166, v122, v123
	v_mul_f32_e32 v125, v125, v125
	v_mul_f32_e32 v127, v127, v127
	v_cvt_pk_bf16_f32 v167, v116, v117
	v_cvt_pk_bf16_f32 v168, v118, v119
	v_mul_f32_e32 v117, v117, v117
	v_mul_f32_e32 v119, v119, v119
	v_mul_f32_e32 v121, v121, v121
	v_cvt_pk_bf16_f32 v169, v112, v113
	v_cvt_pk_bf16_f32 v170, v114, v115
	v_mul_f32_e32 v113, v113, v113
	v_mul_f32_e32 v115, v115, v115
	v_fmac_f32_e32 v125, v124, v124
	v_fmac_f32_e32 v127, v126, v126
	v_fmac_f32_e32 v117, v116, v116
	v_fmac_f32_e32 v119, v118, v118
	v_fmac_f32_e32 v121, v120, v120
	v_fmac_f32_e32 v113, v112, v112
	v_fmac_f32_e32 v115, v114, v114
	v_cndmask_b32_e64 v114, v165, v169, s[0:1]
	v_cndmask_b32_e64 v116, v164, v168, s[0:1]
	v_add_f32_e32 v120, v125, v127
	v_add_f32_e32 v117, v117, v119
	v_cndmask_b32_e64 v112, v166, v170, s[0:1]
	v_mov_b32_dpp v183, v116 quad_perm:[1,0,3,2] row_mask:0xf bank_mask:0xf
	v_add_f32_e32 v116, v121, v120
	v_add_f32_e32 v113, v113, v117
	v_mov_b32_dpp v184, v114 quad_perm:[1,0,3,2] row_mask:0xf bank_mask:0xf
	v_mov_b32_e32 v120, v141
	v_and_b32_e32 v114, 64, v163
	v_mul_f32_e32 v123, v123, v123
	v_add_f32_e32 v113, v115, v113
	v_mov_b32_dpp v120, v112 quad_perm:[1,0,3,2] row_mask:0xf bank_mask:0xf
	v_xor_b32_e32 v112, 16, v163
	v_add_u32_e32 v115, 64, v114
	v_fmac_f32_e32 v123, v122, v122
	v_cmp_lt_i32_e32 vcc, v112, v115
	v_add_f32_e32 v116, v123, v116
	v_add_f32_e32 v113, v116, v113
	v_cndmask_b32_e32 v112, v163, v112, vcc
	v_lshlrev_b32_e32 v114, 2, v112
	v_mov_b32_e32 v112, v113
	s_nop 1
	v_permlane16_swap_b32_e32 v112, v113
	v_cndmask_b32_e64 v118, v153, v167, s[0:1]
	v_cndmask_b32_e64 v117, v183, v164, s[0:1]
	v_cndmask_b32_e64 v119, v120, v166, s[0:1]
	v_mov_b32_dpp v182, v118 quad_perm:[1,0,3,2] row_mask:0xf bank_mask:0xf
	s_waitcnt lgkmcnt(0)
	v_add_f32_e32 v112, v113, v112
	v_xor_b32_e32 v113, 32, v163
	v_cmp_lt_i32_e32 vcc, v113, v115
	v_cndmask_b32_e64 v116, v182, v153, s[0:1]
	v_cndmask_b32_e64 v118, v184, v165, s[0:1]
	v_cndmask_b32_e32 v113, v163, v113, vcc
	v_lshlrev_b32_e32 v115, 2, v113
	v_mov_b32_e32 v113, v112
	s_nop 1
	v_permlane32_swap_b32_e32 v113, v112
	global_store_dwordx4 v[172:173], v[116:119], off
	s_nop 1
	v_cndmask_b32_e64 v116, v167, v182, s[0:1]
	v_cndmask_b32_e64 v117, v168, v183, s[0:1]
	v_cndmask_b32_e64 v118, v169, v184, s[0:1]
	v_cndmask_b32_e64 v119, v170, v120, s[0:1]
	global_store_dwordx4 v[154:155], v[116:119], off
	s_and_saveexec_b64 s[24:25], s[2:3]
	s_cbranch_execz .LBB0_1944
	v_ashrrev_i32_e32 v153, 31, v152
	v_lshl_add_u64 v[116:117], v[152:153], 2, s[10:11]
	s_waitcnt lgkmcnt(0)
	v_add_f32_e32 v112, v112, v113
	global_atomic_add_f32 v[116:117], v112, off
; __device__ __forceinline__ unsigned cvt_pk_bf16(float lo, float hi) { unsigned r; asm volatile("v_cvt_pk_bf16_f32 %0, %1, %2" : "=v"(r) : "v"(lo), "v"(hi)); return r; }
; __device__ __forceinline__ unsigned dpp_xor1(unsigned v) { return (unsigned)__builtin_amdgcn_update_dpp(0, (int)v, 0xB1, 0xf, 0xf, false); }
; __device__ __forceinline__ float dpp_xor1(float v) { return __int_as_float(__builtin_amdgcn_update_dpp(0, __float_as_int(v), 0xB1, 0xf, 0xf, false)); }
;     __device__ __forceinline__ void operator()(const f32x4 (&acc)[2][2][4][2], const Unit& u, int wr, int wc, int fr, int fq) const {
;     ...
;                     const int row = row0 + ai * HALF + m * 16; float s = 0.f;
;                     const bf16_t* pa = baseb + (size_t)(row - (odd ? 1 : 0)) * DM + col0 + (odd ? 8 : 0);
;                     const u32x4 la = *(const u32x4*)pa, lb = *(const u32x4*)(pa + DM);
;                     const u32x4 snd = odd ? la : lb; u32x4 rcv;
;                     rcv.x = dpp_xor1(snd.x); rcv.y = dpp_xor1(snd.y); rcv.z = dpp_xor1(snd.z); rcv.w = dpp_xor1(snd.w);
;                     const u32x4 bw0 = odd ? rcv : la, bw1 = odd ? lb : rcv;
;                     u32x4 pw[2];
; #pragma unroll
;                     for (int bj = 0; bj < 2; ++bj) { const u32x4 bw = bj ? bw1 : bw0;
;                         const f32x4 b0 = (f32x4){bf_lo(bw.x), bf_hi(bw.x), bf_lo(bw.y), bf_hi(bw.y)}, b1 = (f32x4){bf_lo(bw.z), bf_hi(bw.z), bf_lo(bw.w), bf_hi(bw.w)};
;                         const f32x4 v0 = acc[ai][bj][m][0] + b0, v1 = acc[ai][bj][m][1] + b1;
;                         pw[bj].x = cvt_pk_bf16(v0[0], v0[1]); pw[bj].y = cvt_pk_bf16(v0[2], v0[3]); pw[bj].z = cvt_pk_bf16(v1[0], v1[1]); pw[bj].w = cvt_pk_bf16(v1[2], v1[3]);
;                         s += (v0[0] * v0[0] + v0[1] * v0[1]) + (v0[2] * v0[2] + v0[3] * v0[3]) + (v1[0] * v1[0] + v1[1] * v1[1]) + (v1[2] * v1[2] + v1[3] * v1[3]); }
;                     store_pair_rows(HB, (size_t)DM, row, col0, fr, pw[0], pw[1]);
;                     s += __shfl_xor(s, 16); s += __shfl_xor(s, 32);
;                     if (fq == 0) unsafeAtomicAdd(ssn + row, s);
.LBB0_1944:
	s_or_b64 exec, exec, s[24:25]
	v_or_b32_e32 v112, 16, v152
	v_sub_u32_e32 v116, v112, v158
	v_ashrrev_i32_e32 v117, 31, v116
	v_readlane_b32 s24, v254, 25
	v_lshlrev_b64 v[116:117], 12, v[116:117]
	v_readlane_b32 s25, v254, 26
	s_waitcnt lgkmcnt(0)
	v_mov_b32_e32 v113, v141
	v_mov_b32_e32 v153, v141
	v_lshl_add_u64 v[116:117], s[24:25], 0, v[116:117]
	v_lshl_add_u64 v[116:117], v[150:151], 1, v[116:117]
	v_lshl_add_u64 v[124:125], v[116:117], 0, v[140:141]
	v_add_co_u32_e32 v126, vcc, 0x1000, v124
	v_mov_b32_e32 v154, v141
	s_nop 0
	v_addc_co_u32_e32 v127, vcc, 0, v125, vcc
	global_load_dwordx4 v[116:119], v[124:125], off
	global_load_dwordx4 v[120:123], v[126:127], off
	v_mov_b32_e32 v155, v141
	v_mov_b32_e32 v172, v141
	v_mov_b32_e32 v171, v141
	v_mov_b32_e32 v170, v141
	v_mov_b32_e32 v173, v141
	s_waitcnt vmcnt(0)
	v_cndmask_b32_e64 v164, v119, v123, s[0:1]
	v_cndmask_b32_e64 v165, v118, v122, s[0:1]
	v_cndmask_b32_e64 v166, v117, v121, s[0:1]
	v_cndmask_b32_e64 v167, v116, v120, s[0:1]
	v_mov_b32_dpp v154, v165 quad_perm:[1,0,3,2] row_mask:0xf bank_mask:0xf
	v_mov_b32_dpp v153, v166 quad_perm:[1,0,3,2] row_mask:0xf bank_mask:0xf
	v_mov_b32_dpp v113, v167 quad_perm:[1,0,3,2] row_mask:0xf bank_mask:0xf
	v_mov_b32_dpp v155, v164 quad_perm:[1,0,3,2] row_mask:0xf bank_mask:0xf
	v_cndmask_b32_e64 v164, v155, v119, s[0:1]
	v_cndmask_b32_e64 v165, v154, v118, s[0:1]
	v_cndmask_b32_e64 v119, v153, v117, s[0:1]
	v_cndmask_b32_e64 v117, v113, v116, s[0:1]
	v_cndmask_b32_e64 v153, v121, v153, s[0:1]
	v_cndmask_b32_e64 v113, v120, v113, s[0:1]
	v_cndmask_b32_e64 v169, v123, v155, s[0:1]
	v_cndmask_b32_e64 v167, v122, v154, s[0:1]
	v_lshlrev_b32_e32 v116, 16, v117
	v_and_b32_e32 v117, 0xffff0000, v117
	v_lshlrev_b32_e32 v118, 16, v119
	v_and_b32_e32 v119, 0xffff0000, v119
	v_lshlrev_b32_e32 v120, 16, v165
	v_and_b32_e32 v121, 0xffff0000, v165
	v_lshlrev_b32_e32 v122, 16, v164
	v_and_b32_e32 v123, 0xffff0000, v164
	v_lshlrev_b32_e32 v154, 16, v113
	v_and_b32_e32 v155, 0xffff0000, v113
	v_lshlrev_b32_e32 v164, 16, v153
	v_and_b32_e32 v165, 0xffff0000, v153
	v_lshlrev_b32_e32 v166, 16, v167
	v_and_b32_e32 v167, 0xffff0000, v167
	v_lshlrev_b32_e32 v168, 16, v169
	v_and_b32_e32 v169, 0xffff0000, v169
	v_pk_add_f32 v[110:111], v[110:111], v[118:119]
	v_pk_add_f32 v[108:109], v[108:109], v[116:117]
	v_pk_add_f32 v[102:103], v[102:103], v[164:165]
	v_pk_add_f32 v[100:101], v[100:101], v[154:155]
	v_pk_add_f32 v[106:107], v[106:107], v[122:123]
	v_pk_add_f32 v[104:105], v[104:105], v[120:121]
	v_pk_add_f32 v[98:99], v[98:99], v[168:169]
	v_pk_add_f32 v[96:97], v[96:97], v[166:167]
	v_cvt_pk_bf16_f32 v113, v108, v109
	v_cvt_pk_bf16_f32 v116, v110, v111
	v_cvt_pk_bf16_f32 v117, v104, v105
	v_cvt_pk_bf16_f32 v118, v106, v107
	v_mul_f32_e32 v109, v109, v109
	v_mul_f32_e32 v111, v111, v111
	v_cvt_pk_bf16_f32 v119, v100, v101
	v_cvt_pk_bf16_f32 v120, v102, v103
	v_mul_f32_e32 v101, v101, v101
	v_mul_f32_e32 v103, v103, v103
	v_mul_f32_e32 v105, v105, v105
	v_cvt_pk_bf16_f32 v121, v96, v97
	v_cvt_pk_bf16_f32 v122, v98, v99
	v_mul_f32_e32 v97, v97, v97
	v_mul_f32_e32 v99, v99, v99
	v_fmac_f32_e32 v109, v108, v108
	v_fmac_f32_e32 v111, v110, v110
	v_fmac_f32_e32 v101, v100, v100
	v_fmac_f32_e32 v103, v102, v102
	v_mul_f32_e32 v107, v107, v107
	v_fmac_f32_e32 v105, v104, v104
	v_fmac_f32_e32 v97, v96, v96
	v_fmac_f32_e32 v99, v98, v98
	v_cndmask_b32_e64 v98, v117, v121, s[0:1]
	v_add_f32_e32 v104, v109, v111
	v_add_f32_e32 v101, v101, v103
	v_fmac_f32_e32 v107, v106, v106
	v_mov_b32_dpp v172, v98 quad_perm:[1,0,3,2] row_mask:0xf bank_mask:0xf
	v_add_f32_e32 v98, v105, v104
	v_add_f32_e32 v97, v97, v101
	v_cndmask_b32_e64 v100, v116, v120, s[0:1]
	v_add_f32_e32 v98, v107, v98
	v_add_f32_e32 v97, v99, v97
	v_mov_b32_dpp v171, v100 quad_perm:[1,0,3,2] row_mask:0xf bank_mask:0xf
	v_add_f32_e32 v100, v98, v97
	v_mov_b32_e32 v101, v100
	s_nop 1
	v_permlane16_swap_b32_e32 v101, v100
	v_cndmask_b32_e64 v96, v118, v122, s[0:1]
	v_cndmask_b32_e64 v102, v113, v119, s[0:1]
	v_cndmask_b32_e64 v97, v171, v116, s[0:1]
	v_mov_b32_dpp v173, v96 quad_perm:[1,0,3,2] row_mask:0xf bank_mask:0xf
	v_mov_b32_dpp v170, v102 quad_perm:[1,0,3,2] row_mask:0xf bank_mask:0xf
	v_cndmask_b32_e64 v96, v170, v113, s[0:1]
	v_cndmask_b32_e64 v98, v172, v117, s[0:1]
	v_cndmask_b32_e64 v99, v173, v118, s[0:1]
	global_store_dwordx4 v[124:125], v[96:99], off
	s_waitcnt lgkmcnt(0)
	s_nop 0
	v_add_f32_e32 v96, v100, v101
	v_mov_b32_e32 v97, v96
	s_nop 1
	v_permlane32_swap_b32_e32 v97, v96
	v_cndmask_b32_e64 v98, v119, v170, s[0:1]
	v_cndmask_b32_e64 v99, v120, v171, s[0:1]
	v_cndmask_b32_e64 v100, v121, v172, s[0:1]
	v_cndmask_b32_e64 v101, v122, v173, s[0:1]
	global_store_dwordx4 v[126:127], v[98:101], off
	s_and_saveexec_b64 s[24:25], s[2:3]
	s_cbranch_execz .LBB0_1946
	v_ashrrev_i32_e32 v113, 31, v112
	v_lshl_add_u64 v[98:99], v[112:113], 2, s[10:11]
	s_waitcnt lgkmcnt(0)
	v_add_f32_e32 v96, v96, v97
	global_atomic_add_f32 v[98:99], v96, off
; __device__ __forceinline__ unsigned cvt_pk_bf16(float lo, float hi) { unsigned r; asm volatile("v_cvt_pk_bf16_f32 %0, %1, %2" : "=v"(r) : "v"(lo), "v"(hi)); return r; }
; __device__ __forceinline__ unsigned dpp_xor1(unsigned v) { return (unsigned)__builtin_amdgcn_update_dpp(0, (int)v, 0xB1, 0xf, 0xf, false); }
; __device__ __forceinline__ float dpp_xor1(float v) { return __int_as_float(__builtin_amdgcn_update_dpp(0, __float_as_int(v), 0xB1, 0xf, 0xf, false)); }
;     __device__ __forceinline__ void operator()(const f32x4 (&acc)[2][2][4][2], const Unit& u, int wr, int wc, int fr, int fq) const {
;     ...
;                     const int row = row0 + ai * HALF + m * 16; float s = 0.f;
;                     const bf16_t* pa = baseb + (size_t)(row - (odd ? 1 : 0)) * DM + col0 + (odd ? 8 : 0);
;                     const u32x4 la = *(const u32x4*)pa, lb = *(const u32x4*)(pa + DM);
;                     const u32x4 snd = odd ? la : lb; u32x4 rcv;
;                     rcv.x = dpp_xor1(snd.x); rcv.y = dpp_xor1(snd.y); rcv.z = dpp_xor1(snd.z); rcv.w = dpp_xor1(snd.w);
;                     const u32x4 bw0 = odd ? rcv : la, bw1 = odd ? lb : rcv;
;                     u32x4 pw[2];
; #pragma unroll
;                     for (int bj = 0; bj < 2; ++bj) { const u32x4 bw = bj ? bw1 : bw0;
;                         const f32x4 b0 = (f32x4){bf_lo(bw.x), bf_hi(bw.x), bf_lo(bw.y), bf_hi(bw.y)}, b1 = (f32x4){bf_lo(bw.z), bf_hi(bw.z), bf_lo(bw.w), bf_hi(bw.w)};
;                         const f32x4 v0 = acc[ai][bj][m][0] + b0, v1 = acc[ai][bj][m][1] + b1;
;                         pw[bj].x = cvt_pk_bf16(v0[0], v0[1]); pw[bj].y = cvt_pk_bf16(v0[2], v0[3]); pw[bj].z = cvt_pk_bf16(v1[0], v1[1]); pw[bj].w = cvt_pk_bf16(v1[2], v1[3]);
;                         s += (v0[0] * v0[0] + v0[1] * v0[1]) + (v0[2] * v0[2] + v0[3] * v0[3]) + (v1[0] * v1[0] + v1[1] * v1[1]) + (v1[2] * v1[2] + v1[3] * v1[3]); }
;                     store_pair_rows(HB, (size_t)DM, row, col0, fr, pw[0], pw[1]);
;                     s += __shfl_xor(s, 16); s += __shfl_xor(s, 32);
;                     if (fq == 0) unsafeAtomicAdd(ssn + row, s);
.LBB0_1946:
	s_or_b64 exec, exec, s[24:25]
	v_or_b32_e32 v96, 32, v152
	v_sub_u32_e32 v98, v96, v158
	v_ashrrev_i32_e32 v99, 31, v98
	v_readlane_b32 s24, v254, 25
	v_lshlrev_b64 v[98:99], 12, v[98:99]
	v_readlane_b32 s25, v254, 26
	s_waitcnt lgkmcnt(0)
	v_mov_b32_e32 v97, v141
	v_mov_b32_e32 v110, v141
	v_lshl_add_u64 v[98:99], s[24:25], 0, v[98:99]
	v_lshl_add_u64 v[98:99], v[150:151], 1, v[98:99]
	v_lshl_add_u64 v[106:107], v[98:99], 0, v[140:141]
	v_add_co_u32_e32 v108, vcc, 0x1000, v106
	v_mov_b32_e32 v112, v141
	s_nop 0
	v_addc_co_u32_e32 v109, vcc, 0, v107, vcc
	global_load_dwordx4 v[98:101], v[106:107], off
	global_load_dwordx4 v[102:105], v[108:109], off
	v_mov_b32_e32 v111, v141
	v_mov_b32_e32 v122, v141
	v_mov_b32_e32 v121, v141
	v_mov_b32_e32 v120, v141
	v_mov_b32_e32 v123, v141
	s_waitcnt vmcnt(0)
	v_cndmask_b32_e64 v113, v101, v105, s[0:1]
	v_cndmask_b32_e64 v117, v99, v103, s[0:1]
	v_cndmask_b32_e64 v118, v98, v102, s[0:1]
	v_cndmask_b32_e64 v116, v100, v104, s[0:1]
	v_mov_b32_dpp v110, v117 quad_perm:[1,0,3,2] row_mask:0xf bank_mask:0xf
	v_mov_b32_dpp v97, v118 quad_perm:[1,0,3,2] row_mask:0xf bank_mask:0xf
	v_mov_b32_dpp v112, v113 quad_perm:[1,0,3,2] row_mask:0xf bank_mask:0xf
	v_mov_b32_dpp v111, v116 quad_perm:[1,0,3,2] row_mask:0xf bank_mask:0xf
	v_cndmask_b32_e64 v113, v112, v101, s[0:1]
	v_cndmask_b32_e64 v101, v110, v99, s[0:1]
	v_cndmask_b32_e64 v99, v97, v98, s[0:1]
	v_cndmask_b32_e64 v118, v103, v110, s[0:1]
	v_cndmask_b32_e64 v97, v102, v97, s[0:1]
	v_cndmask_b32_e64 v116, v111, v100, s[0:1]
	v_cndmask_b32_e64 v119, v105, v112, s[0:1]
	v_cndmask_b32_e64 v117, v104, v111, s[0:1]
	v_lshlrev_b32_e32 v98, 16, v99
	v_and_b32_e32 v99, 0xffff0000, v99
	v_lshlrev_b32_e32 v100, 16, v101
	v_and_b32_e32 v101, 0xffff0000, v101
	v_lshlrev_b32_e32 v104, 16, v113
	v_and_b32_e32 v105, 0xffff0000, v113
	v_lshlrev_b32_e32 v110, 16, v97
	v_and_b32_e32 v111, 0xffff0000, v97
	v_lshlrev_b32_e32 v112, 16, v118
	v_and_b32_e32 v113, 0xffff0000, v118
	v_lshlrev_b32_e32 v102, 16, v116
	v_and_b32_e32 v103, 0xffff0000, v116
	v_lshlrev_b32_e32 v116, 16, v117
	v_and_b32_e32 v117, 0xffff0000, v117
	v_lshlrev_b32_e32 v118, 16, v119
	v_and_b32_e32 v119, 0xffff0000, v119
	v_pk_add_f32 v[94:95], v[94:95], v[100:101]
	v_pk_add_f32 v[92:93], v[92:93], v[98:99]
	v_pk_add_f32 v[86:87], v[86:87], v[112:113]
	v_pk_add_f32 v[84:85], v[84:85], v[110:111]
	v_pk_add_f32 v[90:91], v[90:91], v[104:105]
	v_pk_add_f32 v[88:89], v[88:89], v[102:103]
	v_pk_add_f32 v[82:83], v[82:83], v[118:119]
	v_pk_add_f32 v[80:81], v[80:81], v[116:117]
	v_cvt_pk_bf16_f32 v97, v92, v93
	v_cvt_pk_bf16_f32 v98, v94, v95
	v_cvt_pk_bf16_f32 v99, v88, v89
	v_cvt_pk_bf16_f32 v100, v90, v91
	v_mul_f32_e32 v93, v93, v93
	v_mul_f32_e32 v95, v95, v95
	v_cvt_pk_bf16_f32 v101, v84, v85
	v_cvt_pk_bf16_f32 v102, v86, v87
	v_mul_f32_e32 v85, v85, v85
	v_mul_f32_e32 v87, v87, v87
	v_mul_f32_e32 v89, v89, v89
	v_cvt_pk_bf16_f32 v103, v80, v81
	v_cvt_pk_bf16_f32 v104, v82, v83
	v_mul_f32_e32 v81, v81, v81
	v_mul_f32_e32 v83, v83, v83
	v_fmac_f32_e32 v93, v92, v92
	v_fmac_f32_e32 v95, v94, v94
	v_fmac_f32_e32 v85, v84, v84
	v_fmac_f32_e32 v87, v86, v86
	v_mul_f32_e32 v91, v91, v91
	v_fmac_f32_e32 v89, v88, v88
	v_fmac_f32_e32 v81, v80, v80
	v_fmac_f32_e32 v83, v82, v82
	v_cndmask_b32_e64 v82, v99, v103, s[0:1]
	v_add_f32_e32 v88, v93, v95
	v_add_f32_e32 v85, v85, v87
	v_fmac_f32_e32 v91, v90, v90
	v_mov_b32_dpp v122, v82 quad_perm:[1,0,3,2] row_mask:0xf bank_mask:0xf
	v_add_f32_e32 v82, v89, v88
	v_add_f32_e32 v81, v81, v85
	v_cndmask_b32_e64 v84, v98, v102, s[0:1]
	v_add_f32_e32 v82, v91, v82
	v_add_f32_e32 v81, v83, v81
	v_mov_b32_dpp v121, v84 quad_perm:[1,0,3,2] row_mask:0xf bank_mask:0xf
	v_add_f32_e32 v84, v82, v81
	v_mov_b32_e32 v85, v84
	s_nop 1
	v_permlane16_swap_b32_e32 v85, v84
	v_cndmask_b32_e64 v80, v100, v104, s[0:1]
	v_cndmask_b32_e64 v86, v97, v101, s[0:1]
	v_cndmask_b32_e64 v81, v121, v98, s[0:1]
	v_mov_b32_dpp v123, v80 quad_perm:[1,0,3,2] row_mask:0xf bank_mask:0xf
	v_mov_b32_dpp v120, v86 quad_perm:[1,0,3,2] row_mask:0xf bank_mask:0xf
	v_cndmask_b32_e64 v80, v120, v97, s[0:1]
	v_cndmask_b32_e64 v82, v122, v99, s[0:1]
	v_cndmask_b32_e64 v83, v123, v100, s[0:1]
	global_store_dwordx4 v[106:107], v[80:83], off
	s_waitcnt lgkmcnt(0)
	s_nop 0
	v_add_f32_e32 v80, v84, v85
	v_mov_b32_e32 v81, v80
	s_nop 1
	v_permlane32_swap_b32_e32 v81, v80
	v_cndmask_b32_e64 v82, v101, v120, s[0:1]
	v_cndmask_b32_e64 v83, v102, v121, s[0:1]
	v_cndmask_b32_e64 v84, v103, v122, s[0:1]
	v_cndmask_b32_e64 v85, v104, v123, s[0:1]
	global_store_dwordx4 v[108:109], v[82:85], off
	s_and_saveexec_b64 s[24:25], s[2:3]
	s_cbranch_execz .LBB0_1948
	v_ashrrev_i32_e32 v97, 31, v96
	v_lshl_add_u64 v[82:83], v[96:97], 2, s[10:11]
	s_waitcnt lgkmcnt(0)
	v_add_f32_e32 v80, v80, v81
	global_atomic_add_f32 v[82:83], v80, off
; __device__ __forceinline__ unsigned cvt_pk_bf16(float lo, float hi) { unsigned r; asm volatile("v_cvt_pk_bf16_f32 %0, %1, %2" : "=v"(r) : "v"(lo), "v"(hi)); return r; }
; __device__ __forceinline__ unsigned dpp_xor1(unsigned v) { return (unsigned)__builtin_amdgcn_update_dpp(0, (int)v, 0xB1, 0xf, 0xf, false); }
; __device__ __forceinline__ float dpp_xor1(float v) { return __int_as_float(__builtin_amdgcn_update_dpp(0, __float_as_int(v), 0xB1, 0xf, 0xf, false)); }
;     __device__ __forceinline__ void operator()(const f32x4 (&acc)[2][2][4][2], const Unit& u, int wr, int wc, int fr, int fq) const {
;     ...
;                     const int row = row0 + ai * HALF + m * 16; float s = 0.f;
;                     const bf16_t* pa = baseb + (size_t)(row - (odd ? 1 : 0)) * DM + col0 + (odd ? 8 : 0);
;                     const u32x4 la = *(const u32x4*)pa, lb = *(const u32x4*)(pa + DM);
;                     const u32x4 snd = odd ? la : lb; u32x4 rcv;
;                     rcv.x = dpp_xor1(snd.x); rcv.y = dpp_xor1(snd.y); rcv.z = dpp_xor1(snd.z); rcv.w = dpp_xor1(snd.w);
;                     const u32x4 bw0 = odd ? rcv : la, bw1 = odd ? lb : rcv;
;                     u32x4 pw[2];
; #pragma unroll
;                     for (int bj = 0; bj < 2; ++bj) { const u32x4 bw = bj ? bw1 : bw0;
;                         const f32x4 b0 = (f32x4){bf_lo(bw.x), bf_hi(bw.x), bf_lo(bw.y), bf_hi(bw.y)}, b1 = (f32x4){bf_lo(bw.z), bf_hi(bw.z), bf_lo(bw.w), bf_hi(bw.w)};
;                         const f32x4 v0 = acc[ai][bj][m][0] + b0, v1 = acc[ai][bj][m][1] + b1;
;                         pw[bj].x = cvt_pk_bf16(v0[0], v0[1]); pw[bj].y = cvt_pk_bf16(v0[2], v0[3]); pw[bj].z = cvt_pk_bf16(v1[0], v1[1]); pw[bj].w = cvt_pk_bf16(v1[2], v1[3]);
;                         s += (v0[0] * v0[0] + v0[1] * v0[1]) + (v0[2] * v0[2] + v0[3] * v0[3]) + (v1[0] * v1[0] + v1[1] * v1[1]) + (v1[2] * v1[2] + v1[3] * v1[3]); }
;                     store_pair_rows(HB, (size_t)DM, row, col0, fr, pw[0], pw[1]);
;                     s += __shfl_xor(s, 16); s += __shfl_xor(s, 32);
;                     if (fq == 0) unsafeAtomicAdd(ssn + row, s);
.LBB0_1948:
	s_or_b64 exec, exec, s[24:25]
	v_or_b32_e32 v80, 48, v152
	v_sub_u32_e32 v82, v80, v158
	v_ashrrev_i32_e32 v83, 31, v82
	v_readlane_b32 s24, v254, 25
	v_lshlrev_b64 v[82:83], 12, v[82:83]
	v_readlane_b32 s25, v254, 26
	s_waitcnt lgkmcnt(0)
	v_mov_b32_e32 v81, v141
	v_mov_b32_e32 v94, v141
	v_lshl_add_u64 v[82:83], s[24:25], 0, v[82:83]
	v_lshl_add_u64 v[82:83], v[150:151], 1, v[82:83]
	v_lshl_add_u64 v[90:91], v[82:83], 0, v[140:141]
	v_add_co_u32_e32 v92, vcc, 0x1000, v90
	v_mov_b32_e32 v96, v141
	s_nop 0
	v_addc_co_u32_e32 v93, vcc, 0, v91, vcc
	global_load_dwordx4 v[82:85], v[90:91], off
	global_load_dwordx4 v[86:89], v[92:93], off
	v_mov_b32_e32 v95, v141
	v_mov_b32_e32 v104, v141
	v_mov_b32_e32 v103, v141
	v_mov_b32_e32 v102, v141
	v_mov_b32_e32 v105, v141
	s_waitcnt vmcnt(0)
	v_cndmask_b32_e64 v97, v85, v89, s[0:1]
	v_cndmask_b32_e64 v99, v83, v87, s[0:1]
	v_cndmask_b32_e64 v100, v82, v86, s[0:1]
	v_cndmask_b32_e64 v98, v84, v88, s[0:1]
	v_mov_b32_dpp v94, v99 quad_perm:[1,0,3,2] row_mask:0xf bank_mask:0xf
	v_mov_b32_dpp v81, v100 quad_perm:[1,0,3,2] row_mask:0xf bank_mask:0xf
	v_mov_b32_dpp v96, v97 quad_perm:[1,0,3,2] row_mask:0xf bank_mask:0xf
	v_mov_b32_dpp v95, v98 quad_perm:[1,0,3,2] row_mask:0xf bank_mask:0xf
	v_cndmask_b32_e64 v97, v96, v85, s[0:1]
	v_cndmask_b32_e64 v85, v94, v83, s[0:1]
	v_cndmask_b32_e64 v83, v81, v82, s[0:1]
	v_cndmask_b32_e64 v100, v87, v94, s[0:1]
	v_cndmask_b32_e64 v81, v86, v81, s[0:1]
	v_cndmask_b32_e64 v98, v95, v84, s[0:1]
	v_cndmask_b32_e64 v101, v89, v96, s[0:1]
	v_cndmask_b32_e64 v99, v88, v95, s[0:1]
	v_lshlrev_b32_e32 v82, 16, v83
	v_and_b32_e32 v83, 0xffff0000, v83
	v_lshlrev_b32_e32 v84, 16, v85
	v_and_b32_e32 v85, 0xffff0000, v85
	v_lshlrev_b32_e32 v88, 16, v97
	v_and_b32_e32 v89, 0xffff0000, v97
	v_lshlrev_b32_e32 v94, 16, v81
	v_and_b32_e32 v95, 0xffff0000, v81
	v_lshlrev_b32_e32 v96, 16, v100
	v_and_b32_e32 v97, 0xffff0000, v100
	v_lshlrev_b32_e32 v86, 16, v98
	v_and_b32_e32 v87, 0xffff0000, v98
	v_lshlrev_b32_e32 v98, 16, v99
	v_and_b32_e32 v99, 0xffff0000, v99
	v_lshlrev_b32_e32 v100, 16, v101
	v_and_b32_e32 v101, 0xffff0000, v101
	v_pk_add_f32 v[78:79], v[78:79], v[84:85]
	v_pk_add_f32 v[76:77], v[76:77], v[82:83]
	v_pk_add_f32 v[70:71], v[70:71], v[96:97]
	v_pk_add_f32 v[68:69], v[68:69], v[94:95]
	v_pk_add_f32 v[74:75], v[74:75], v[88:89]
	v_pk_add_f32 v[72:73], v[72:73], v[86:87]
	v_pk_add_f32 v[66:67], v[66:67], v[100:101]
	v_pk_add_f32 v[64:65], v[64:65], v[98:99]
	v_cvt_pk_bf16_f32 v81, v76, v77
	v_cvt_pk_bf16_f32 v82, v78, v79
	v_cvt_pk_bf16_f32 v83, v72, v73
	v_cvt_pk_bf16_f32 v84, v74, v75
	v_mul_f32_e32 v77, v77, v77
	v_mul_f32_e32 v79, v79, v79
	v_cvt_pk_bf16_f32 v85, v68, v69
	v_cvt_pk_bf16_f32 v86, v70, v71
	v_mul_f32_e32 v69, v69, v69
	v_mul_f32_e32 v71, v71, v71
	v_mul_f32_e32 v73, v73, v73
	v_cvt_pk_bf16_f32 v87, v64, v65
	v_cvt_pk_bf16_f32 v88, v66, v67
	v_mul_f32_e32 v65, v65, v65
	v_mul_f32_e32 v67, v67, v67
	v_fmac_f32_e32 v77, v76, v76
	v_fmac_f32_e32 v79, v78, v78
	v_fmac_f32_e32 v69, v68, v68
	v_fmac_f32_e32 v71, v70, v70
	v_mul_f32_e32 v75, v75, v75
	v_fmac_f32_e32 v73, v72, v72
	v_fmac_f32_e32 v65, v64, v64
	v_fmac_f32_e32 v67, v66, v66
	v_cndmask_b32_e64 v66, v83, v87, s[0:1]
	v_add_f32_e32 v72, v77, v79
	v_add_f32_e32 v69, v69, v71
	v_fmac_f32_e32 v75, v74, v74
	v_mov_b32_dpp v104, v66 quad_perm:[1,0,3,2] row_mask:0xf bank_mask:0xf
	v_add_f32_e32 v66, v73, v72
	v_add_f32_e32 v65, v65, v69
	v_cndmask_b32_e64 v68, v82, v86, s[0:1]
	v_add_f32_e32 v66, v75, v66
	v_add_f32_e32 v65, v67, v65
	v_mov_b32_dpp v103, v68 quad_perm:[1,0,3,2] row_mask:0xf bank_mask:0xf
	v_add_f32_e32 v68, v66, v65
	v_mov_b32_e32 v69, v68
	s_nop 1
	v_permlane16_swap_b32_e32 v69, v68
	v_cndmask_b32_e64 v64, v84, v88, s[0:1]
	v_cndmask_b32_e64 v70, v81, v85, s[0:1]
	v_cndmask_b32_e64 v65, v103, v82, s[0:1]
	v_mov_b32_dpp v105, v64 quad_perm:[1,0,3,2] row_mask:0xf bank_mask:0xf
	v_mov_b32_dpp v102, v70 quad_perm:[1,0,3,2] row_mask:0xf bank_mask:0xf
	v_cndmask_b32_e64 v64, v102, v81, s[0:1]
	v_cndmask_b32_e64 v66, v104, v83, s[0:1]
	v_cndmask_b32_e64 v67, v105, v84, s[0:1]
	global_store_dwordx4 v[90:91], v[64:67], off
	s_waitcnt lgkmcnt(0)
	s_nop 0
	v_add_f32_e32 v64, v68, v69
	v_mov_b32_e32 v65, v64
	s_nop 1
	v_permlane32_swap_b32_e32 v65, v64
	v_cndmask_b32_e64 v66, v85, v102, s[0:1]
	v_cndmask_b32_e64 v67, v86, v103, s[0:1]
	v_cndmask_b32_e64 v68, v87, v104, s[0:1]
	v_cndmask_b32_e64 v69, v88, v105, s[0:1]
	global_store_dwordx4 v[92:93], v[66:69], off
	s_and_saveexec_b64 s[24:25], s[2:3]
	s_cbranch_execz .LBB0_1950
	v_ashrrev_i32_e32 v81, 31, v80
	v_lshl_add_u64 v[66:67], v[80:81], 2, s[10:11]
	s_waitcnt lgkmcnt(0)
	v_add_f32_e32 v64, v64, v65
	global_atomic_add_f32 v[66:67], v64, off
; __device__ __forceinline__ unsigned cvt_pk_bf16(float lo, float hi) { unsigned r; asm volatile("v_cvt_pk_bf16_f32 %0, %1, %2" : "=v"(r) : "v"(lo), "v"(hi)); return r; }
; __device__ __forceinline__ unsigned dpp_xor1(unsigned v) { return (unsigned)__builtin_amdgcn_update_dpp(0, (int)v, 0xB1, 0xf, 0xf, false); }
; __device__ __forceinline__ float dpp_xor1(float v) { return __int_as_float(__builtin_amdgcn_update_dpp(0, __float_as_int(v), 0xB1, 0xf, 0xf, false)); }
;     __device__ __forceinline__ void operator()(const f32x4 (&acc)[2][2][4][2], const Unit& u, int wr, int wc, int fr, int fq) const {
;     ...
;                     const int row = row0 + ai * HALF + m * 16; float s = 0.f;
;                     const bf16_t* pa = baseb + (size_t)(row - (odd ? 1 : 0)) * DM + col0 + (odd ? 8 : 0);
;                     const u32x4 la = *(const u32x4*)pa, lb = *(const u32x4*)(pa + DM);
;                     const u32x4 snd = odd ? la : lb; u32x4 rcv;
;                     rcv.x = dpp_xor1(snd.x); rcv.y = dpp_xor1(snd.y); rcv.z = dpp_xor1(snd.z); rcv.w = dpp_xor1(snd.w);
;                     const u32x4 bw0 = odd ? rcv : la, bw1 = odd ? lb : rcv;
;                     u32x4 pw[2];
; #pragma unroll
;                     for (int bj = 0; bj < 2; ++bj) { const u32x4 bw = bj ? bw1 : bw0;
;                         const f32x4 b0 = (f32x4){bf_lo(bw.x), bf_hi(bw.x), bf_lo(bw.y), bf_hi(bw.y)}, b1 = (f32x4){bf_lo(bw.z), bf_hi(bw.z), bf_lo(bw.w), bf_hi(bw.w)};
;                         const f32x4 v0 = acc[ai][bj][m][0] + b0, v1 = acc[ai][bj][m][1] + b1;
;                         pw[bj].x = cvt_pk_bf16(v0[0], v0[1]); pw[bj].y = cvt_pk_bf16(v0[2], v0[3]); pw[bj].z = cvt_pk_bf16(v1[0], v1[1]); pw[bj].w = cvt_pk_bf16(v1[2], v1[3]);
;                         s += (v0[0] * v0[0] + v0[1] * v0[1]) + (v0[2] * v0[2] + v0[3] * v0[3]) + (v1[0] * v1[0] + v1[1] * v1[1]) + (v1[2] * v1[2] + v1[3] * v1[3]); }
;                     store_pair_rows(HB, (size_t)DM, row, col0, fr, pw[0], pw[1]);
;                     s += __shfl_xor(s, 16); s += __shfl_xor(s, 32);
;                     if (fq == 0) unsafeAtomicAdd(ssn + row, s);
.LBB0_1950:
	s_or_b64 exec, exec, s[24:25]
	v_add_u32_e32 v64, 0x80, v152
	v_sub_u32_e32 v66, v64, v158
	v_ashrrev_i32_e32 v67, 31, v66
	v_readlane_b32 s24, v254, 25
	v_lshlrev_b64 v[66:67], 12, v[66:67]
	v_readlane_b32 s25, v254, 26
	s_waitcnt lgkmcnt(0)
	v_mov_b32_e32 v65, v141
	v_mov_b32_e32 v78, v141
	v_lshl_add_u64 v[66:67], s[24:25], 0, v[66:67]
	v_lshl_add_u64 v[66:67], v[150:151], 1, v[66:67]
	v_lshl_add_u64 v[74:75], v[66:67], 0, v[140:141]
	v_add_co_u32_e32 v76, vcc, 0x1000, v74
	v_mov_b32_e32 v80, v141
	s_nop 0
	v_addc_co_u32_e32 v77, vcc, 0, v75, vcc
	global_load_dwordx4 v[66:69], v[74:75], off
	global_load_dwordx4 v[70:73], v[76:77], off
	v_mov_b32_e32 v79, v141
	v_mov_b32_e32 v88, v141
	v_mov_b32_e32 v87, v141
	v_mov_b32_e32 v86, v141
	v_mov_b32_e32 v89, v141
	s_waitcnt vmcnt(0)
	v_cndmask_b32_e64 v81, v69, v73, s[0:1]
	v_cndmask_b32_e64 v83, v67, v71, s[0:1]
	v_cndmask_b32_e64 v84, v66, v70, s[0:1]
	v_cndmask_b32_e64 v82, v68, v72, s[0:1]
	v_mov_b32_dpp v78, v83 quad_perm:[1,0,3,2] row_mask:0xf bank_mask:0xf
	v_mov_b32_dpp v65, v84 quad_perm:[1,0,3,2] row_mask:0xf bank_mask:0xf
	v_mov_b32_dpp v80, v81 quad_perm:[1,0,3,2] row_mask:0xf bank_mask:0xf
	v_mov_b32_dpp v79, v82 quad_perm:[1,0,3,2] row_mask:0xf bank_mask:0xf
	v_cndmask_b32_e64 v81, v80, v69, s[0:1]
	v_cndmask_b32_e64 v69, v78, v67, s[0:1]
	v_cndmask_b32_e64 v67, v65, v66, s[0:1]
	v_cndmask_b32_e64 v84, v71, v78, s[0:1]
	v_cndmask_b32_e64 v65, v70, v65, s[0:1]
	v_cndmask_b32_e64 v82, v79, v68, s[0:1]
	v_cndmask_b32_e64 v85, v73, v80, s[0:1]
	v_cndmask_b32_e64 v83, v72, v79, s[0:1]
	v_lshlrev_b32_e32 v66, 16, v67
	v_and_b32_e32 v67, 0xffff0000, v67
	v_lshlrev_b32_e32 v68, 16, v69
	v_and_b32_e32 v69, 0xffff0000, v69
	v_lshlrev_b32_e32 v72, 16, v81
	v_and_b32_e32 v73, 0xffff0000, v81
	v_lshlrev_b32_e32 v78, 16, v65
	v_and_b32_e32 v79, 0xffff0000, v65
	v_lshlrev_b32_e32 v80, 16, v84
	v_and_b32_e32 v81, 0xffff0000, v84
	v_lshlrev_b32_e32 v70, 16, v82
	v_and_b32_e32 v71, 0xffff0000, v82
	v_lshlrev_b32_e32 v82, 16, v83
	v_and_b32_e32 v83, 0xffff0000, v83
	v_lshlrev_b32_e32 v84, 16, v85
	v_and_b32_e32 v85, 0xffff0000, v85
	v_pk_add_f32 v[62:63], v[62:63], v[68:69]
	v_pk_add_f32 v[60:61], v[60:61], v[66:67]
	v_pk_add_f32 v[54:55], v[54:55], v[80:81]
	v_pk_add_f32 v[52:53], v[52:53], v[78:79]
	v_pk_add_f32 v[58:59], v[58:59], v[72:73]
	v_pk_add_f32 v[56:57], v[56:57], v[70:71]
	v_pk_add_f32 v[50:51], v[50:51], v[84:85]
	v_pk_add_f32 v[48:49], v[48:49], v[82:83]
	v_cvt_pk_bf16_f32 v65, v60, v61
	v_cvt_pk_bf16_f32 v66, v62, v63
	v_cvt_pk_bf16_f32 v67, v56, v57
	v_cvt_pk_bf16_f32 v68, v58, v59
	v_mul_f32_e32 v61, v61, v61
	v_mul_f32_e32 v63, v63, v63
	v_cvt_pk_bf16_f32 v69, v52, v53
	v_cvt_pk_bf16_f32 v70, v54, v55
	v_mul_f32_e32 v53, v53, v53
	v_mul_f32_e32 v55, v55, v55
	v_mul_f32_e32 v57, v57, v57
	v_cvt_pk_bf16_f32 v71, v48, v49
	v_cvt_pk_bf16_f32 v72, v50, v51
	v_mul_f32_e32 v49, v49, v49
	v_mul_f32_e32 v51, v51, v51
	v_fmac_f32_e32 v61, v60, v60
	v_fmac_f32_e32 v63, v62, v62
	v_fmac_f32_e32 v53, v52, v52
	v_fmac_f32_e32 v55, v54, v54
	v_mul_f32_e32 v59, v59, v59
	v_fmac_f32_e32 v57, v56, v56
	v_fmac_f32_e32 v49, v48, v48
	v_fmac_f32_e32 v51, v50, v50
	v_cndmask_b32_e64 v50, v67, v71, s[0:1]
	v_add_f32_e32 v56, v61, v63
	v_add_f32_e32 v53, v53, v55
	v_fmac_f32_e32 v59, v58, v58
	v_mov_b32_dpp v88, v50 quad_perm:[1,0,3,2] row_mask:0xf bank_mask:0xf
	v_add_f32_e32 v50, v57, v56
	v_add_f32_e32 v49, v49, v53
	v_cndmask_b32_e64 v52, v66, v70, s[0:1]
	v_add_f32_e32 v50, v59, v50
	v_add_f32_e32 v49, v51, v49
	v_mov_b32_dpp v87, v52 quad_perm:[1,0,3,2] row_mask:0xf bank_mask:0xf
	v_add_f32_e32 v52, v50, v49
	v_mov_b32_e32 v53, v52
	s_nop 1
	v_permlane16_swap_b32_e32 v53, v52
	v_cndmask_b32_e64 v48, v68, v72, s[0:1]
	v_cndmask_b32_e64 v54, v65, v69, s[0:1]
	v_cndmask_b32_e64 v49, v87, v66, s[0:1]
	v_mov_b32_dpp v89, v48 quad_perm:[1,0,3,2] row_mask:0xf bank_mask:0xf
	v_mov_b32_dpp v86, v54 quad_perm:[1,0,3,2] row_mask:0xf bank_mask:0xf
	v_cndmask_b32_e64 v48, v86, v65, s[0:1]
	v_cndmask_b32_e64 v50, v88, v67, s[0:1]
	v_cndmask_b32_e64 v51, v89, v68, s[0:1]
	global_store_dwordx4 v[74:75], v[48:51], off
	s_waitcnt lgkmcnt(0)
	s_nop 0
	v_add_f32_e32 v48, v52, v53
	v_mov_b32_e32 v49, v48
	s_nop 1
	v_permlane32_swap_b32_e32 v49, v48
	v_cndmask_b32_e64 v50, v69, v86, s[0:1]
	v_cndmask_b32_e64 v51, v70, v87, s[0:1]
	v_cndmask_b32_e64 v52, v71, v88, s[0:1]
	v_cndmask_b32_e64 v53, v72, v89, s[0:1]
	global_store_dwordx4 v[76:77], v[50:53], off
	s_and_saveexec_b64 s[24:25], s[2:3]
	s_cbranch_execz .LBB0_1952
	v_ashrrev_i32_e32 v65, 31, v64
	v_lshl_add_u64 v[50:51], v[64:65], 2, s[10:11]
	s_waitcnt lgkmcnt(0)
	v_add_f32_e32 v48, v48, v49
	global_atomic_add_f32 v[50:51], v48, off
; __device__ __forceinline__ unsigned cvt_pk_bf16(float lo, float hi) { unsigned r; asm volatile("v_cvt_pk_bf16_f32 %0, %1, %2" : "=v"(r) : "v"(lo), "v"(hi)); return r; }
; __device__ __forceinline__ unsigned dpp_xor1(unsigned v) { return (unsigned)__builtin_amdgcn_update_dpp(0, (int)v, 0xB1, 0xf, 0xf, false); }
; __device__ __forceinline__ float dpp_xor1(float v) { return __int_as_float(__builtin_amdgcn_update_dpp(0, __float_as_int(v), 0xB1, 0xf, 0xf, false)); }
;     __device__ __forceinline__ void operator()(const f32x4 (&acc)[2][2][4][2], const Unit& u, int wr, int wc, int fr, int fq) const {
;     ...
;                     const int row = row0 + ai * HALF + m * 16; float s = 0.f;
;                     const bf16_t* pa = baseb + (size_t)(row - (odd ? 1 : 0)) * DM + col0 + (odd ? 8 : 0);
;                     const u32x4 la = *(const u32x4*)pa, lb = *(const u32x4*)(pa + DM);
;                     const u32x4 snd = odd ? la : lb; u32x4 rcv;
;                     rcv.x = dpp_xor1(snd.x); rcv.y = dpp_xor1(snd.y); rcv.z = dpp_xor1(snd.z); rcv.w = dpp_xor1(snd.w);
;                     const u32x4 bw0 = odd ? rcv : la, bw1 = odd ? lb : rcv;
;                     u32x4 pw[2];
; #pragma unroll
;                     for (int bj = 0; bj < 2; ++bj) { const u32x4 bw = bj ? bw1 : bw0;
;                         const f32x4 b0 = (f32x4){bf_lo(bw.x), bf_hi(bw.x), bf_lo(bw.y), bf_hi(bw.y)}, b1 = (f32x4){bf_lo(bw.z), bf_hi(bw.z), bf_lo(bw.w), bf_hi(bw.w)};
;                         const f32x4 v0 = acc[ai][bj][m][0] + b0, v1 = acc[ai][bj][m][1] + b1;
;                         pw[bj].x = cvt_pk_bf16(v0[0], v0[1]); pw[bj].y = cvt_pk_bf16(v0[2], v0[3]); pw[bj].z = cvt_pk_bf16(v1[0], v1[1]); pw[bj].w = cvt_pk_bf16(v1[2], v1[3]);
;                         s += (v0[0] * v0[0] + v0[1] * v0[1]) + (v0[2] * v0[2] + v0[3] * v0[3]) + (v1[0] * v1[0] + v1[1] * v1[1]) + (v1[2] * v1[2] + v1[3] * v1[3]); }
;                     store_pair_rows(HB, (size_t)DM, row, col0, fr, pw[0], pw[1]);
;                     s += __shfl_xor(s, 16); s += __shfl_xor(s, 32);
;                     if (fq == 0) unsafeAtomicAdd(ssn + row, s);
.LBB0_1952:
	s_or_b64 exec, exec, s[24:25]
	v_add_u32_e32 v48, 0x90, v152
	v_sub_u32_e32 v50, v48, v158
	v_ashrrev_i32_e32 v51, 31, v50
	v_readlane_b32 s24, v254, 25
	v_lshlrev_b64 v[50:51], 12, v[50:51]
	v_readlane_b32 s25, v254, 26
	s_waitcnt lgkmcnt(0)
	v_mov_b32_e32 v49, v141
	v_mov_b32_e32 v62, v141
	v_lshl_add_u64 v[50:51], s[24:25], 0, v[50:51]
	v_lshl_add_u64 v[50:51], v[150:151], 1, v[50:51]
	v_lshl_add_u64 v[58:59], v[50:51], 0, v[140:141]
	v_add_co_u32_e32 v60, vcc, 0x1000, v58
	v_mov_b32_e32 v64, v141
	s_nop 0
	v_addc_co_u32_e32 v61, vcc, 0, v59, vcc
	global_load_dwordx4 v[50:53], v[58:59], off
	global_load_dwordx4 v[54:57], v[60:61], off
	v_mov_b32_e32 v63, v141
	v_mov_b32_e32 v72, v141
	v_mov_b32_e32 v71, v141
	v_mov_b32_e32 v70, v141
	v_mov_b32_e32 v73, v141
	s_waitcnt vmcnt(0)
	v_cndmask_b32_e64 v65, v53, v57, s[0:1]
	v_cndmask_b32_e64 v67, v51, v55, s[0:1]
	v_cndmask_b32_e64 v68, v50, v54, s[0:1]
	v_cndmask_b32_e64 v66, v52, v56, s[0:1]
	v_mov_b32_dpp v62, v67 quad_perm:[1,0,3,2] row_mask:0xf bank_mask:0xf
	v_mov_b32_dpp v49, v68 quad_perm:[1,0,3,2] row_mask:0xf bank_mask:0xf
	v_mov_b32_dpp v64, v65 quad_perm:[1,0,3,2] row_mask:0xf bank_mask:0xf
	v_mov_b32_dpp v63, v66 quad_perm:[1,0,3,2] row_mask:0xf bank_mask:0xf
	v_cndmask_b32_e64 v65, v64, v53, s[0:1]
	v_cndmask_b32_e64 v53, v62, v51, s[0:1]
	v_cndmask_b32_e64 v51, v49, v50, s[0:1]
	v_cndmask_b32_e64 v68, v55, v62, s[0:1]
	v_cndmask_b32_e64 v49, v54, v49, s[0:1]
	v_cndmask_b32_e64 v66, v63, v52, s[0:1]
	v_cndmask_b32_e64 v69, v57, v64, s[0:1]
	v_cndmask_b32_e64 v67, v56, v63, s[0:1]
	v_lshlrev_b32_e32 v50, 16, v51
	v_and_b32_e32 v51, 0xffff0000, v51
	v_lshlrev_b32_e32 v52, 16, v53
	v_and_b32_e32 v53, 0xffff0000, v53
	v_lshlrev_b32_e32 v56, 16, v65
	v_and_b32_e32 v57, 0xffff0000, v65
	v_lshlrev_b32_e32 v62, 16, v49
	v_and_b32_e32 v63, 0xffff0000, v49
	v_lshlrev_b32_e32 v64, 16, v68
	v_and_b32_e32 v65, 0xffff0000, v68
	v_lshlrev_b32_e32 v54, 16, v66
	v_and_b32_e32 v55, 0xffff0000, v66
	v_lshlrev_b32_e32 v66, 16, v67
	v_and_b32_e32 v67, 0xffff0000, v67
	v_lshlrev_b32_e32 v68, 16, v69
	v_and_b32_e32 v69, 0xffff0000, v69
	v_pk_add_f32 v[46:47], v[46:47], v[52:53]
	v_pk_add_f32 v[44:45], v[44:45], v[50:51]
	v_pk_add_f32 v[38:39], v[38:39], v[64:65]
	v_pk_add_f32 v[36:37], v[36:37], v[62:63]
	v_pk_add_f32 v[42:43], v[42:43], v[56:57]
	v_pk_add_f32 v[40:41], v[40:41], v[54:55]
	v_pk_add_f32 v[34:35], v[34:35], v[68:69]
	v_pk_add_f32 v[32:33], v[32:33], v[66:67]
	v_cvt_pk_bf16_f32 v49, v44, v45
	v_cvt_pk_bf16_f32 v50, v46, v47
	v_cvt_pk_bf16_f32 v51, v40, v41
	v_cvt_pk_bf16_f32 v52, v42, v43
	v_mul_f32_e32 v45, v45, v45
	v_mul_f32_e32 v47, v47, v47
	v_cvt_pk_bf16_f32 v53, v36, v37
	v_cvt_pk_bf16_f32 v54, v38, v39
	v_mul_f32_e32 v37, v37, v37
	v_mul_f32_e32 v39, v39, v39
	v_mul_f32_e32 v41, v41, v41
	v_cvt_pk_bf16_f32 v55, v32, v33
	v_cvt_pk_bf16_f32 v56, v34, v35
	v_mul_f32_e32 v33, v33, v33
	v_mul_f32_e32 v35, v35, v35
	v_fmac_f32_e32 v45, v44, v44
	v_fmac_f32_e32 v47, v46, v46
	v_fmac_f32_e32 v37, v36, v36
	v_fmac_f32_e32 v39, v38, v38
	v_mul_f32_e32 v43, v43, v43
	v_fmac_f32_e32 v41, v40, v40
	v_fmac_f32_e32 v33, v32, v32
	v_fmac_f32_e32 v35, v34, v34
	v_cndmask_b32_e64 v34, v51, v55, s[0:1]
	v_add_f32_e32 v40, v45, v47
	v_add_f32_e32 v37, v37, v39
	v_fmac_f32_e32 v43, v42, v42
	v_mov_b32_dpp v72, v34 quad_perm:[1,0,3,2] row_mask:0xf bank_mask:0xf
	v_add_f32_e32 v34, v41, v40
	v_add_f32_e32 v33, v33, v37
	v_cndmask_b32_e64 v36, v50, v54, s[0:1]
	v_add_f32_e32 v34, v43, v34
	v_add_f32_e32 v33, v35, v33
	v_mov_b32_dpp v71, v36 quad_perm:[1,0,3,2] row_mask:0xf bank_mask:0xf
	v_add_f32_e32 v36, v34, v33
	v_mov_b32_e32 v37, v36
	s_nop 1
	v_permlane16_swap_b32_e32 v37, v36
	v_cndmask_b32_e64 v32, v52, v56, s[0:1]
	v_cndmask_b32_e64 v38, v49, v53, s[0:1]
	v_cndmask_b32_e64 v33, v71, v50, s[0:1]
	v_mov_b32_dpp v73, v32 quad_perm:[1,0,3,2] row_mask:0xf bank_mask:0xf
	v_mov_b32_dpp v70, v38 quad_perm:[1,0,3,2] row_mask:0xf bank_mask:0xf
	v_cndmask_b32_e64 v32, v70, v49, s[0:1]
	v_cndmask_b32_e64 v34, v72, v51, s[0:1]
	v_cndmask_b32_e64 v35, v73, v52, s[0:1]
	global_store_dwordx4 v[58:59], v[32:35], off
	s_waitcnt lgkmcnt(0)
	s_nop 0
	v_add_f32_e32 v32, v36, v37
	v_mov_b32_e32 v33, v32
	s_nop 1
	v_permlane32_swap_b32_e32 v33, v32
	v_cndmask_b32_e64 v34, v53, v70, s[0:1]
	v_cndmask_b32_e64 v35, v54, v71, s[0:1]
	v_cndmask_b32_e64 v36, v55, v72, s[0:1]
	v_cndmask_b32_e64 v37, v56, v73, s[0:1]
	global_store_dwordx4 v[60:61], v[34:37], off
	s_and_saveexec_b64 s[24:25], s[2:3]
	s_cbranch_execz .LBB0_1954
	v_ashrrev_i32_e32 v49, 31, v48
	v_lshl_add_u64 v[34:35], v[48:49], 2, s[10:11]
	s_waitcnt lgkmcnt(0)
	v_add_f32_e32 v32, v32, v33
	global_atomic_add_f32 v[34:35], v32, off
; __device__ __forceinline__ unsigned cvt_pk_bf16(float lo, float hi) { unsigned r; asm volatile("v_cvt_pk_bf16_f32 %0, %1, %2" : "=v"(r) : "v"(lo), "v"(hi)); return r; }
; __device__ __forceinline__ unsigned dpp_xor1(unsigned v) { return (unsigned)__builtin_amdgcn_update_dpp(0, (int)v, 0xB1, 0xf, 0xf, false); }
; __device__ __forceinline__ float dpp_xor1(float v) { return __int_as_float(__builtin_amdgcn_update_dpp(0, __float_as_int(v), 0xB1, 0xf, 0xf, false)); }
;     __device__ __forceinline__ void operator()(const f32x4 (&acc)[2][2][4][2], const Unit& u, int wr, int wc, int fr, int fq) const {
;     ...
;                     const int row = row0 + ai * HALF + m * 16; float s = 0.f;
;                     const bf16_t* pa = baseb + (size_t)(row - (odd ? 1 : 0)) * DM + col0 + (odd ? 8 : 0);
;                     const u32x4 la = *(const u32x4*)pa, lb = *(const u32x4*)(pa + DM);
;                     const u32x4 snd = odd ? la : lb; u32x4 rcv;
;                     rcv.x = dpp_xor1(snd.x); rcv.y = dpp_xor1(snd.y); rcv.z = dpp_xor1(snd.z); rcv.w = dpp_xor1(snd.w);
;                     const u32x4 bw0 = odd ? rcv : la, bw1 = odd ? lb : rcv;
;                     u32x4 pw[2];
; #pragma unroll
;                     for (int bj = 0; bj < 2; ++bj) { const u32x4 bw = bj ? bw1 : bw0;
;                         const f32x4 b0 = (f32x4){bf_lo(bw.x), bf_hi(bw.x), bf_lo(bw.y), bf_hi(bw.y)}, b1 = (f32x4){bf_lo(bw.z), bf_hi(bw.z), bf_lo(bw.w), bf_hi(bw.w)};
;                         const f32x4 v0 = acc[ai][bj][m][0] + b0, v1 = acc[ai][bj][m][1] + b1;
;                         pw[bj].x = cvt_pk_bf16(v0[0], v0[1]); pw[bj].y = cvt_pk_bf16(v0[2], v0[3]); pw[bj].z = cvt_pk_bf16(v1[0], v1[1]); pw[bj].w = cvt_pk_bf16(v1[2], v1[3]);
;                         s += (v0[0] * v0[0] + v0[1] * v0[1]) + (v0[2] * v0[2] + v0[3] * v0[3]) + (v1[0] * v1[0] + v1[1] * v1[1]) + (v1[2] * v1[2] + v1[3] * v1[3]); }
;                     store_pair_rows(HB, (size_t)DM, row, col0, fr, pw[0], pw[1]);
;                     s += __shfl_xor(s, 16); s += __shfl_xor(s, 32);
;                     if (fq == 0) unsafeAtomicAdd(ssn + row, s);
.LBB0_1954:
	s_or_b64 exec, exec, s[24:25]
	v_add_u32_e32 v32, 0xa0, v152
	v_sub_u32_e32 v34, v32, v158
	v_ashrrev_i32_e32 v35, 31, v34
	v_readlane_b32 s24, v254, 25
	v_lshlrev_b64 v[34:35], 12, v[34:35]
	v_readlane_b32 s25, v254, 26
	s_waitcnt lgkmcnt(0)
	v_mov_b32_e32 v33, v141
	v_mov_b32_e32 v46, v141
	v_lshl_add_u64 v[34:35], s[24:25], 0, v[34:35]
	v_lshl_add_u64 v[34:35], v[150:151], 1, v[34:35]
	v_lshl_add_u64 v[42:43], v[34:35], 0, v[140:141]
	v_add_co_u32_e32 v44, vcc, 0x1000, v42
	v_mov_b32_e32 v48, v141
	s_nop 0
	v_addc_co_u32_e32 v45, vcc, 0, v43, vcc
	global_load_dwordx4 v[34:37], v[42:43], off
	global_load_dwordx4 v[38:41], v[44:45], off
	v_mov_b32_e32 v47, v141
	v_mov_b32_e32 v56, v141
	v_mov_b32_e32 v55, v141
	v_mov_b32_e32 v54, v141
	v_mov_b32_e32 v57, v141
	s_waitcnt vmcnt(0)
	v_cndmask_b32_e64 v49, v37, v41, s[0:1]
	v_cndmask_b32_e64 v51, v35, v39, s[0:1]
	v_cndmask_b32_e64 v52, v34, v38, s[0:1]
	v_cndmask_b32_e64 v50, v36, v40, s[0:1]
	v_mov_b32_dpp v46, v51 quad_perm:[1,0,3,2] row_mask:0xf bank_mask:0xf
	v_mov_b32_dpp v33, v52 quad_perm:[1,0,3,2] row_mask:0xf bank_mask:0xf
	v_mov_b32_dpp v48, v49 quad_perm:[1,0,3,2] row_mask:0xf bank_mask:0xf
	v_mov_b32_dpp v47, v50 quad_perm:[1,0,3,2] row_mask:0xf bank_mask:0xf
	v_cndmask_b32_e64 v49, v48, v37, s[0:1]
	v_cndmask_b32_e64 v37, v46, v35, s[0:1]
	v_cndmask_b32_e64 v35, v33, v34, s[0:1]
	v_cndmask_b32_e64 v52, v39, v46, s[0:1]
	v_cndmask_b32_e64 v33, v38, v33, s[0:1]
	v_cndmask_b32_e64 v50, v47, v36, s[0:1]
	v_cndmask_b32_e64 v53, v41, v48, s[0:1]
	v_cndmask_b32_e64 v51, v40, v47, s[0:1]
	v_lshlrev_b32_e32 v34, 16, v35
	v_and_b32_e32 v35, 0xffff0000, v35
	v_lshlrev_b32_e32 v36, 16, v37
	v_and_b32_e32 v37, 0xffff0000, v37
	v_lshlrev_b32_e32 v40, 16, v49
	v_and_b32_e32 v41, 0xffff0000, v49
	v_lshlrev_b32_e32 v46, 16, v33
	v_and_b32_e32 v47, 0xffff0000, v33
	v_lshlrev_b32_e32 v48, 16, v52
	v_and_b32_e32 v49, 0xffff0000, v52
	v_lshlrev_b32_e32 v38, 16, v50
	v_and_b32_e32 v39, 0xffff0000, v50
	v_lshlrev_b32_e32 v50, 16, v51
	v_and_b32_e32 v51, 0xffff0000, v51
	v_lshlrev_b32_e32 v52, 16, v53
	v_and_b32_e32 v53, 0xffff0000, v53
	v_pk_add_f32 v[30:31], v[30:31], v[36:37]
	v_pk_add_f32 v[28:29], v[28:29], v[34:35]
	v_pk_add_f32 v[22:23], v[22:23], v[48:49]
	v_pk_add_f32 v[20:21], v[20:21], v[46:47]
	v_pk_add_f32 v[26:27], v[26:27], v[40:41]
	v_pk_add_f32 v[24:25], v[24:25], v[38:39]
	v_pk_add_f32 v[18:19], v[18:19], v[52:53]
	v_pk_add_f32 v[16:17], v[16:17], v[50:51]
	v_cvt_pk_bf16_f32 v33, v28, v29
	v_cvt_pk_bf16_f32 v34, v30, v31
	v_cvt_pk_bf16_f32 v35, v24, v25
	v_cvt_pk_bf16_f32 v36, v26, v27
	v_mul_f32_e32 v29, v29, v29
	v_mul_f32_e32 v31, v31, v31
	v_cvt_pk_bf16_f32 v37, v20, v21
	v_cvt_pk_bf16_f32 v38, v22, v23
	v_mul_f32_e32 v21, v21, v21
	v_mul_f32_e32 v23, v23, v23
	v_mul_f32_e32 v25, v25, v25
	v_cvt_pk_bf16_f32 v39, v16, v17
	v_cvt_pk_bf16_f32 v40, v18, v19
	v_mul_f32_e32 v17, v17, v17
	v_mul_f32_e32 v19, v19, v19
	v_fmac_f32_e32 v29, v28, v28
	v_fmac_f32_e32 v31, v30, v30
	v_fmac_f32_e32 v21, v20, v20
	v_fmac_f32_e32 v23, v22, v22
	v_mul_f32_e32 v27, v27, v27
	v_fmac_f32_e32 v25, v24, v24
	v_fmac_f32_e32 v17, v16, v16
	v_fmac_f32_e32 v19, v18, v18
	v_cndmask_b32_e64 v18, v35, v39, s[0:1]
	v_add_f32_e32 v24, v29, v31
	v_add_f32_e32 v21, v21, v23
	v_fmac_f32_e32 v27, v26, v26
	v_mov_b32_dpp v56, v18 quad_perm:[1,0,3,2] row_mask:0xf bank_mask:0xf
	v_add_f32_e32 v18, v25, v24
	v_add_f32_e32 v17, v17, v21
	v_cndmask_b32_e64 v20, v34, v38, s[0:1]
	v_add_f32_e32 v18, v27, v18
	v_add_f32_e32 v17, v19, v17
	v_mov_b32_dpp v55, v20 quad_perm:[1,0,3,2] row_mask:0xf bank_mask:0xf
	v_add_f32_e32 v20, v18, v17
	v_mov_b32_e32 v21, v20
	s_nop 1
	v_permlane16_swap_b32_e32 v21, v20
	v_cndmask_b32_e64 v16, v36, v40, s[0:1]
	v_cndmask_b32_e64 v22, v33, v37, s[0:1]
	v_cndmask_b32_e64 v17, v55, v34, s[0:1]
	v_mov_b32_dpp v57, v16 quad_perm:[1,0,3,2] row_mask:0xf bank_mask:0xf
	v_mov_b32_dpp v54, v22 quad_perm:[1,0,3,2] row_mask:0xf bank_mask:0xf
	v_cndmask_b32_e64 v16, v54, v33, s[0:1]
	v_cndmask_b32_e64 v18, v56, v35, s[0:1]
	v_cndmask_b32_e64 v19, v57, v36, s[0:1]
	global_store_dwordx4 v[42:43], v[16:19], off
	s_waitcnt lgkmcnt(0)
	s_nop 0
	v_add_f32_e32 v16, v20, v21
	v_mov_b32_e32 v17, v16
	s_nop 1
	v_permlane32_swap_b32_e32 v17, v16
	v_cndmask_b32_e64 v18, v37, v54, s[0:1]
	v_cndmask_b32_e64 v19, v38, v55, s[0:1]
	v_cndmask_b32_e64 v20, v39, v56, s[0:1]
	v_cndmask_b32_e64 v21, v40, v57, s[0:1]
	global_store_dwordx4 v[44:45], v[18:21], off
	s_and_saveexec_b64 s[24:25], s[2:3]
	s_cbranch_execz .LBB0_1956
	v_ashrrev_i32_e32 v33, 31, v32
	v_lshl_add_u64 v[18:19], v[32:33], 2, s[10:11]
	s_waitcnt lgkmcnt(0)
	v_add_f32_e32 v16, v16, v17
	global_atomic_add_f32 v[18:19], v16, off
; __device__ __forceinline__ unsigned cvt_pk_bf16(float lo, float hi) { unsigned r; asm volatile("v_cvt_pk_bf16_f32 %0, %1, %2" : "=v"(r) : "v"(lo), "v"(hi)); return r; }
; __device__ __forceinline__ unsigned dpp_xor1(unsigned v) { return (unsigned)__builtin_amdgcn_update_dpp(0, (int)v, 0xB1, 0xf, 0xf, false); }
; __device__ __forceinline__ float dpp_xor1(float v) { return __int_as_float(__builtin_amdgcn_update_dpp(0, __float_as_int(v), 0xB1, 0xf, 0xf, false)); }
;     __device__ __forceinline__ void operator()(const f32x4 (&acc)[2][2][4][2], const Unit& u, int wr, int wc, int fr, int fq) const {
;     ...
;                     const int row = row0 + ai * HALF + m * 16; float s = 0.f;
;                     const bf16_t* pa = baseb + (size_t)(row - (odd ? 1 : 0)) * DM + col0 + (odd ? 8 : 0);
;                     const u32x4 la = *(const u32x4*)pa, lb = *(const u32x4*)(pa + DM);
;                     const u32x4 snd = odd ? la : lb; u32x4 rcv;
;                     rcv.x = dpp_xor1(snd.x); rcv.y = dpp_xor1(snd.y); rcv.z = dpp_xor1(snd.z); rcv.w = dpp_xor1(snd.w);
;                     const u32x4 bw0 = odd ? rcv : la, bw1 = odd ? lb : rcv;
;                     u32x4 pw[2];
; #pragma unroll
;                     for (int bj = 0; bj < 2; ++bj) { const u32x4 bw = bj ? bw1 : bw0;
;                         const f32x4 b0 = (f32x4){bf_lo(bw.x), bf_hi(bw.x), bf_lo(bw.y), bf_hi(bw.y)}, b1 = (f32x4){bf_lo(bw.z), bf_hi(bw.z), bf_lo(bw.w), bf_hi(bw.w)};
;                         const f32x4 v0 = acc[ai][bj][m][0] + b0, v1 = acc[ai][bj][m][1] + b1;
;                         pw[bj].x = cvt_pk_bf16(v0[0], v0[1]); pw[bj].y = cvt_pk_bf16(v0[2], v0[3]); pw[bj].z = cvt_pk_bf16(v1[0], v1[1]); pw[bj].w = cvt_pk_bf16(v1[2], v1[3]);
;                         s += (v0[0] * v0[0] + v0[1] * v0[1]) + (v0[2] * v0[2] + v0[3] * v0[3]) + (v1[0] * v1[0] + v1[1] * v1[1]) + (v1[2] * v1[2] + v1[3] * v1[3]); }
;                     store_pair_rows(HB, (size_t)DM, row, col0, fr, pw[0], pw[1]);
;                     s += __shfl_xor(s, 16); s += __shfl_xor(s, 32);
;                     if (fq == 0) unsafeAtomicAdd(ssn + row, s);
.LBB0_1956:
	s_or_b64 exec, exec, s[24:25]
	v_add_u32_e32 v16, 0xb0, v152
	v_sub_u32_e32 v18, v16, v158
	v_ashrrev_i32_e32 v19, 31, v18
	v_readlane_b32 s24, v254, 25
	v_lshlrev_b64 v[18:19], 12, v[18:19]
	v_readlane_b32 s25, v254, 26
	s_waitcnt lgkmcnt(0)
	v_mov_b32_e32 v17, v141
	v_mov_b32_e32 v30, v141
	v_lshl_add_u64 v[18:19], s[24:25], 0, v[18:19]
	v_lshl_add_u64 v[18:19], v[150:151], 1, v[18:19]
	v_lshl_add_u64 v[26:27], v[18:19], 0, v[140:141]
	v_add_co_u32_e32 v28, vcc, 0x1000, v26
	v_mov_b32_e32 v32, v141
	s_nop 0
	v_addc_co_u32_e32 v29, vcc, 0, v27, vcc
	global_load_dwordx4 v[18:21], v[26:27], off
	global_load_dwordx4 v[22:25], v[28:29], off
	v_mov_b32_e32 v31, v141
	v_mov_b32_e32 v40, v141
	v_mov_b32_e32 v39, v141
	v_mov_b32_e32 v38, v141
	v_mov_b32_e32 v41, v141
	s_waitcnt vmcnt(0)
	v_cndmask_b32_e64 v33, v21, v25, s[0:1]
	v_cndmask_b32_e64 v35, v19, v23, s[0:1]
	v_cndmask_b32_e64 v36, v18, v22, s[0:1]
	v_cndmask_b32_e64 v34, v20, v24, s[0:1]
	v_mov_b32_dpp v30, v35 quad_perm:[1,0,3,2] row_mask:0xf bank_mask:0xf
	v_mov_b32_dpp v17, v36 quad_perm:[1,0,3,2] row_mask:0xf bank_mask:0xf
	v_mov_b32_dpp v32, v33 quad_perm:[1,0,3,2] row_mask:0xf bank_mask:0xf
	v_mov_b32_dpp v31, v34 quad_perm:[1,0,3,2] row_mask:0xf bank_mask:0xf
	v_cndmask_b32_e64 v33, v32, v21, s[0:1]
	v_cndmask_b32_e64 v21, v30, v19, s[0:1]
	v_cndmask_b32_e64 v19, v17, v18, s[0:1]
	v_cndmask_b32_e64 v36, v23, v30, s[0:1]
	v_cndmask_b32_e64 v17, v22, v17, s[0:1]
	v_cndmask_b32_e64 v34, v31, v20, s[0:1]
	v_cndmask_b32_e64 v37, v25, v32, s[0:1]
	v_cndmask_b32_e64 v35, v24, v31, s[0:1]
	v_lshlrev_b32_e32 v18, 16, v19
	v_and_b32_e32 v19, 0xffff0000, v19
	v_lshlrev_b32_e32 v20, 16, v21
	v_and_b32_e32 v21, 0xffff0000, v21
	v_lshlrev_b32_e32 v24, 16, v33
	v_and_b32_e32 v25, 0xffff0000, v33
	v_lshlrev_b32_e32 v30, 16, v17
	v_and_b32_e32 v31, 0xffff0000, v17
	v_lshlrev_b32_e32 v32, 16, v36
	v_and_b32_e32 v33, 0xffff0000, v36
	v_lshlrev_b32_e32 v22, 16, v34
	v_and_b32_e32 v23, 0xffff0000, v34
	v_lshlrev_b32_e32 v34, 16, v35
	v_and_b32_e32 v35, 0xffff0000, v35
	v_lshlrev_b32_e32 v36, 16, v37
	v_and_b32_e32 v37, 0xffff0000, v37
	v_pk_add_f32 v[14:15], v[14:15], v[20:21]
	v_pk_add_f32 v[12:13], v[12:13], v[18:19]
	v_pk_add_f32 v[6:7], v[6:7], v[32:33]
	v_pk_add_f32 v[4:5], v[4:5], v[30:31]
	v_pk_add_f32 v[10:11], v[10:11], v[24:25]
	v_pk_add_f32 v[8:9], v[8:9], v[22:23]
	v_pk_add_f32 v[2:3], v[2:3], v[36:37]
	v_pk_add_f32 v[0:1], v[0:1], v[34:35]
	v_cvt_pk_bf16_f32 v17, v12, v13
	v_cvt_pk_bf16_f32 v18, v14, v15
	v_cvt_pk_bf16_f32 v19, v8, v9
	v_cvt_pk_bf16_f32 v20, v10, v11
	v_mul_f32_e32 v13, v13, v13
	v_mul_f32_e32 v15, v15, v15
	v_cvt_pk_bf16_f32 v21, v4, v5
	v_cvt_pk_bf16_f32 v22, v6, v7
	v_mul_f32_e32 v5, v5, v5
	v_mul_f32_e32 v7, v7, v7
	v_mul_f32_e32 v9, v9, v9
	v_cvt_pk_bf16_f32 v23, v0, v1
	v_cvt_pk_bf16_f32 v24, v2, v3
	v_mul_f32_e32 v1, v1, v1
	v_mul_f32_e32 v3, v3, v3
	v_fmac_f32_e32 v13, v12, v12
	v_fmac_f32_e32 v15, v14, v14
	v_fmac_f32_e32 v5, v4, v4
	v_fmac_f32_e32 v7, v6, v6
	v_mul_f32_e32 v11, v11, v11
	v_fmac_f32_e32 v9, v8, v8
	v_fmac_f32_e32 v1, v0, v0
	v_fmac_f32_e32 v3, v2, v2
	v_cndmask_b32_e64 v2, v19, v23, s[0:1]
	v_add_f32_e32 v8, v13, v15
	v_add_f32_e32 v5, v5, v7
	v_fmac_f32_e32 v11, v10, v10
	v_mov_b32_dpp v40, v2 quad_perm:[1,0,3,2] row_mask:0xf bank_mask:0xf
	v_add_f32_e32 v2, v9, v8
	v_add_f32_e32 v1, v1, v5
	v_cndmask_b32_e64 v4, v18, v22, s[0:1]
	v_add_f32_e32 v2, v11, v2
	v_add_f32_e32 v1, v3, v1
	v_mov_b32_dpp v39, v4 quad_perm:[1,0,3,2] row_mask:0xf bank_mask:0xf
	v_add_f32_e32 v4, v2, v1
	v_mov_b32_e32 v5, v4
	s_nop 1
	v_permlane16_swap_b32_e32 v5, v4
	v_cndmask_b32_e64 v0, v20, v24, s[0:1]
	v_cndmask_b32_e64 v6, v17, v21, s[0:1]
	v_cndmask_b32_e64 v1, v39, v18, s[0:1]
	v_mov_b32_dpp v41, v0 quad_perm:[1,0,3,2] row_mask:0xf bank_mask:0xf
	v_mov_b32_dpp v38, v6 quad_perm:[1,0,3,2] row_mask:0xf bank_mask:0xf
	v_cndmask_b32_e64 v0, v38, v17, s[0:1]
	v_cndmask_b32_e64 v2, v40, v19, s[0:1]
	v_cndmask_b32_e64 v3, v41, v20, s[0:1]
	global_store_dwordx4 v[26:27], v[0:3], off
	s_waitcnt lgkmcnt(0)
	s_nop 0
	v_add_f32_e32 v0, v4, v5
	v_mov_b32_e32 v1, v0
	s_nop 1
	v_permlane32_swap_b32_e32 v1, v0
	v_cndmask_b32_e64 v2, v21, v38, s[0:1]
	v_cndmask_b32_e64 v3, v22, v39, s[0:1]
	v_cndmask_b32_e64 v4, v23, v40, s[0:1]
	v_cndmask_b32_e64 v5, v24, v41, s[0:1]
	global_store_dwordx4 v[28:29], v[2:5], off
	s_and_saveexec_b64 s[24:25], s[2:3]
	s_cbranch_execz .LBB0_1958
	v_ashrrev_i32_e32 v17, 31, v16
	v_lshl_add_u64 v[2:3], v[16:17], 2, s[10:11]
	s_waitcnt lgkmcnt(0)
	v_add_f32_e32 v0, v0, v1
	global_atomic_add_f32 v[2:3], v0, off

; #define GAS __attribute__((address_space(1)))
;     __device__ __forceinline__ void operator()(const f32x4 (&acc)[2][2][4][2], const Unit& u, int wr, int wc, int fr, int fq) const {
;     ...
;         const int row0 = u.pm * BM + wr * 64 + fr, col0 = u.pn * BM + wc * 32 + 8 * fq; const bool odd = (fr & 1) != 0;
; #pragma unroll
;         for (int ai = 0; ai < 2; ++ai)
; #pragma unroll
;             for (int m = 0; m < 4; ++m) {
;                 const int row = row0 + ai * HALF + m * 16; float s = 0.f;
;                 const size_t off = (size_t)row * DM + col0;
;                 const size_t offp = (size_t)(row - (odd ? 1 : 0)) * DM + col0 + (odd ? 4 : 0);
; #pragma unroll
;                 for (int bj = 0; bj < 2; ++bj) {
;                     f32x4 b0, b1;
;                     if constexpr (BASE_F32) { const f32x4 la = *(const GAS f32x4*)(basef + offp + bj * HALF), lb = *(const GAS f32x4*)(basef + offp + DM + bj * HALF);
;                         const f32x4 snd = odd ? la : lb; f32x4 rcv; rcv[0] = dpp_xor1(snd[0]); rcv[1] = dpp_xor1(snd[1]); rcv[2] = dpp_xor1(snd[2]); rcv[3] = dpp_xor1(snd[3]);
;                         b0 = odd ? rcv : la; b1 = odd ? lb : rcv; }
;                     else { const u32x4 bw = *(const u32x4*)(baseb + off + bj * HALF);
;                         b0 = (f32x4){bf_lo(bw.x), bf_hi(bw.x), bf_lo(bw.y), bf_hi(bw.y)}; b1 = (f32x4){bf_lo(bw.z), bf_hi(bw.z), bf_lo(bw.w), bf_hi(bw.w)}; }
;                     const f32x4 v0 = acc[ai][bj][m][0] + b0, v1 = acc[ai][bj][m][1] + b1;
;                     if constexpr (OUT_F32) { const f32x4 snd = odd ? v0 : v1; f32x4 rcv; rcv[0] = dpp_xor1(snd[0]); rcv[1] = dpp_xor1(snd[1]); rcv[2] = dpp_xor1(snd[2]); rcv[3] = dpp_xor1(snd[3]);
;                         *(f32x4*)(H + offp + bj * HALF) = odd ? rcv : v0; *(f32x4*)(H + offp + DM + bj * HALF) = odd ? v1 : rcv; }
;                     else { u32x4 w; w.x = cvt_pk_bf16(v0[0], v0[1]); w.y = cvt_pk_bf16(v0[2], v0[3]); w.z = cvt_pk_bf16(v1[0], v1[1]); w.w = cvt_pk_bf16(v1[2], v1[3]);
;                         *(u32x4*)(HB + off + bj * HALF) = w; }
;                     s += (v0[0] * v0[0] + v0[1] * v0[1]) + (v0[2] * v0[2] + v0[3] * v0[3]) + (v1[0] * v1[0] + v1[1] * v1[1]) + (v1[2] * v1[2] + v1[3] * v1[3]);
;                 }
;                 s += __shfl_xor(s, 16); s += __shfl_xor(s, 32);
;                 if (fq == 0) unsafeAtomicAdd(ssn + row, s);
.LBB0_2190:
	v_lshl_add_u32 v148, s44, 8, v137
	v_ashrrev_i32_e32 v149, 31, v148
	v_readlane_b32 s20, v254, 25
	v_lshl_or_b32 v146, s45, 8, v154
	v_lshlrev_b64 v[150:151], 12, v[148:149]
	v_readlane_b32 s21, v254, 26
	v_ashrrev_i32_e32 v147, 31, v146
	v_sub_u32_e32 v166, v148, v153
	v_lshl_add_u64 v[150:151], s[20:21], 0, v[150:151]
	v_lshl_add_u64 v[164:165], v[146:147], 1, v[150:151]
	global_load_dwordx4 v[160:163], v[164:165], off
	v_ashrrev_i32_e32 v167, 31, v166
	v_readlane_b32 s20, v254, 7
	v_lshlrev_b64 v[166:167], 13, v[166:167]
	v_readlane_b32 s21, v254, 8
	v_mov_b32_e32 v159, 0
	v_mov_b32_e32 v174, 0
	v_mov_b32_e32 v175, 0
	v_mov_b32_e32 v176, 0
	v_or_b32_e32 v150, v146, v136
	v_mov_b32_e32 v151, v147
	v_lshl_add_u64 v[166:167], s[20:21], 0, v[166:167]
	v_lshl_add_u64 v[166:167], v[150:151], 2, v[166:167]
	v_add_co_u32_e32 v168, vcc, s35, v166
	v_readlane_b32 s22, v254, 9
	s_nop 0
	v_addc_co_u32_e32 v169, vcc, 0, v167, vcc
	v_readlane_b32 s23, v254, 10
	s_waitcnt vmcnt(0)
	v_lshlrev_b32_e32 v170, 16, v160
	v_and_b32_e32 v171, 0xffff0000, v160
	v_lshlrev_b32_e32 v160, 16, v161
	v_and_b32_e32 v161, 0xffff0000, v161
	v_lshlrev_b32_e32 v172, 16, v162
	v_and_b32_e32 v173, 0xffff0000, v162
	v_lshlrev_b32_e32 v162, 16, v163
	v_and_b32_e32 v163, 0xffff0000, v163
	v_pk_add_f32 v[170:171], v[124:125], v[170:171]
	v_pk_add_f32 v[160:161], v[126:127], v[160:161]
	v_pk_add_f32 v[172:173], v[120:121], v[172:173]
	v_pk_add_f32 v[162:163], v[122:123], v[162:163]
	v_cndmask_b32_e64 v122, v171, v173, s[0:1]
	v_cndmask_b32_e64 v120, v161, v163, s[0:1]
	v_cndmask_b32_e64 v121, v160, v162, s[0:1]
	v_cndmask_b32_e64 v123, v170, v172, s[0:1]
	v_mov_b32_dpp v174, v122 quad_perm:[1,0,3,2] row_mask:0xf bank_mask:0xf
	v_mov_b32_dpp v175, v121 quad_perm:[1,0,3,2] row_mask:0xf bank_mask:0xf
	v_mov_b32_dpp v159, v123 quad_perm:[1,0,3,2] row_mask:0xf bank_mask:0xf
	v_mov_b32_dpp v176, v120 quad_perm:[1,0,3,2] row_mask:0xf bank_mask:0xf
	v_cndmask_b32_e64 v123, v176, v161, s[0:1]
	v_cndmask_b32_e64 v122, v175, v160, s[0:1]
	v_cndmask_b32_e64 v121, v174, v171, s[0:1]
	v_cndmask_b32_e64 v120, v159, v170, s[0:1]
	v_cndmask_b32_e64 v127, v163, v176, s[0:1]
	v_cndmask_b32_e64 v126, v162, v175, s[0:1]
	v_cndmask_b32_e64 v125, v173, v174, s[0:1]
	v_cndmask_b32_e64 v124, v172, v159, s[0:1]
	global_store_dwordx4 v[166:167], v[120:123], off
	global_store_dwordx4 v[168:169], v[124:127], off
	global_load_dwordx4 v[122:125], v[164:165], off offset:256
	v_and_b32_e32 v121, 64, v158
	v_xor_b32_e32 v120, 16, v158
	v_add_u32_e32 v121, 64, v121
	v_xor_b32_e32 v126, 32, v158
	v_cmp_lt_i32_e32 vcc, v120, v121
	v_mul_f32_e32 v127, v161, v161
	v_mul_f32_e32 v161, v173, v173
	v_cndmask_b32_e32 v120, v158, v120, vcc
	v_cmp_lt_i32_e32 vcc, v126, v121
	v_lshlrev_b32_e32 v121, 2, v120
	v_fmac_f32_e32 v127, v160, v160
	v_cndmask_b32_e32 v126, v158, v126, vcc
	v_lshlrev_b32_e32 v120, 2, v126
	v_mul_f32_e32 v126, v171, v171
	v_fmac_f32_e32 v126, v170, v170
	v_mul_f32_e32 v163, v163, v163
	v_fmac_f32_e32 v161, v172, v172
	v_add_f32_e32 v126, v126, v127
	v_fmac_f32_e32 v163, v162, v162
	v_add_f32_e32 v126, v161, v126
	v_add_f32_e32 v162, v163, v126
	v_mov_b32_e32 v174, 0
	v_mov_b32_e32 v165, 0
	v_mov_b32_e32 v164, 0
	v_mov_b32_e32 v159, 0
	s_waitcnt vmcnt(0)
	v_lshlrev_b32_e32 v126, 16, v122
	v_and_b32_e32 v127, 0xffff0000, v122
	v_lshlrev_b32_e32 v122, 16, v123
	v_and_b32_e32 v123, 0xffff0000, v123
	v_lshlrev_b32_e32 v160, 16, v124
	v_and_b32_e32 v161, 0xffff0000, v124
	v_lshlrev_b32_e32 v124, 16, v125
	v_and_b32_e32 v125, 0xffff0000, v125
	v_pk_add_f32 v[116:117], v[116:117], v[126:127]
	v_pk_add_f32 v[118:119], v[118:119], v[122:123]
	v_pk_add_f32 v[122:123], v[112:113], v[160:161]
	v_pk_add_f32 v[124:125], v[114:115], v[124:125]
	v_mul_f32_e32 v126, v117, v117
	v_mul_f32_e32 v127, v119, v119
	v_cndmask_b32_e64 v112, v119, v125, s[0:1]
	v_mul_f32_e32 v160, v123, v123
	v_fmac_f32_e32 v126, v116, v116
	v_fmac_f32_e32 v127, v118, v118
	v_mul_f32_e32 v161, v125, v125
	v_mov_b32_dpp v174, v112 quad_perm:[1,0,3,2] row_mask:0xf bank_mask:0xf
	v_fmac_f32_e32 v160, v122, v122
	v_add_f32_e32 v112, v126, v127
	v_cndmask_b32_e64 v113, v118, v124, s[0:1]
	v_add_f32_e32 v112, v160, v112
	v_fmac_f32_e32 v161, v124, v124
	v_cndmask_b32_e64 v114, v117, v123, s[0:1]
	v_mov_b32_dpp v165, v113 quad_perm:[1,0,3,2] row_mask:0xf bank_mask:0xf
	v_add_f32_e32 v112, v161, v112
	v_cndmask_b32_e64 v115, v116, v122, s[0:1]
	v_mov_b32_dpp v164, v114 quad_perm:[1,0,3,2] row_mask:0xf bank_mask:0xf
	v_cndmask_b32_e64 v114, v165, v118, s[0:1]
	v_add_f32_e32 v118, v162, v112
	v_mov_b32_dpp v159, v115 quad_perm:[1,0,3,2] row_mask:0xf bank_mask:0xf
	v_cndmask_b32_e64 v115, v174, v119, s[0:1]
	v_mov_b32_e32 v119, v118
	s_nop 1
	v_permlane16_swap_b32_e32 v119, v118
	v_cndmask_b32_e64 v113, v164, v117, s[0:1]
	v_cndmask_b32_e64 v112, v159, v116, s[0:1]
	global_store_dwordx4 v[166:167], v[112:115], off offset:512
	v_cndmask_b32_e64 v117, v125, v174, s[0:1]
	v_cndmask_b32_e64 v116, v124, v165, s[0:1]
	s_waitcnt lgkmcnt(0)
	v_add_f32_e32 v112, v118, v119
	v_mov_b32_e32 v113, v112
	s_nop 1
	v_permlane32_swap_b32_e32 v113, v112
	v_cndmask_b32_e64 v115, v123, v164, s[0:1]
	v_cndmask_b32_e64 v114, v122, v159, s[0:1]
	global_store_dwordx4 v[168:169], v[114:117], off offset:512
	s_and_saveexec_b64 s[20:21], s[2:3]
	s_cbranch_execz .LBB0_2192
	v_lshl_add_u64 v[114:115], v[148:149], 2, s[12:13]
	s_waitcnt lgkmcnt(0)
	v_add_f32_e32 v112, v112, v113
	global_atomic_add_f32 v[114:115], v112, off
; #define GAS __attribute__((address_space(1)))
;     __device__ __forceinline__ void operator()(const f32x4 (&acc)[2][2][4][2], const Unit& u, int wr, int wc, int fr, int fq) const {
;     ...
;         const int row0 = u.pm * BM + wr * 64 + fr, col0 = u.pn * BM + wc * 32 + 8 * fq; const bool odd = (fr & 1) != 0;
; #pragma unroll
;         for (int ai = 0; ai < 2; ++ai)
; #pragma unroll
;             for (int m = 0; m < 4; ++m) {
;                 const int row = row0 + ai * HALF + m * 16; float s = 0.f;
;                 const size_t off = (size_t)row * DM + col0;
;                 const size_t offp = (size_t)(row - (odd ? 1 : 0)) * DM + col0 + (odd ? 4 : 0);
; #pragma unroll
;                 for (int bj = 0; bj < 2; ++bj) {
;                     f32x4 b0, b1;
;                     if constexpr (BASE_F32) { const f32x4 la = *(const GAS f32x4*)(basef + offp + bj * HALF), lb = *(const GAS f32x4*)(basef + offp + DM + bj * HALF);
;                         const f32x4 snd = odd ? la : lb; f32x4 rcv; rcv[0] = dpp_xor1(snd[0]); rcv[1] = dpp_xor1(snd[1]); rcv[2] = dpp_xor1(snd[2]); rcv[3] = dpp_xor1(snd[3]);
;                         b0 = odd ? rcv : la; b1 = odd ? lb : rcv; }
;                     else { const u32x4 bw = *(const u32x4*)(baseb + off + bj * HALF);
;                         b0 = (f32x4){bf_lo(bw.x), bf_hi(bw.x), bf_lo(bw.y), bf_hi(bw.y)}; b1 = (f32x4){bf_lo(bw.z), bf_hi(bw.z), bf_lo(bw.w), bf_hi(bw.w)}; }
;                     const f32x4 v0 = acc[ai][bj][m][0] + b0, v1 = acc[ai][bj][m][1] + b1;
;                     if constexpr (OUT_F32) { const f32x4 snd = odd ? v0 : v1; f32x4 rcv; rcv[0] = dpp_xor1(snd[0]); rcv[1] = dpp_xor1(snd[1]); rcv[2] = dpp_xor1(snd[2]); rcv[3] = dpp_xor1(snd[3]);
;                         *(f32x4*)(H + offp + bj * HALF) = odd ? rcv : v0; *(f32x4*)(H + offp + DM + bj * HALF) = odd ? v1 : rcv; }
;                     else { u32x4 w; w.x = cvt_pk_bf16(v0[0], v0[1]); w.y = cvt_pk_bf16(v0[2], v0[3]); w.z = cvt_pk_bf16(v1[0], v1[1]); w.w = cvt_pk_bf16(v1[2], v1[3]);
;                         *(u32x4*)(HB + off + bj * HALF) = w; }
;                     s += (v0[0] * v0[0] + v0[1] * v0[1]) + (v0[2] * v0[2] + v0[3] * v0[3]) + (v1[0] * v1[0] + v1[1] * v1[1]) + (v1[2] * v1[2] + v1[3] * v1[3]);
;                 }
;                 s += __shfl_xor(s, 16); s += __shfl_xor(s, 32);
;                 if (fq == 0) unsafeAtomicAdd(ssn + row, s);
.LBB0_2192:
	s_or_b64 exec, exec, s[20:21]
	v_or_b32_e32 v112, 16, v148
	s_waitcnt lgkmcnt(0)
	v_ashrrev_i32_e32 v113, 31, v112
	v_readlane_b32 s20, v254, 25
	v_lshlrev_b64 v[114:115], 12, v[112:113]
	v_readlane_b32 s21, v254, 26
	v_sub_u32_e32 v122, v112, v153
	v_ashrrev_i32_e32 v123, 31, v122
	v_lshl_add_u64 v[114:115], s[20:21], 0, v[114:115]
	v_lshl_add_u64 v[118:119], v[146:147], 1, v[114:115]
	global_load_dwordx4 v[114:117], v[118:119], off
	v_readlane_b32 s20, v254, 7
	v_lshlrev_b64 v[122:123], 13, v[122:123]
	v_readlane_b32 s21, v254, 8
	v_mov_b32_e32 v149, 0
	v_mov_b32_e32 v159, 0
	v_mov_b32_e32 v162, 0
	v_mov_b32_e32 v163, 0
	v_lshl_add_u64 v[122:123], s[20:21], 0, v[122:123]
	v_lshl_add_u64 v[122:123], v[150:151], 2, v[122:123]
	v_add_co_u32_e32 v124, vcc, s35, v122
	v_readlane_b32 s22, v254, 9
	s_nop 0
	v_addc_co_u32_e32 v125, vcc, 0, v123, vcc
	v_readlane_b32 s23, v254, 10
	s_waitcnt vmcnt(0)
	v_lshlrev_b32_e32 v126, 16, v114
	v_and_b32_e32 v127, 0xffff0000, v114
	v_lshlrev_b32_e32 v114, 16, v115
	v_and_b32_e32 v115, 0xffff0000, v115
	v_lshlrev_b32_e32 v160, 16, v116
	v_and_b32_e32 v161, 0xffff0000, v116
	v_lshlrev_b32_e32 v116, 16, v117
	v_and_b32_e32 v117, 0xffff0000, v117
	v_pk_add_f32 v[126:127], v[108:109], v[126:127]
	v_pk_add_f32 v[114:115], v[110:111], v[114:115]
	v_pk_add_f32 v[160:161], v[104:105], v[160:161]
	v_pk_add_f32 v[116:117], v[106:107], v[116:117]
	v_cndmask_b32_e64 v106, v127, v161, s[0:1]
	v_cndmask_b32_e64 v104, v115, v117, s[0:1]
	v_cndmask_b32_e64 v105, v114, v116, s[0:1]
	v_cndmask_b32_e64 v107, v126, v160, s[0:1]
	v_mov_b32_dpp v159, v106 quad_perm:[1,0,3,2] row_mask:0xf bank_mask:0xf
	v_mov_b32_dpp v162, v105 quad_perm:[1,0,3,2] row_mask:0xf bank_mask:0xf
	v_mov_b32_dpp v149, v107 quad_perm:[1,0,3,2] row_mask:0xf bank_mask:0xf
	v_mov_b32_dpp v163, v104 quad_perm:[1,0,3,2] row_mask:0xf bank_mask:0xf
	v_cndmask_b32_e64 v107, v163, v115, s[0:1]
	v_cndmask_b32_e64 v106, v162, v114, s[0:1]
	v_cndmask_b32_e64 v105, v159, v127, s[0:1]
	v_cndmask_b32_e64 v104, v149, v126, s[0:1]
	v_cndmask_b32_e64 v111, v117, v163, s[0:1]
	v_cndmask_b32_e64 v110, v116, v162, s[0:1]
	v_cndmask_b32_e64 v109, v161, v159, s[0:1]
	v_cndmask_b32_e64 v108, v160, v149, s[0:1]
	global_store_dwordx4 v[122:123], v[104:107], off
	global_store_dwordx4 v[124:125], v[108:111], off
	global_load_dwordx4 v[104:107], v[118:119], off offset:256
	v_mov_b32_e32 v159, 0
	v_mul_f32_e32 v108, v127, v127
	v_mul_f32_e32 v109, v115, v115
	v_mul_f32_e32 v110, v161, v161
	v_fmac_f32_e32 v108, v126, v126
	v_fmac_f32_e32 v109, v114, v114
	v_mul_f32_e32 v111, v117, v117
	v_fmac_f32_e32 v110, v160, v160
	v_add_f32_e32 v108, v108, v109
	v_fmac_f32_e32 v111, v116, v116
	v_add_f32_e32 v108, v110, v108
	v_add_f32_e32 v114, v111, v108
	v_mov_b32_e32 v149, 0
	v_mov_b32_e32 v119, 0
	v_mov_b32_e32 v118, 0
	s_waitcnt vmcnt(0)
	v_lshlrev_b32_e32 v108, 16, v104
	v_and_b32_e32 v109, 0xffff0000, v104
	v_lshlrev_b32_e32 v104, 16, v105
	v_and_b32_e32 v105, 0xffff0000, v105
	v_lshlrev_b32_e32 v110, 16, v106
	v_and_b32_e32 v111, 0xffff0000, v106
	v_lshlrev_b32_e32 v106, 16, v107
	v_and_b32_e32 v107, 0xffff0000, v107
	v_pk_add_f32 v[100:101], v[100:101], v[108:109]
	v_pk_add_f32 v[102:103], v[102:103], v[104:105]
	v_pk_add_f32 v[104:105], v[96:97], v[110:111]
	v_pk_add_f32 v[106:107], v[98:99], v[106:107]
	v_mul_f32_e32 v108, v101, v101
	v_mul_f32_e32 v109, v103, v103
	v_cndmask_b32_e64 v96, v103, v107, s[0:1]
	v_mul_f32_e32 v110, v105, v105
	v_fmac_f32_e32 v108, v100, v100
	v_fmac_f32_e32 v109, v102, v102
	v_mul_f32_e32 v111, v107, v107
	v_mov_b32_dpp v159, v96 quad_perm:[1,0,3,2] row_mask:0xf bank_mask:0xf
	v_fmac_f32_e32 v110, v104, v104
	v_add_f32_e32 v96, v108, v109
	v_cndmask_b32_e64 v97, v102, v106, s[0:1]
	v_add_f32_e32 v96, v110, v96
	v_fmac_f32_e32 v111, v106, v106
	v_cndmask_b32_e64 v98, v101, v105, s[0:1]
	v_mov_b32_dpp v149, v97 quad_perm:[1,0,3,2] row_mask:0xf bank_mask:0xf
	v_add_f32_e32 v96, v111, v96
	v_cndmask_b32_e64 v99, v100, v104, s[0:1]
	v_mov_b32_dpp v119, v98 quad_perm:[1,0,3,2] row_mask:0xf bank_mask:0xf
	v_cndmask_b32_e64 v98, v149, v102, s[0:1]
	v_add_f32_e32 v102, v114, v96
	v_mov_b32_dpp v118, v99 quad_perm:[1,0,3,2] row_mask:0xf bank_mask:0xf
	v_cndmask_b32_e64 v99, v159, v103, s[0:1]
	v_mov_b32_e32 v103, v102
	s_nop 1
	v_permlane16_swap_b32_e32 v103, v102
	v_cndmask_b32_e64 v97, v119, v101, s[0:1]
	v_cndmask_b32_e64 v96, v118, v100, s[0:1]
	global_store_dwordx4 v[122:123], v[96:99], off offset:512
	v_cndmask_b32_e64 v101, v107, v159, s[0:1]
	v_cndmask_b32_e64 v100, v106, v149, s[0:1]
	s_waitcnt lgkmcnt(0)
	v_add_f32_e32 v96, v102, v103
	v_mov_b32_e32 v97, v96
	s_nop 1
	v_permlane32_swap_b32_e32 v97, v96
	v_cndmask_b32_e64 v99, v105, v119, s[0:1]
	v_cndmask_b32_e64 v98, v104, v118, s[0:1]
	global_store_dwordx4 v[124:125], v[98:101], off offset:512
	s_and_saveexec_b64 s[20:21], s[2:3]
	s_cbranch_execz .LBB0_2194
	v_lshl_add_u64 v[98:99], v[112:113], 2, s[12:13]
	s_waitcnt lgkmcnt(0)
	v_add_f32_e32 v96, v96, v97
	global_atomic_add_f32 v[98:99], v96, off
; #define GAS __attribute__((address_space(1)))
;     __device__ __forceinline__ void operator()(const f32x4 (&acc)[2][2][4][2], const Unit& u, int wr, int wc, int fr, int fq) const {
;     ...
;         const int row0 = u.pm * BM + wr * 64 + fr, col0 = u.pn * BM + wc * 32 + 8 * fq; const bool odd = (fr & 1) != 0;
; #pragma unroll
;         for (int ai = 0; ai < 2; ++ai)
; #pragma unroll
;             for (int m = 0; m < 4; ++m) {
;                 const int row = row0 + ai * HALF + m * 16; float s = 0.f;
;                 const size_t off = (size_t)row * DM + col0;
;                 const size_t offp = (size_t)(row - (odd ? 1 : 0)) * DM + col0 + (odd ? 4 : 0);
; #pragma unroll
;                 for (int bj = 0; bj < 2; ++bj) {
;                     f32x4 b0, b1;
;                     if constexpr (BASE_F32) { const f32x4 la = *(const GAS f32x4*)(basef + offp + bj * HALF), lb = *(const GAS f32x4*)(basef + offp + DM + bj * HALF);
;                         const f32x4 snd = odd ? la : lb; f32x4 rcv; rcv[0] = dpp_xor1(snd[0]); rcv[1] = dpp_xor1(snd[1]); rcv[2] = dpp_xor1(snd[2]); rcv[3] = dpp_xor1(snd[3]);
;                         b0 = odd ? rcv : la; b1 = odd ? lb : rcv; }
;                     else { const u32x4 bw = *(const u32x4*)(baseb + off + bj * HALF);
;                         b0 = (f32x4){bf_lo(bw.x), bf_hi(bw.x), bf_lo(bw.y), bf_hi(bw.y)}; b1 = (f32x4){bf_lo(bw.z), bf_hi(bw.z), bf_lo(bw.w), bf_hi(bw.w)}; }
;                     const f32x4 v0 = acc[ai][bj][m][0] + b0, v1 = acc[ai][bj][m][1] + b1;
;                     if constexpr (OUT_F32) { const f32x4 snd = odd ? v0 : v1; f32x4 rcv; rcv[0] = dpp_xor1(snd[0]); rcv[1] = dpp_xor1(snd[1]); rcv[2] = dpp_xor1(snd[2]); rcv[3] = dpp_xor1(snd[3]);
;                         *(f32x4*)(H + offp + bj * HALF) = odd ? rcv : v0; *(f32x4*)(H + offp + DM + bj * HALF) = odd ? v1 : rcv; }
;                     else { u32x4 w; w.x = cvt_pk_bf16(v0[0], v0[1]); w.y = cvt_pk_bf16(v0[2], v0[3]); w.z = cvt_pk_bf16(v1[0], v1[1]); w.w = cvt_pk_bf16(v1[2], v1[3]);
;                         *(u32x4*)(HB + off + bj * HALF) = w; }
;                     s += (v0[0] * v0[0] + v0[1] * v0[1]) + (v0[2] * v0[2] + v0[3] * v0[3]) + (v1[0] * v1[0] + v1[1] * v1[1]) + (v1[2] * v1[2] + v1[3] * v1[3]);
;                 }
;                 s += __shfl_xor(s, 16); s += __shfl_xor(s, 32);
;                 if (fq == 0) unsafeAtomicAdd(ssn + row, s);
.LBB0_2194:
	s_or_b64 exec, exec, s[20:21]
	v_or_b32_e32 v96, 32, v148
	s_waitcnt lgkmcnt(0)
	v_ashrrev_i32_e32 v97, 31, v96
	v_readlane_b32 s20, v254, 25
	v_lshlrev_b64 v[98:99], 12, v[96:97]
	v_readlane_b32 s21, v254, 26
	v_sub_u32_e32 v104, v96, v153
	v_ashrrev_i32_e32 v105, 31, v104
	v_lshl_add_u64 v[98:99], s[20:21], 0, v[98:99]
	v_lshl_add_u64 v[102:103], v[146:147], 1, v[98:99]
	global_load_dwordx4 v[98:101], v[102:103], off
	v_readlane_b32 s20, v254, 7
	v_lshlrev_b64 v[104:105], 13, v[104:105]
	v_readlane_b32 s21, v254, 8
	v_mov_b32_e32 v112, 0
	v_mov_b32_e32 v113, 0
	v_mov_b32_e32 v114, 0
	v_mov_b32_e32 v115, 0
	v_lshl_add_u64 v[104:105], s[20:21], 0, v[104:105]
	v_lshl_add_u64 v[104:105], v[150:151], 2, v[104:105]
	v_add_co_u32_e32 v106, vcc, s35, v104
	v_readlane_b32 s22, v254, 9
	s_nop 0
	v_addc_co_u32_e32 v107, vcc, 0, v105, vcc
	v_readlane_b32 s23, v254, 10
	s_waitcnt vmcnt(0)
	v_lshlrev_b32_e32 v108, 16, v98
	v_and_b32_e32 v109, 0xffff0000, v98
	v_lshlrev_b32_e32 v98, 16, v99
	v_and_b32_e32 v99, 0xffff0000, v99
	v_lshlrev_b32_e32 v110, 16, v100
	v_and_b32_e32 v111, 0xffff0000, v100
	v_lshlrev_b32_e32 v100, 16, v101
	v_and_b32_e32 v101, 0xffff0000, v101
	v_pk_add_f32 v[108:109], v[92:93], v[108:109]
	v_pk_add_f32 v[98:99], v[94:95], v[98:99]
	v_pk_add_f32 v[110:111], v[88:89], v[110:111]
	v_pk_add_f32 v[100:101], v[90:91], v[100:101]
	v_cndmask_b32_e64 v90, v109, v111, s[0:1]
	v_cndmask_b32_e64 v88, v99, v101, s[0:1]
	v_cndmask_b32_e64 v89, v98, v100, s[0:1]
	v_cndmask_b32_e64 v91, v108, v110, s[0:1]
	v_mov_b32_dpp v113, v90 quad_perm:[1,0,3,2] row_mask:0xf bank_mask:0xf
	v_mov_b32_dpp v114, v89 quad_perm:[1,0,3,2] row_mask:0xf bank_mask:0xf
	v_mov_b32_dpp v112, v91 quad_perm:[1,0,3,2] row_mask:0xf bank_mask:0xf
	v_mov_b32_dpp v115, v88 quad_perm:[1,0,3,2] row_mask:0xf bank_mask:0xf
	v_cndmask_b32_e64 v91, v115, v99, s[0:1]
	v_cndmask_b32_e64 v90, v114, v98, s[0:1]
	v_cndmask_b32_e64 v89, v113, v109, s[0:1]
	v_cndmask_b32_e64 v88, v112, v108, s[0:1]
	v_cndmask_b32_e64 v95, v101, v115, s[0:1]
	v_cndmask_b32_e64 v94, v100, v114, s[0:1]
	v_cndmask_b32_e64 v93, v111, v113, s[0:1]
	v_cndmask_b32_e64 v92, v110, v112, s[0:1]
	global_store_dwordx4 v[104:105], v[88:91], off
	global_store_dwordx4 v[106:107], v[92:95], off
	global_load_dwordx4 v[88:91], v[102:103], off offset:256
	v_mov_b32_e32 v113, 0
	v_mul_f32_e32 v92, v109, v109
	v_mul_f32_e32 v93, v99, v99
	v_mul_f32_e32 v94, v111, v111
	v_fmac_f32_e32 v92, v108, v108
	v_fmac_f32_e32 v93, v98, v98
	v_mul_f32_e32 v95, v101, v101
	v_fmac_f32_e32 v94, v110, v110
	v_add_f32_e32 v92, v92, v93
	v_fmac_f32_e32 v95, v100, v100
	v_add_f32_e32 v92, v94, v92
	v_add_f32_e32 v98, v95, v92
	v_mov_b32_e32 v112, 0
	v_mov_b32_e32 v103, 0
	v_mov_b32_e32 v102, 0
	s_waitcnt vmcnt(0)
	v_lshlrev_b32_e32 v92, 16, v88
	v_and_b32_e32 v93, 0xffff0000, v88
	v_lshlrev_b32_e32 v88, 16, v89
	v_and_b32_e32 v89, 0xffff0000, v89
	v_lshlrev_b32_e32 v94, 16, v90
	v_and_b32_e32 v95, 0xffff0000, v90
	v_lshlrev_b32_e32 v90, 16, v91
	v_and_b32_e32 v91, 0xffff0000, v91
	v_pk_add_f32 v[84:85], v[84:85], v[92:93]
	v_pk_add_f32 v[86:87], v[86:87], v[88:89]
	v_pk_add_f32 v[88:89], v[80:81], v[94:95]
	v_pk_add_f32 v[90:91], v[82:83], v[90:91]
	v_mul_f32_e32 v92, v85, v85
	v_mul_f32_e32 v93, v87, v87
	v_cndmask_b32_e64 v80, v87, v91, s[0:1]
	v_mul_f32_e32 v94, v89, v89
	v_fmac_f32_e32 v92, v84, v84
	v_fmac_f32_e32 v93, v86, v86
	v_mul_f32_e32 v95, v91, v91
	v_mov_b32_dpp v113, v80 quad_perm:[1,0,3,2] row_mask:0xf bank_mask:0xf
	v_fmac_f32_e32 v94, v88, v88
	v_add_f32_e32 v80, v92, v93
	v_cndmask_b32_e64 v81, v86, v90, s[0:1]
	v_add_f32_e32 v80, v94, v80
	v_fmac_f32_e32 v95, v90, v90
	v_cndmask_b32_e64 v82, v85, v89, s[0:1]
	v_mov_b32_dpp v112, v81 quad_perm:[1,0,3,2] row_mask:0xf bank_mask:0xf
	v_add_f32_e32 v80, v95, v80
	v_cndmask_b32_e64 v83, v84, v88, s[0:1]
	v_mov_b32_dpp v103, v82 quad_perm:[1,0,3,2] row_mask:0xf bank_mask:0xf
	v_cndmask_b32_e64 v82, v112, v86, s[0:1]
	v_add_f32_e32 v86, v98, v80
	v_mov_b32_dpp v102, v83 quad_perm:[1,0,3,2] row_mask:0xf bank_mask:0xf
	v_cndmask_b32_e64 v83, v113, v87, s[0:1]
	v_mov_b32_e32 v87, v86
	s_nop 1
	v_permlane16_swap_b32_e32 v87, v86
	v_cndmask_b32_e64 v81, v103, v85, s[0:1]
	v_cndmask_b32_e64 v80, v102, v84, s[0:1]
	global_store_dwordx4 v[104:105], v[80:83], off offset:512
	v_cndmask_b32_e64 v85, v91, v113, s[0:1]
	v_cndmask_b32_e64 v84, v90, v112, s[0:1]
	s_waitcnt lgkmcnt(0)
	v_add_f32_e32 v80, v86, v87
	v_mov_b32_e32 v81, v80
	s_nop 1
	v_permlane32_swap_b32_e32 v81, v80
	v_cndmask_b32_e64 v83, v89, v103, s[0:1]
	v_cndmask_b32_e64 v82, v88, v102, s[0:1]
	global_store_dwordx4 v[106:107], v[82:85], off offset:512
	s_and_saveexec_b64 s[20:21], s[2:3]
	s_cbranch_execz .LBB0_2196
	v_lshl_add_u64 v[82:83], v[96:97], 2, s[12:13]
	s_waitcnt lgkmcnt(0)
	v_add_f32_e32 v80, v80, v81
	global_atomic_add_f32 v[82:83], v80, off
; #define GAS __attribute__((address_space(1)))
;     __device__ __forceinline__ void operator()(const f32x4 (&acc)[2][2][4][2], const Unit& u, int wr, int wc, int fr, int fq) const {
;     ...
;         const int row0 = u.pm * BM + wr * 64 + fr, col0 = u.pn * BM + wc * 32 + 8 * fq; const bool odd = (fr & 1) != 0;
; #pragma unroll
;         for (int ai = 0; ai < 2; ++ai)
; #pragma unroll
;             for (int m = 0; m < 4; ++m) {
;                 const int row = row0 + ai * HALF + m * 16; float s = 0.f;
;                 const size_t off = (size_t)row * DM + col0;
;                 const size_t offp = (size_t)(row - (odd ? 1 : 0)) * DM + col0 + (odd ? 4 : 0);
; #pragma unroll
;                 for (int bj = 0; bj < 2; ++bj) {
;                     f32x4 b0, b1;
;                     if constexpr (BASE_F32) { const f32x4 la = *(const GAS f32x4*)(basef + offp + bj * HALF), lb = *(const GAS f32x4*)(basef + offp + DM + bj * HALF);
;                         const f32x4 snd = odd ? la : lb; f32x4 rcv; rcv[0] = dpp_xor1(snd[0]); rcv[1] = dpp_xor1(snd[1]); rcv[2] = dpp_xor1(snd[2]); rcv[3] = dpp_xor1(snd[3]);
;                         b0 = odd ? rcv : la; b1 = odd ? lb : rcv; }
;                     else { const u32x4 bw = *(const u32x4*)(baseb + off + bj * HALF);
;                         b0 = (f32x4){bf_lo(bw.x), bf_hi(bw.x), bf_lo(bw.y), bf_hi(bw.y)}; b1 = (f32x4){bf_lo(bw.z), bf_hi(bw.z), bf_lo(bw.w), bf_hi(bw.w)}; }
;                     const f32x4 v0 = acc[ai][bj][m][0] + b0, v1 = acc[ai][bj][m][1] + b1;
;                     if constexpr (OUT_F32) { const f32x4 snd = odd ? v0 : v1; f32x4 rcv; rcv[0] = dpp_xor1(snd[0]); rcv[1] = dpp_xor1(snd[1]); rcv[2] = dpp_xor1(snd[2]); rcv[3] = dpp_xor1(snd[3]);
;                         *(f32x4*)(H + offp + bj * HALF) = odd ? rcv : v0; *(f32x4*)(H + offp + DM + bj * HALF) = odd ? v1 : rcv; }
;                     else { u32x4 w; w.x = cvt_pk_bf16(v0[0], v0[1]); w.y = cvt_pk_bf16(v0[2], v0[3]); w.z = cvt_pk_bf16(v1[0], v1[1]); w.w = cvt_pk_bf16(v1[2], v1[3]);
;                         *(u32x4*)(HB + off + bj * HALF) = w; }
;                     s += (v0[0] * v0[0] + v0[1] * v0[1]) + (v0[2] * v0[2] + v0[3] * v0[3]) + (v1[0] * v1[0] + v1[1] * v1[1]) + (v1[2] * v1[2] + v1[3] * v1[3]);
;                 }
;                 s += __shfl_xor(s, 16); s += __shfl_xor(s, 32);
;                 if (fq == 0) unsafeAtomicAdd(ssn + row, s);
.LBB0_2196:
	s_or_b64 exec, exec, s[20:21]
	v_or_b32_e32 v80, 48, v148
	s_waitcnt lgkmcnt(0)
	v_ashrrev_i32_e32 v81, 31, v80
	v_readlane_b32 s20, v254, 25
	v_lshlrev_b64 v[82:83], 12, v[80:81]
	v_readlane_b32 s21, v254, 26
	v_sub_u32_e32 v88, v80, v153
	v_ashrrev_i32_e32 v89, 31, v88
	v_lshl_add_u64 v[82:83], s[20:21], 0, v[82:83]
	v_lshl_add_u64 v[86:87], v[146:147], 1, v[82:83]
	global_load_dwordx4 v[82:85], v[86:87], off
	v_readlane_b32 s20, v254, 7
	v_lshlrev_b64 v[88:89], 13, v[88:89]
	v_readlane_b32 s21, v254, 8
	v_mov_b32_e32 v96, 0
	v_mov_b32_e32 v97, 0
	v_mov_b32_e32 v98, 0
	v_mov_b32_e32 v99, 0
	v_lshl_add_u64 v[88:89], s[20:21], 0, v[88:89]
	v_lshl_add_u64 v[88:89], v[150:151], 2, v[88:89]
	v_add_co_u32_e32 v90, vcc, s35, v88
	v_readlane_b32 s22, v254, 9
	s_nop 0
	v_addc_co_u32_e32 v91, vcc, 0, v89, vcc
	v_readlane_b32 s23, v254, 10
	s_waitcnt vmcnt(0)
	v_lshlrev_b32_e32 v92, 16, v82
	v_and_b32_e32 v93, 0xffff0000, v82
	v_lshlrev_b32_e32 v82, 16, v83
	v_and_b32_e32 v83, 0xffff0000, v83
	v_lshlrev_b32_e32 v94, 16, v84
	v_and_b32_e32 v95, 0xffff0000, v84
	v_lshlrev_b32_e32 v84, 16, v85
	v_and_b32_e32 v85, 0xffff0000, v85
	v_pk_add_f32 v[92:93], v[76:77], v[92:93]
	v_pk_add_f32 v[82:83], v[78:79], v[82:83]
	v_pk_add_f32 v[94:95], v[72:73], v[94:95]
	v_pk_add_f32 v[84:85], v[74:75], v[84:85]
	v_cndmask_b32_e64 v74, v93, v95, s[0:1]
	v_cndmask_b32_e64 v72, v83, v85, s[0:1]
	v_cndmask_b32_e64 v73, v82, v84, s[0:1]
	v_cndmask_b32_e64 v75, v92, v94, s[0:1]
	v_mov_b32_dpp v97, v74 quad_perm:[1,0,3,2] row_mask:0xf bank_mask:0xf
	v_mov_b32_dpp v98, v73 quad_perm:[1,0,3,2] row_mask:0xf bank_mask:0xf
	v_mov_b32_dpp v96, v75 quad_perm:[1,0,3,2] row_mask:0xf bank_mask:0xf
	v_mov_b32_dpp v99, v72 quad_perm:[1,0,3,2] row_mask:0xf bank_mask:0xf
	v_cndmask_b32_e64 v75, v99, v83, s[0:1]
	v_cndmask_b32_e64 v74, v98, v82, s[0:1]
	v_cndmask_b32_e64 v73, v97, v93, s[0:1]
	v_cndmask_b32_e64 v72, v96, v92, s[0:1]
	v_cndmask_b32_e64 v79, v85, v99, s[0:1]
	v_cndmask_b32_e64 v78, v84, v98, s[0:1]
	v_cndmask_b32_e64 v77, v95, v97, s[0:1]
	v_cndmask_b32_e64 v76, v94, v96, s[0:1]
	global_store_dwordx4 v[88:89], v[72:75], off
	global_store_dwordx4 v[90:91], v[76:79], off
	global_load_dwordx4 v[72:75], v[86:87], off offset:256
	v_mov_b32_e32 v97, 0
	v_mul_f32_e32 v76, v93, v93
	v_mul_f32_e32 v77, v83, v83
	v_mul_f32_e32 v78, v95, v95
	v_fmac_f32_e32 v76, v92, v92
	v_fmac_f32_e32 v77, v82, v82
	v_mul_f32_e32 v79, v85, v85
	v_fmac_f32_e32 v78, v94, v94
	v_add_f32_e32 v76, v76, v77
	v_fmac_f32_e32 v79, v84, v84
	v_add_f32_e32 v76, v78, v76
	v_add_f32_e32 v82, v79, v76
	v_mov_b32_e32 v96, 0
	v_mov_b32_e32 v87, 0
	v_mov_b32_e32 v86, 0
	s_waitcnt vmcnt(0)
	v_lshlrev_b32_e32 v76, 16, v72
	v_and_b32_e32 v77, 0xffff0000, v72
	v_lshlrev_b32_e32 v72, 16, v73
	v_and_b32_e32 v73, 0xffff0000, v73
	v_lshlrev_b32_e32 v78, 16, v74
	v_and_b32_e32 v79, 0xffff0000, v74
	v_lshlrev_b32_e32 v74, 16, v75
	v_and_b32_e32 v75, 0xffff0000, v75
	v_pk_add_f32 v[68:69], v[68:69], v[76:77]
	v_pk_add_f32 v[70:71], v[70:71], v[72:73]
	v_pk_add_f32 v[72:73], v[64:65], v[78:79]
	v_pk_add_f32 v[74:75], v[66:67], v[74:75]
	v_mul_f32_e32 v76, v69, v69
	v_mul_f32_e32 v77, v71, v71
	v_cndmask_b32_e64 v64, v71, v75, s[0:1]
	v_mul_f32_e32 v78, v73, v73
	v_fmac_f32_e32 v76, v68, v68
	v_fmac_f32_e32 v77, v70, v70
	v_mul_f32_e32 v79, v75, v75
	v_mov_b32_dpp v97, v64 quad_perm:[1,0,3,2] row_mask:0xf bank_mask:0xf
	v_fmac_f32_e32 v78, v72, v72
	v_add_f32_e32 v64, v76, v77
	v_cndmask_b32_e64 v65, v70, v74, s[0:1]
	v_add_f32_e32 v64, v78, v64
	v_fmac_f32_e32 v79, v74, v74
	v_cndmask_b32_e64 v66, v69, v73, s[0:1]
	v_mov_b32_dpp v96, v65 quad_perm:[1,0,3,2] row_mask:0xf bank_mask:0xf
	v_add_f32_e32 v64, v79, v64
	v_cndmask_b32_e64 v67, v68, v72, s[0:1]
	v_mov_b32_dpp v87, v66 quad_perm:[1,0,3,2] row_mask:0xf bank_mask:0xf
	v_cndmask_b32_e64 v66, v96, v70, s[0:1]
	v_add_f32_e32 v70, v82, v64
	v_mov_b32_dpp v86, v67 quad_perm:[1,0,3,2] row_mask:0xf bank_mask:0xf
	v_cndmask_b32_e64 v67, v97, v71, s[0:1]
	v_mov_b32_e32 v71, v70
	s_nop 1
	v_permlane16_swap_b32_e32 v71, v70
	v_cndmask_b32_e64 v65, v87, v69, s[0:1]
	v_cndmask_b32_e64 v64, v86, v68, s[0:1]
	global_store_dwordx4 v[88:89], v[64:67], off offset:512
	v_cndmask_b32_e64 v69, v75, v97, s[0:1]
	v_cndmask_b32_e64 v68, v74, v96, s[0:1]
	s_waitcnt lgkmcnt(0)
	v_add_f32_e32 v64, v70, v71
	v_mov_b32_e32 v65, v64
	s_nop 1
	v_permlane32_swap_b32_e32 v65, v64
	v_cndmask_b32_e64 v67, v73, v87, s[0:1]
	v_cndmask_b32_e64 v66, v72, v86, s[0:1]
	global_store_dwordx4 v[90:91], v[66:69], off offset:512
	s_and_saveexec_b64 s[20:21], s[2:3]
	s_cbranch_execz .LBB0_2198
	v_lshl_add_u64 v[66:67], v[80:81], 2, s[12:13]
	s_waitcnt lgkmcnt(0)
	v_add_f32_e32 v64, v64, v65
	global_atomic_add_f32 v[66:67], v64, off
; #define GAS __attribute__((address_space(1)))
;     __device__ __forceinline__ void operator()(const f32x4 (&acc)[2][2][4][2], const Unit& u, int wr, int wc, int fr, int fq) const {
;     ...
;         const int row0 = u.pm * BM + wr * 64 + fr, col0 = u.pn * BM + wc * 32 + 8 * fq; const bool odd = (fr & 1) != 0;
; #pragma unroll
;         for (int ai = 0; ai < 2; ++ai)
; #pragma unroll
;             for (int m = 0; m < 4; ++m) {
;                 const int row = row0 + ai * HALF + m * 16; float s = 0.f;
;                 const size_t off = (size_t)row * DM + col0;
;                 const size_t offp = (size_t)(row - (odd ? 1 : 0)) * DM + col0 + (odd ? 4 : 0);
; #pragma unroll
;                 for (int bj = 0; bj < 2; ++bj) {
;                     f32x4 b0, b1;
;                     if constexpr (BASE_F32) { const f32x4 la = *(const GAS f32x4*)(basef + offp + bj * HALF), lb = *(const GAS f32x4*)(basef + offp + DM + bj * HALF);
;                         const f32x4 snd = odd ? la : lb; f32x4 rcv; rcv[0] = dpp_xor1(snd[0]); rcv[1] = dpp_xor1(snd[1]); rcv[2] = dpp_xor1(snd[2]); rcv[3] = dpp_xor1(snd[3]);
;                         b0 = odd ? rcv : la; b1 = odd ? lb : rcv; }
;                     else { const u32x4 bw = *(const u32x4*)(baseb + off + bj * HALF);
;                         b0 = (f32x4){bf_lo(bw.x), bf_hi(bw.x), bf_lo(bw.y), bf_hi(bw.y)}; b1 = (f32x4){bf_lo(bw.z), bf_hi(bw.z), bf_lo(bw.w), bf_hi(bw.w)}; }
;                     const f32x4 v0 = acc[ai][bj][m][0] + b0, v1 = acc[ai][bj][m][1] + b1;
;                     if constexpr (OUT_F32) { const f32x4 snd = odd ? v0 : v1; f32x4 rcv; rcv[0] = dpp_xor1(snd[0]); rcv[1] = dpp_xor1(snd[1]); rcv[2] = dpp_xor1(snd[2]); rcv[3] = dpp_xor1(snd[3]);
;                         *(f32x4*)(H + offp + bj * HALF) = odd ? rcv : v0; *(f32x4*)(H + offp + DM + bj * HALF) = odd ? v1 : rcv; }
;                     else { u32x4 w; w.x = cvt_pk_bf16(v0[0], v0[1]); w.y = cvt_pk_bf16(v0[2], v0[3]); w.z = cvt_pk_bf16(v1[0], v1[1]); w.w = cvt_pk_bf16(v1[2], v1[3]);
;                         *(u32x4*)(HB + off + bj * HALF) = w; }
;                     s += (v0[0] * v0[0] + v0[1] * v0[1]) + (v0[2] * v0[2] + v0[3] * v0[3]) + (v1[0] * v1[0] + v1[1] * v1[1]) + (v1[2] * v1[2] + v1[3] * v1[3]);
;                 }
;                 s += __shfl_xor(s, 16); s += __shfl_xor(s, 32);
;                 if (fq == 0) unsafeAtomicAdd(ssn + row, s);
.LBB0_2198:
	s_or_b64 exec, exec, s[20:21]
	v_add_u32_e32 v64, 0x80, v148
	s_waitcnt lgkmcnt(0)
	v_ashrrev_i32_e32 v65, 31, v64
	v_readlane_b32 s20, v254, 25
	v_lshlrev_b64 v[66:67], 12, v[64:65]
	v_readlane_b32 s21, v254, 26
	v_sub_u32_e32 v72, v64, v153
	v_ashrrev_i32_e32 v73, 31, v72
	v_lshl_add_u64 v[66:67], s[20:21], 0, v[66:67]
	v_lshl_add_u64 v[70:71], v[146:147], 1, v[66:67]
	global_load_dwordx4 v[66:69], v[70:71], off
	v_readlane_b32 s20, v254, 7
	v_lshlrev_b64 v[72:73], 13, v[72:73]
	v_readlane_b32 s21, v254, 8
	v_mov_b32_e32 v80, 0
	v_mov_b32_e32 v81, 0
	v_mov_b32_e32 v82, 0
	v_mov_b32_e32 v83, 0
	v_lshl_add_u64 v[72:73], s[20:21], 0, v[72:73]
	v_lshl_add_u64 v[72:73], v[150:151], 2, v[72:73]
	v_add_co_u32_e32 v74, vcc, s35, v72
	v_readlane_b32 s22, v254, 9
	s_nop 0
	v_addc_co_u32_e32 v75, vcc, 0, v73, vcc
	v_readlane_b32 s23, v254, 10
	s_waitcnt vmcnt(0)
	v_lshlrev_b32_e32 v76, 16, v66
	v_and_b32_e32 v77, 0xffff0000, v66
	v_lshlrev_b32_e32 v66, 16, v67
	v_and_b32_e32 v67, 0xffff0000, v67
	v_lshlrev_b32_e32 v78, 16, v68
	v_and_b32_e32 v79, 0xffff0000, v68
	v_lshlrev_b32_e32 v68, 16, v69
	v_and_b32_e32 v69, 0xffff0000, v69
	v_pk_add_f32 v[76:77], v[60:61], v[76:77]
	v_pk_add_f32 v[66:67], v[62:63], v[66:67]
	v_pk_add_f32 v[78:79], v[56:57], v[78:79]
	v_pk_add_f32 v[68:69], v[58:59], v[68:69]
	v_cndmask_b32_e64 v58, v77, v79, s[0:1]
	v_cndmask_b32_e64 v56, v67, v69, s[0:1]
	v_cndmask_b32_e64 v57, v66, v68, s[0:1]
	v_cndmask_b32_e64 v59, v76, v78, s[0:1]
	v_mov_b32_dpp v81, v58 quad_perm:[1,0,3,2] row_mask:0xf bank_mask:0xf
	v_mov_b32_dpp v82, v57 quad_perm:[1,0,3,2] row_mask:0xf bank_mask:0xf
	v_mov_b32_dpp v80, v59 quad_perm:[1,0,3,2] row_mask:0xf bank_mask:0xf
	v_mov_b32_dpp v83, v56 quad_perm:[1,0,3,2] row_mask:0xf bank_mask:0xf
	v_cndmask_b32_e64 v59, v83, v67, s[0:1]
	v_cndmask_b32_e64 v58, v82, v66, s[0:1]
	v_cndmask_b32_e64 v57, v81, v77, s[0:1]
	v_cndmask_b32_e64 v56, v80, v76, s[0:1]
	v_cndmask_b32_e64 v63, v69, v83, s[0:1]
	v_cndmask_b32_e64 v62, v68, v82, s[0:1]
	v_cndmask_b32_e64 v61, v79, v81, s[0:1]
	v_cndmask_b32_e64 v60, v78, v80, s[0:1]
	global_store_dwordx4 v[72:73], v[56:59], off
	global_store_dwordx4 v[74:75], v[60:63], off
	global_load_dwordx4 v[56:59], v[70:71], off offset:256
	v_mov_b32_e32 v81, 0
	v_mul_f32_e32 v60, v77, v77
	v_mul_f32_e32 v61, v67, v67
	v_mul_f32_e32 v62, v79, v79
	v_fmac_f32_e32 v60, v76, v76
	v_fmac_f32_e32 v61, v66, v66
	v_mul_f32_e32 v63, v69, v69
	v_fmac_f32_e32 v62, v78, v78
	v_add_f32_e32 v60, v60, v61
	v_fmac_f32_e32 v63, v68, v68
	v_add_f32_e32 v60, v62, v60
	v_add_f32_e32 v66, v63, v60
	v_mov_b32_e32 v80, 0
	v_mov_b32_e32 v71, 0
	v_mov_b32_e32 v70, 0
	s_waitcnt vmcnt(0)
	v_lshlrev_b32_e32 v60, 16, v56
	v_and_b32_e32 v61, 0xffff0000, v56
	v_lshlrev_b32_e32 v56, 16, v57
	v_and_b32_e32 v57, 0xffff0000, v57
	v_lshlrev_b32_e32 v62, 16, v58
	v_and_b32_e32 v63, 0xffff0000, v58
	v_lshlrev_b32_e32 v58, 16, v59
	v_and_b32_e32 v59, 0xffff0000, v59
	v_pk_add_f32 v[52:53], v[52:53], v[60:61]
	v_pk_add_f32 v[54:55], v[54:55], v[56:57]
	v_pk_add_f32 v[56:57], v[48:49], v[62:63]
	v_pk_add_f32 v[58:59], v[50:51], v[58:59]
	v_mul_f32_e32 v60, v53, v53
	v_mul_f32_e32 v61, v55, v55
	v_cndmask_b32_e64 v48, v55, v59, s[0:1]
	v_mul_f32_e32 v62, v57, v57
	v_fmac_f32_e32 v60, v52, v52
	v_fmac_f32_e32 v61, v54, v54
	v_mul_f32_e32 v63, v59, v59
	v_mov_b32_dpp v81, v48 quad_perm:[1,0,3,2] row_mask:0xf bank_mask:0xf
	v_fmac_f32_e32 v62, v56, v56
	v_add_f32_e32 v48, v60, v61
	v_cndmask_b32_e64 v49, v54, v58, s[0:1]
	v_add_f32_e32 v48, v62, v48
	v_fmac_f32_e32 v63, v58, v58
	v_cndmask_b32_e64 v50, v53, v57, s[0:1]
	v_mov_b32_dpp v80, v49 quad_perm:[1,0,3,2] row_mask:0xf bank_mask:0xf
	v_add_f32_e32 v48, v63, v48
	v_cndmask_b32_e64 v51, v52, v56, s[0:1]
	v_mov_b32_dpp v71, v50 quad_perm:[1,0,3,2] row_mask:0xf bank_mask:0xf
	v_cndmask_b32_e64 v50, v80, v54, s[0:1]
	v_add_f32_e32 v54, v66, v48
	v_mov_b32_dpp v70, v51 quad_perm:[1,0,3,2] row_mask:0xf bank_mask:0xf
	v_cndmask_b32_e64 v51, v81, v55, s[0:1]
	v_mov_b32_e32 v55, v54
	s_nop 1
	v_permlane16_swap_b32_e32 v55, v54
	v_cndmask_b32_e64 v49, v71, v53, s[0:1]
	v_cndmask_b32_e64 v48, v70, v52, s[0:1]
	global_store_dwordx4 v[72:73], v[48:51], off offset:512
	v_cndmask_b32_e64 v53, v59, v81, s[0:1]
	v_cndmask_b32_e64 v52, v58, v80, s[0:1]
	s_waitcnt lgkmcnt(0)
	v_add_f32_e32 v48, v54, v55
	v_mov_b32_e32 v49, v48
	s_nop 1
	v_permlane32_swap_b32_e32 v49, v48
	v_cndmask_b32_e64 v51, v57, v71, s[0:1]
	v_cndmask_b32_e64 v50, v56, v70, s[0:1]
	global_store_dwordx4 v[74:75], v[50:53], off offset:512
	s_and_saveexec_b64 s[20:21], s[2:3]
	s_cbranch_execz .LBB0_2200
	v_lshl_add_u64 v[50:51], v[64:65], 2, s[12:13]
	s_waitcnt lgkmcnt(0)
	v_add_f32_e32 v48, v48, v49
	global_atomic_add_f32 v[50:51], v48, off
; #define GAS __attribute__((address_space(1)))
;     __device__ __forceinline__ void operator()(const f32x4 (&acc)[2][2][4][2], const Unit& u, int wr, int wc, int fr, int fq) const {
;     ...
;         const int row0 = u.pm * BM + wr * 64 + fr, col0 = u.pn * BM + wc * 32 + 8 * fq; const bool odd = (fr & 1) != 0;
; #pragma unroll
;         for (int ai = 0; ai < 2; ++ai)
; #pragma unroll
;             for (int m = 0; m < 4; ++m) {
;                 const int row = row0 + ai * HALF + m * 16; float s = 0.f;
;                 const size_t off = (size_t)row * DM + col0;
;                 const size_t offp = (size_t)(row - (odd ? 1 : 0)) * DM + col0 + (odd ? 4 : 0);
; #pragma unroll
;                 for (int bj = 0; bj < 2; ++bj) {
;                     f32x4 b0, b1;
;                     if constexpr (BASE_F32) { const f32x4 la = *(const GAS f32x4*)(basef + offp + bj * HALF), lb = *(const GAS f32x4*)(basef + offp + DM + bj * HALF);
;                         const f32x4 snd = odd ? la : lb; f32x4 rcv; rcv[0] = dpp_xor1(snd[0]); rcv[1] = dpp_xor1(snd[1]); rcv[2] = dpp_xor1(snd[2]); rcv[3] = dpp_xor1(snd[3]);
;                         b0 = odd ? rcv : la; b1 = odd ? lb : rcv; }
;                     else { const u32x4 bw = *(const u32x4*)(baseb + off + bj * HALF);
;                         b0 = (f32x4){bf_lo(bw.x), bf_hi(bw.x), bf_lo(bw.y), bf_hi(bw.y)}; b1 = (f32x4){bf_lo(bw.z), bf_hi(bw.z), bf_lo(bw.w), bf_hi(bw.w)}; }
;                     const f32x4 v0 = acc[ai][bj][m][0] + b0, v1 = acc[ai][bj][m][1] + b1;
;                     if constexpr (OUT_F32) { const f32x4 snd = odd ? v0 : v1; f32x4 rcv; rcv[0] = dpp_xor1(snd[0]); rcv[1] = dpp_xor1(snd[1]); rcv[2] = dpp_xor1(snd[2]); rcv[3] = dpp_xor1(snd[3]);
;                         *(f32x4*)(H + offp + bj * HALF) = odd ? rcv : v0; *(f32x4*)(H + offp + DM + bj * HALF) = odd ? v1 : rcv; }
;                     else { u32x4 w; w.x = cvt_pk_bf16(v0[0], v0[1]); w.y = cvt_pk_bf16(v0[2], v0[3]); w.z = cvt_pk_bf16(v1[0], v1[1]); w.w = cvt_pk_bf16(v1[2], v1[3]);
;                         *(u32x4*)(HB + off + bj * HALF) = w; }
;                     s += (v0[0] * v0[0] + v0[1] * v0[1]) + (v0[2] * v0[2] + v0[3] * v0[3]) + (v1[0] * v1[0] + v1[1] * v1[1]) + (v1[2] * v1[2] + v1[3] * v1[3]);
;                 }
;                 s += __shfl_xor(s, 16); s += __shfl_xor(s, 32);
;                 if (fq == 0) unsafeAtomicAdd(ssn + row, s);
.LBB0_2200:
	s_or_b64 exec, exec, s[20:21]
	v_add_u32_e32 v48, 0x90, v148
	s_waitcnt lgkmcnt(0)
	v_ashrrev_i32_e32 v49, 31, v48
	v_readlane_b32 s20, v254, 25
	v_lshlrev_b64 v[50:51], 12, v[48:49]
	v_readlane_b32 s21, v254, 26
	v_sub_u32_e32 v56, v48, v153
	v_ashrrev_i32_e32 v57, 31, v56
	v_lshl_add_u64 v[50:51], s[20:21], 0, v[50:51]
	v_lshl_add_u64 v[54:55], v[146:147], 1, v[50:51]
	global_load_dwordx4 v[50:53], v[54:55], off
	v_readlane_b32 s20, v254, 7
	v_lshlrev_b64 v[56:57], 13, v[56:57]
	v_readlane_b32 s21, v254, 8
	v_mov_b32_e32 v64, 0
	v_mov_b32_e32 v65, 0
	v_mov_b32_e32 v66, 0
	v_mov_b32_e32 v67, 0
	v_lshl_add_u64 v[56:57], s[20:21], 0, v[56:57]
	v_lshl_add_u64 v[56:57], v[150:151], 2, v[56:57]
	v_add_co_u32_e32 v58, vcc, s35, v56
	v_readlane_b32 s22, v254, 9
	s_nop 0
	v_addc_co_u32_e32 v59, vcc, 0, v57, vcc
	v_readlane_b32 s23, v254, 10
	s_waitcnt vmcnt(0)
	v_lshlrev_b32_e32 v60, 16, v50
	v_and_b32_e32 v61, 0xffff0000, v50
	v_lshlrev_b32_e32 v50, 16, v51
	v_and_b32_e32 v51, 0xffff0000, v51
	v_lshlrev_b32_e32 v62, 16, v52
	v_and_b32_e32 v63, 0xffff0000, v52
	v_lshlrev_b32_e32 v52, 16, v53
	v_and_b32_e32 v53, 0xffff0000, v53
	v_pk_add_f32 v[60:61], v[44:45], v[60:61]
	v_pk_add_f32 v[50:51], v[46:47], v[50:51]
	v_pk_add_f32 v[62:63], v[40:41], v[62:63]
	v_pk_add_f32 v[52:53], v[42:43], v[52:53]
	v_cndmask_b32_e64 v42, v61, v63, s[0:1]
	v_cndmask_b32_e64 v40, v51, v53, s[0:1]
	v_cndmask_b32_e64 v41, v50, v52, s[0:1]
	v_cndmask_b32_e64 v43, v60, v62, s[0:1]
	v_mov_b32_dpp v65, v42 quad_perm:[1,0,3,2] row_mask:0xf bank_mask:0xf
	v_mov_b32_dpp v66, v41 quad_perm:[1,0,3,2] row_mask:0xf bank_mask:0xf
	v_mov_b32_dpp v64, v43 quad_perm:[1,0,3,2] row_mask:0xf bank_mask:0xf
	v_mov_b32_dpp v67, v40 quad_perm:[1,0,3,2] row_mask:0xf bank_mask:0xf
	v_cndmask_b32_e64 v43, v67, v51, s[0:1]
	v_cndmask_b32_e64 v42, v66, v50, s[0:1]
	v_cndmask_b32_e64 v41, v65, v61, s[0:1]
	v_cndmask_b32_e64 v40, v64, v60, s[0:1]
	v_cndmask_b32_e64 v47, v53, v67, s[0:1]
	v_cndmask_b32_e64 v46, v52, v66, s[0:1]
	v_cndmask_b32_e64 v45, v63, v65, s[0:1]
	v_cndmask_b32_e64 v44, v62, v64, s[0:1]
	global_store_dwordx4 v[56:57], v[40:43], off
	global_store_dwordx4 v[58:59], v[44:47], off
	global_load_dwordx4 v[40:43], v[54:55], off offset:256
	v_mov_b32_e32 v65, 0
	v_mul_f32_e32 v44, v61, v61
	v_mul_f32_e32 v45, v51, v51
	v_mul_f32_e32 v46, v63, v63
	v_fmac_f32_e32 v44, v60, v60
	v_fmac_f32_e32 v45, v50, v50
	v_mul_f32_e32 v47, v53, v53
	v_fmac_f32_e32 v46, v62, v62
	v_add_f32_e32 v44, v44, v45
	v_fmac_f32_e32 v47, v52, v52
	v_add_f32_e32 v44, v46, v44
	v_add_f32_e32 v50, v47, v44
	v_mov_b32_e32 v64, 0
	v_mov_b32_e32 v55, 0
	v_mov_b32_e32 v54, 0
	s_waitcnt vmcnt(0)
	v_lshlrev_b32_e32 v44, 16, v40
	v_and_b32_e32 v45, 0xffff0000, v40
	v_lshlrev_b32_e32 v40, 16, v41
	v_and_b32_e32 v41, 0xffff0000, v41
	v_lshlrev_b32_e32 v46, 16, v42
	v_and_b32_e32 v47, 0xffff0000, v42
	v_lshlrev_b32_e32 v42, 16, v43
	v_and_b32_e32 v43, 0xffff0000, v43
	v_pk_add_f32 v[36:37], v[36:37], v[44:45]
	v_pk_add_f32 v[38:39], v[38:39], v[40:41]
	v_pk_add_f32 v[40:41], v[32:33], v[46:47]
	v_pk_add_f32 v[42:43], v[34:35], v[42:43]
	v_mul_f32_e32 v44, v37, v37
	v_mul_f32_e32 v45, v39, v39
	v_cndmask_b32_e64 v32, v39, v43, s[0:1]
	v_mul_f32_e32 v46, v41, v41
	v_fmac_f32_e32 v44, v36, v36
	v_fmac_f32_e32 v45, v38, v38
	v_mul_f32_e32 v47, v43, v43
	v_mov_b32_dpp v65, v32 quad_perm:[1,0,3,2] row_mask:0xf bank_mask:0xf
	v_fmac_f32_e32 v46, v40, v40
	v_add_f32_e32 v32, v44, v45
	v_cndmask_b32_e64 v33, v38, v42, s[0:1]
	v_add_f32_e32 v32, v46, v32
	v_fmac_f32_e32 v47, v42, v42
	v_cndmask_b32_e64 v34, v37, v41, s[0:1]
	v_mov_b32_dpp v64, v33 quad_perm:[1,0,3,2] row_mask:0xf bank_mask:0xf
	v_add_f32_e32 v32, v47, v32
	v_cndmask_b32_e64 v35, v36, v40, s[0:1]
	v_mov_b32_dpp v55, v34 quad_perm:[1,0,3,2] row_mask:0xf bank_mask:0xf
	v_cndmask_b32_e64 v34, v64, v38, s[0:1]
	v_add_f32_e32 v38, v50, v32
	v_mov_b32_dpp v54, v35 quad_perm:[1,0,3,2] row_mask:0xf bank_mask:0xf
	v_cndmask_b32_e64 v35, v65, v39, s[0:1]
	v_mov_b32_e32 v39, v38
	s_nop 1
	v_permlane16_swap_b32_e32 v39, v38
	v_cndmask_b32_e64 v33, v55, v37, s[0:1]
	v_cndmask_b32_e64 v32, v54, v36, s[0:1]
	global_store_dwordx4 v[56:57], v[32:35], off offset:512
	v_cndmask_b32_e64 v37, v43, v65, s[0:1]
	v_cndmask_b32_e64 v36, v42, v64, s[0:1]
	s_waitcnt lgkmcnt(0)
	v_add_f32_e32 v32, v38, v39
	v_mov_b32_e32 v33, v32
	s_nop 1
	v_permlane32_swap_b32_e32 v33, v32
	v_cndmask_b32_e64 v35, v41, v55, s[0:1]
	v_cndmask_b32_e64 v34, v40, v54, s[0:1]
	global_store_dwordx4 v[58:59], v[34:37], off offset:512
	s_and_saveexec_b64 s[20:21], s[2:3]
	s_cbranch_execz .LBB0_2202
	v_lshl_add_u64 v[34:35], v[48:49], 2, s[12:13]
	s_waitcnt lgkmcnt(0)
	v_add_f32_e32 v32, v32, v33
	global_atomic_add_f32 v[34:35], v32, off
; #define GAS __attribute__((address_space(1)))
;     __device__ __forceinline__ void operator()(const f32x4 (&acc)[2][2][4][2], const Unit& u, int wr, int wc, int fr, int fq) const {
;     ...
;         const int row0 = u.pm * BM + wr * 64 + fr, col0 = u.pn * BM + wc * 32 + 8 * fq; const bool odd = (fr & 1) != 0;
; #pragma unroll
;         for (int ai = 0; ai < 2; ++ai)
; #pragma unroll
;             for (int m = 0; m < 4; ++m) {
;                 const int row = row0 + ai * HALF + m * 16; float s = 0.f;
;                 const size_t off = (size_t)row * DM + col0;
;                 const size_t offp = (size_t)(row - (odd ? 1 : 0)) * DM + col0 + (odd ? 4 : 0);
; #pragma unroll
;                 for (int bj = 0; bj < 2; ++bj) {
;                     f32x4 b0, b1;
;                     if constexpr (BASE_F32) { const f32x4 la = *(const GAS f32x4*)(basef + offp + bj * HALF), lb = *(const GAS f32x4*)(basef + offp + DM + bj * HALF);
;                         const f32x4 snd = odd ? la : lb; f32x4 rcv; rcv[0] = dpp_xor1(snd[0]); rcv[1] = dpp_xor1(snd[1]); rcv[2] = dpp_xor1(snd[2]); rcv[3] = dpp_xor1(snd[3]);
;                         b0 = odd ? rcv : la; b1 = odd ? lb : rcv; }
;                     else { const u32x4 bw = *(const u32x4*)(baseb + off + bj * HALF);
;                         b0 = (f32x4){bf_lo(bw.x), bf_hi(bw.x), bf_lo(bw.y), bf_hi(bw.y)}; b1 = (f32x4){bf_lo(bw.z), bf_hi(bw.z), bf_lo(bw.w), bf_hi(bw.w)}; }
;                     const f32x4 v0 = acc[ai][bj][m][0] + b0, v1 = acc[ai][bj][m][1] + b1;
;                     if constexpr (OUT_F32) { const f32x4 snd = odd ? v0 : v1; f32x4 rcv; rcv[0] = dpp_xor1(snd[0]); rcv[1] = dpp_xor1(snd[1]); rcv[2] = dpp_xor1(snd[2]); rcv[3] = dpp_xor1(snd[3]);
;                         *(f32x4*)(H + offp + bj * HALF) = odd ? rcv : v0; *(f32x4*)(H + offp + DM + bj * HALF) = odd ? v1 : rcv; }
;                     else { u32x4 w; w.x = cvt_pk_bf16(v0[0], v0[1]); w.y = cvt_pk_bf16(v0[2], v0[3]); w.z = cvt_pk_bf16(v1[0], v1[1]); w.w = cvt_pk_bf16(v1[2], v1[3]);
;                         *(u32x4*)(HB + off + bj * HALF) = w; }
;                     s += (v0[0] * v0[0] + v0[1] * v0[1]) + (v0[2] * v0[2] + v0[3] * v0[3]) + (v1[0] * v1[0] + v1[1] * v1[1]) + (v1[2] * v1[2] + v1[3] * v1[3]);
;                 }
;                 s += __shfl_xor(s, 16); s += __shfl_xor(s, 32);
;                 if (fq == 0) unsafeAtomicAdd(ssn + row, s);
.LBB0_2202:
	s_or_b64 exec, exec, s[20:21]
	v_add_u32_e32 v32, 0xa0, v148
	s_waitcnt lgkmcnt(0)
	v_ashrrev_i32_e32 v33, 31, v32
	v_readlane_b32 s20, v254, 25
	v_lshlrev_b64 v[34:35], 12, v[32:33]
	v_readlane_b32 s21, v254, 26
	v_sub_u32_e32 v40, v32, v153
	v_ashrrev_i32_e32 v41, 31, v40
	v_lshl_add_u64 v[34:35], s[20:21], 0, v[34:35]
	v_lshl_add_u64 v[38:39], v[146:147], 1, v[34:35]
	global_load_dwordx4 v[34:37], v[38:39], off
	v_readlane_b32 s20, v254, 7
	v_lshlrev_b64 v[40:41], 13, v[40:41]
	v_readlane_b32 s21, v254, 8
	v_mov_b32_e32 v48, 0
	v_mov_b32_e32 v49, 0
	v_mov_b32_e32 v50, 0
	v_mov_b32_e32 v51, 0
	v_lshl_add_u64 v[40:41], s[20:21], 0, v[40:41]
	v_lshl_add_u64 v[40:41], v[150:151], 2, v[40:41]
	v_add_co_u32_e32 v42, vcc, s35, v40
	v_readlane_b32 s22, v254, 9
	s_nop 0
	v_addc_co_u32_e32 v43, vcc, 0, v41, vcc
	v_readlane_b32 s23, v254, 10
	s_waitcnt vmcnt(0)
	v_lshlrev_b32_e32 v44, 16, v34
	v_and_b32_e32 v45, 0xffff0000, v34
	v_lshlrev_b32_e32 v34, 16, v35
	v_and_b32_e32 v35, 0xffff0000, v35
	v_lshlrev_b32_e32 v46, 16, v36
	v_and_b32_e32 v47, 0xffff0000, v36
	v_lshlrev_b32_e32 v36, 16, v37
	v_and_b32_e32 v37, 0xffff0000, v37
	v_pk_add_f32 v[44:45], v[28:29], v[44:45]
	v_pk_add_f32 v[34:35], v[30:31], v[34:35]
	v_pk_add_f32 v[46:47], v[24:25], v[46:47]
	v_pk_add_f32 v[36:37], v[26:27], v[36:37]
	v_cndmask_b32_e64 v26, v45, v47, s[0:1]
	v_cndmask_b32_e64 v24, v35, v37, s[0:1]
	v_cndmask_b32_e64 v25, v34, v36, s[0:1]
	v_cndmask_b32_e64 v27, v44, v46, s[0:1]
	v_mov_b32_dpp v49, v26 quad_perm:[1,0,3,2] row_mask:0xf bank_mask:0xf
	v_mov_b32_dpp v50, v25 quad_perm:[1,0,3,2] row_mask:0xf bank_mask:0xf
	v_mov_b32_dpp v48, v27 quad_perm:[1,0,3,2] row_mask:0xf bank_mask:0xf
	v_mov_b32_dpp v51, v24 quad_perm:[1,0,3,2] row_mask:0xf bank_mask:0xf
	v_cndmask_b32_e64 v27, v51, v35, s[0:1]
	v_cndmask_b32_e64 v26, v50, v34, s[0:1]
	v_cndmask_b32_e64 v25, v49, v45, s[0:1]
	v_cndmask_b32_e64 v24, v48, v44, s[0:1]
	v_cndmask_b32_e64 v31, v37, v51, s[0:1]
	v_cndmask_b32_e64 v30, v36, v50, s[0:1]
	v_cndmask_b32_e64 v29, v47, v49, s[0:1]
	v_cndmask_b32_e64 v28, v46, v48, s[0:1]
	global_store_dwordx4 v[40:41], v[24:27], off
	global_store_dwordx4 v[42:43], v[28:31], off
	global_load_dwordx4 v[24:27], v[38:39], off offset:256
	v_mov_b32_e32 v49, 0
	v_mul_f32_e32 v28, v45, v45
	v_mul_f32_e32 v29, v35, v35
	v_mul_f32_e32 v30, v47, v47
	v_fmac_f32_e32 v28, v44, v44
	v_fmac_f32_e32 v29, v34, v34
	v_mul_f32_e32 v31, v37, v37
	v_fmac_f32_e32 v30, v46, v46
	v_add_f32_e32 v28, v28, v29
	v_fmac_f32_e32 v31, v36, v36
	v_add_f32_e32 v28, v30, v28
	v_add_f32_e32 v34, v31, v28
	v_mov_b32_e32 v48, 0
	v_mov_b32_e32 v39, 0
	v_mov_b32_e32 v38, 0
	s_waitcnt vmcnt(0)
	v_lshlrev_b32_e32 v28, 16, v24
	v_and_b32_e32 v29, 0xffff0000, v24
	v_lshlrev_b32_e32 v24, 16, v25
	v_and_b32_e32 v25, 0xffff0000, v25
	v_lshlrev_b32_e32 v30, 16, v26
	v_and_b32_e32 v31, 0xffff0000, v26
	v_lshlrev_b32_e32 v26, 16, v27
	v_and_b32_e32 v27, 0xffff0000, v27
	v_pk_add_f32 v[20:21], v[20:21], v[28:29]
	v_pk_add_f32 v[22:23], v[22:23], v[24:25]
	v_pk_add_f32 v[24:25], v[16:17], v[30:31]
	v_pk_add_f32 v[26:27], v[18:19], v[26:27]
	v_mul_f32_e32 v28, v21, v21
	v_mul_f32_e32 v29, v23, v23
	v_cndmask_b32_e64 v16, v23, v27, s[0:1]
	v_mul_f32_e32 v30, v25, v25
	v_fmac_f32_e32 v28, v20, v20
	v_fmac_f32_e32 v29, v22, v22
	v_mul_f32_e32 v31, v27, v27
	v_mov_b32_dpp v49, v16 quad_perm:[1,0,3,2] row_mask:0xf bank_mask:0xf
	v_fmac_f32_e32 v30, v24, v24
	v_add_f32_e32 v16, v28, v29
	v_cndmask_b32_e64 v17, v22, v26, s[0:1]
	v_add_f32_e32 v16, v30, v16
	v_fmac_f32_e32 v31, v26, v26
	v_cndmask_b32_e64 v18, v21, v25, s[0:1]
	v_mov_b32_dpp v48, v17 quad_perm:[1,0,3,2] row_mask:0xf bank_mask:0xf
	v_add_f32_e32 v16, v31, v16
	v_cndmask_b32_e64 v19, v20, v24, s[0:1]
	v_mov_b32_dpp v39, v18 quad_perm:[1,0,3,2] row_mask:0xf bank_mask:0xf
	v_cndmask_b32_e64 v18, v48, v22, s[0:1]
	v_add_f32_e32 v22, v34, v16
	v_mov_b32_dpp v38, v19 quad_perm:[1,0,3,2] row_mask:0xf bank_mask:0xf
	v_cndmask_b32_e64 v19, v49, v23, s[0:1]
	v_mov_b32_e32 v23, v22
	s_nop 1
	v_permlane16_swap_b32_e32 v23, v22
	v_cndmask_b32_e64 v17, v39, v21, s[0:1]
	v_cndmask_b32_e64 v16, v38, v20, s[0:1]
	global_store_dwordx4 v[40:41], v[16:19], off offset:512
	v_cndmask_b32_e64 v21, v27, v49, s[0:1]
	v_cndmask_b32_e64 v20, v26, v48, s[0:1]
	s_waitcnt lgkmcnt(0)
	v_add_f32_e32 v16, v22, v23
	v_mov_b32_e32 v17, v16
	s_nop 1
	v_permlane32_swap_b32_e32 v17, v16
	v_cndmask_b32_e64 v19, v25, v39, s[0:1]
	v_cndmask_b32_e64 v18, v24, v38, s[0:1]
	global_store_dwordx4 v[42:43], v[18:21], off offset:512
	s_and_saveexec_b64 s[20:21], s[2:3]
	s_cbranch_execz .LBB0_2204
	v_lshl_add_u64 v[18:19], v[32:33], 2, s[12:13]
	s_waitcnt lgkmcnt(0)
	v_add_f32_e32 v16, v16, v17
	global_atomic_add_f32 v[18:19], v16, off
; #define GAS __attribute__((address_space(1)))
;     __device__ __forceinline__ void operator()(const f32x4 (&acc)[2][2][4][2], const Unit& u, int wr, int wc, int fr, int fq) const {
;     ...
;         const int row0 = u.pm * BM + wr * 64 + fr, col0 = u.pn * BM + wc * 32 + 8 * fq; const bool odd = (fr & 1) != 0;
; #pragma unroll
;         for (int ai = 0; ai < 2; ++ai)
; #pragma unroll
;             for (int m = 0; m < 4; ++m) {
;                 const int row = row0 + ai * HALF + m * 16; float s = 0.f;
;                 const size_t off = (size_t)row * DM + col0;
;                 const size_t offp = (size_t)(row - (odd ? 1 : 0)) * DM + col0 + (odd ? 4 : 0);
; #pragma unroll
;                 for (int bj = 0; bj < 2; ++bj) {
;                     f32x4 b0, b1;
;                     if constexpr (BASE_F32) { const f32x4 la = *(const GAS f32x4*)(basef + offp + bj * HALF), lb = *(const GAS f32x4*)(basef + offp + DM + bj * HALF);
;                         const f32x4 snd = odd ? la : lb; f32x4 rcv; rcv[0] = dpp_xor1(snd[0]); rcv[1] = dpp_xor1(snd[1]); rcv[2] = dpp_xor1(snd[2]); rcv[3] = dpp_xor1(snd[3]);
;                         b0 = odd ? rcv : la; b1 = odd ? lb : rcv; }
;                     else { const u32x4 bw = *(const u32x4*)(baseb + off + bj * HALF);
;                         b0 = (f32x4){bf_lo(bw.x), bf_hi(bw.x), bf_lo(bw.y), bf_hi(bw.y)}; b1 = (f32x4){bf_lo(bw.z), bf_hi(bw.z), bf_lo(bw.w), bf_hi(bw.w)}; }
;                     const f32x4 v0 = acc[ai][bj][m][0] + b0, v1 = acc[ai][bj][m][1] + b1;
;                     if constexpr (OUT_F32) { const f32x4 snd = odd ? v0 : v1; f32x4 rcv; rcv[0] = dpp_xor1(snd[0]); rcv[1] = dpp_xor1(snd[1]); rcv[2] = dpp_xor1(snd[2]); rcv[3] = dpp_xor1(snd[3]);
;                         *(f32x4*)(H + offp + bj * HALF) = odd ? rcv : v0; *(f32x4*)(H + offp + DM + bj * HALF) = odd ? v1 : rcv; }
;                     else { u32x4 w; w.x = cvt_pk_bf16(v0[0], v0[1]); w.y = cvt_pk_bf16(v0[2], v0[3]); w.z = cvt_pk_bf16(v1[0], v1[1]); w.w = cvt_pk_bf16(v1[2], v1[3]);
;                         *(u32x4*)(HB + off + bj * HALF) = w; }
;                     s += (v0[0] * v0[0] + v0[1] * v0[1]) + (v0[2] * v0[2] + v0[3] * v0[3]) + (v1[0] * v1[0] + v1[1] * v1[1]) + (v1[2] * v1[2] + v1[3] * v1[3]);
;                 }
;                 s += __shfl_xor(s, 16); s += __shfl_xor(s, 32);
;                 if (fq == 0) unsafeAtomicAdd(ssn + row, s);
.LBB0_2204:
	s_or_b64 exec, exec, s[20:21]
	v_add_u32_e32 v16, 0xb0, v148
	s_waitcnt lgkmcnt(0)
	v_ashrrev_i32_e32 v17, 31, v16
	v_readlane_b32 s20, v254, 25
	v_lshlrev_b64 v[18:19], 12, v[16:17]
	v_readlane_b32 s21, v254, 26
	v_sub_u32_e32 v24, v16, v153
	v_ashrrev_i32_e32 v25, 31, v24
	v_lshl_add_u64 v[18:19], s[20:21], 0, v[18:19]
	v_lshl_add_u64 v[22:23], v[146:147], 1, v[18:19]
	global_load_dwordx4 v[18:21], v[22:23], off
	v_readlane_b32 s20, v254, 7
	v_lshlrev_b64 v[24:25], 13, v[24:25]
	v_readlane_b32 s21, v254, 8
	v_mov_b32_e32 v32, 0
	v_mov_b32_e32 v33, 0
	v_mov_b32_e32 v34, 0
	v_mov_b32_e32 v35, 0
	v_lshl_add_u64 v[24:25], s[20:21], 0, v[24:25]
	v_lshl_add_u64 v[24:25], v[150:151], 2, v[24:25]
	v_add_co_u32_e32 v26, vcc, s35, v24
	v_readlane_b32 s22, v254, 9
	s_nop 0
	v_addc_co_u32_e32 v27, vcc, 0, v25, vcc
	v_readlane_b32 s23, v254, 10
	s_waitcnt vmcnt(0)
	v_lshlrev_b32_e32 v28, 16, v18
	v_and_b32_e32 v29, 0xffff0000, v18
	v_lshlrev_b32_e32 v18, 16, v19
	v_and_b32_e32 v19, 0xffff0000, v19
	v_lshlrev_b32_e32 v30, 16, v20
	v_and_b32_e32 v31, 0xffff0000, v20
	v_lshlrev_b32_e32 v20, 16, v21
	v_and_b32_e32 v21, 0xffff0000, v21
	v_pk_add_f32 v[28:29], v[12:13], v[28:29]
	v_pk_add_f32 v[18:19], v[14:15], v[18:19]
	v_pk_add_f32 v[30:31], v[8:9], v[30:31]
	v_pk_add_f32 v[20:21], v[10:11], v[20:21]
	v_cndmask_b32_e64 v10, v29, v31, s[0:1]
	v_cndmask_b32_e64 v8, v19, v21, s[0:1]
	v_cndmask_b32_e64 v9, v18, v20, s[0:1]
	v_cndmask_b32_e64 v11, v28, v30, s[0:1]
	v_mov_b32_dpp v33, v10 quad_perm:[1,0,3,2] row_mask:0xf bank_mask:0xf
	v_mov_b32_dpp v34, v9 quad_perm:[1,0,3,2] row_mask:0xf bank_mask:0xf
	v_mov_b32_dpp v32, v11 quad_perm:[1,0,3,2] row_mask:0xf bank_mask:0xf
	v_mov_b32_dpp v35, v8 quad_perm:[1,0,3,2] row_mask:0xf bank_mask:0xf
	v_cndmask_b32_e64 v11, v35, v19, s[0:1]
	v_cndmask_b32_e64 v10, v34, v18, s[0:1]
	v_cndmask_b32_e64 v9, v33, v29, s[0:1]
	v_cndmask_b32_e64 v8, v32, v28, s[0:1]
	v_cndmask_b32_e64 v15, v21, v35, s[0:1]
	v_cndmask_b32_e64 v14, v20, v34, s[0:1]
	v_cndmask_b32_e64 v13, v31, v33, s[0:1]
	v_cndmask_b32_e64 v12, v30, v32, s[0:1]
	global_store_dwordx4 v[24:25], v[8:11], off
	global_store_dwordx4 v[26:27], v[12:15], off
	global_load_dwordx4 v[8:11], v[22:23], off offset:256
	v_mov_b32_e32 v33, 0
	v_mul_f32_e32 v12, v29, v29
	v_mul_f32_e32 v13, v19, v19
	v_mul_f32_e32 v14, v31, v31
	v_fmac_f32_e32 v12, v28, v28
	v_fmac_f32_e32 v13, v18, v18
	v_mul_f32_e32 v15, v21, v21
	v_fmac_f32_e32 v14, v30, v30
	v_add_f32_e32 v12, v12, v13
	v_fmac_f32_e32 v15, v20, v20
	v_add_f32_e32 v12, v14, v12
	v_add_f32_e32 v18, v15, v12
	v_mov_b32_e32 v32, 0
	v_mov_b32_e32 v23, 0
	v_mov_b32_e32 v22, 0
	s_waitcnt vmcnt(0)
	v_lshlrev_b32_e32 v12, 16, v8
	v_and_b32_e32 v13, 0xffff0000, v8
	v_lshlrev_b32_e32 v8, 16, v9
	v_and_b32_e32 v9, 0xffff0000, v9
	v_lshlrev_b32_e32 v14, 16, v10
	v_and_b32_e32 v15, 0xffff0000, v10
	v_lshlrev_b32_e32 v10, 16, v11
	v_and_b32_e32 v11, 0xffff0000, v11
	v_pk_add_f32 v[4:5], v[4:5], v[12:13]
	v_pk_add_f32 v[6:7], v[6:7], v[8:9]
	v_pk_add_f32 v[8:9], v[0:1], v[14:15]
	v_pk_add_f32 v[10:11], v[2:3], v[10:11]
	v_mul_f32_e32 v12, v5, v5
	v_mul_f32_e32 v13, v7, v7
	v_cndmask_b32_e64 v0, v7, v11, s[0:1]
	v_mul_f32_e32 v14, v9, v9
	v_fmac_f32_e32 v12, v4, v4
	v_fmac_f32_e32 v13, v6, v6
	v_mul_f32_e32 v15, v11, v11
	v_mov_b32_dpp v33, v0 quad_perm:[1,0,3,2] row_mask:0xf bank_mask:0xf
	v_fmac_f32_e32 v14, v8, v8
	v_add_f32_e32 v0, v12, v13
	v_cndmask_b32_e64 v1, v6, v10, s[0:1]
	v_add_f32_e32 v0, v14, v0
	v_fmac_f32_e32 v15, v10, v10
	v_cndmask_b32_e64 v2, v5, v9, s[0:1]
	v_mov_b32_dpp v32, v1 quad_perm:[1,0,3,2] row_mask:0xf bank_mask:0xf
	v_add_f32_e32 v0, v15, v0
	v_cndmask_b32_e64 v3, v4, v8, s[0:1]
	v_mov_b32_dpp v23, v2 quad_perm:[1,0,3,2] row_mask:0xf bank_mask:0xf
	v_cndmask_b32_e64 v2, v32, v6, s[0:1]
	v_add_f32_e32 v6, v18, v0
	v_mov_b32_dpp v22, v3 quad_perm:[1,0,3,2] row_mask:0xf bank_mask:0xf
	v_cndmask_b32_e64 v3, v33, v7, s[0:1]
	v_mov_b32_e32 v7, v6
	s_nop 1
	v_permlane16_swap_b32_e32 v7, v6
	v_cndmask_b32_e64 v1, v23, v5, s[0:1]
	v_cndmask_b32_e64 v0, v22, v4, s[0:1]
	global_store_dwordx4 v[24:25], v[0:3], off offset:512
	v_cndmask_b32_e64 v5, v11, v33, s[0:1]
	v_cndmask_b32_e64 v4, v10, v32, s[0:1]
	s_waitcnt lgkmcnt(0)
	v_add_f32_e32 v0, v6, v7
	v_mov_b32_e32 v1, v0
	s_nop 1
	v_permlane32_swap_b32_e32 v1, v0
	v_cndmask_b32_e64 v3, v9, v23, s[0:1]
	v_cndmask_b32_e64 v2, v8, v22, s[0:1]
	global_store_dwordx4 v[26:27], v[2:5], off offset:512
	s_and_saveexec_b64 s[20:21], s[2:3]
	s_cbranch_execz .LBB0_2206
	v_lshl_add_u64 v[2:3], v[16:17], 2, s[12:13]
	s_waitcnt lgkmcnt(0)
	v_add_f32_e32 v0, v0, v1
	global_atomic_add_f32 v[2:3], v0, off
